# plus P8 merge GEMM final epilogue gate loads hoisted; sample-unit first 12 state loads issued at unit entry (before the q/k/v setup)
# speedup vs baseline: 1.0013x; 1.0013x over previous
; #define GAS __attribute__((address_space(1)))
; #define LAS __attribute__((address_space(3)))
; __device__ __forceinline__ float bflo(unsigned w) { return __uint_as_float(w << 16); }
; __device__ __forceinline__ float bfhi(unsigned w) { return __uint_as_float(w & 0xffff0000u); }
; __device__ __forceinline__ void mlstm_sample_unit(Frame& F, const Args& a, int b, int h) {
;     ...
;     const bf16* QC = WSP(bf16, WS_QC); const bf16* KC = WSP(bf16, WS_KC); const bf16* ZV = WSP(bf16, WS_Z) + (size_t)1 * M * D; const float* GT = WSP(float, WS_GATES); bf16* HRAW = WSP(bf16, WS_HRAW);
;     const size_t r0 = (size_t)NP + 4 * b;
;     { const int idx = tid * 2, row = idx >> 8, col = idx & 255;
;       const unsigned qw = *(const GAS unsigned*)(QC + (r0 + row) * 1024 + h * 256 + col), kw = *(const GAS unsigned*)(KC + (r0 + row) * 1024 + h * 256 + col);
;       L[MS_Q + idx] = bflo(qw); L[MS_Q + idx + 1] = bfhi(qw); L[MS_K + idx] = bflo(kw); L[MS_K + idx + 1] = bfhi(kw); }
;     { const int idx = tid * 4, row = idx >> 9, col = idx & 511; const v2u vw = *(const GAS v2u*)(ZV + (r0 + row) * D + h * 512 + col);
;       L[MS_V + idx] = bflo(vw.x); L[MS_V + idx + 1] = bfhi(vw.x); L[MS_V + idx + 2] = bflo(vw.y); L[MS_V + idx + 3] = bfhi(vw.y); }
;     if (tid < 256) L[MS_N + tid] = a.in[I_SN][(size_t)bh * 256 + tid];
;     ...
;     const int rsub = tid >> 7, c4 = tid & 127; const float decay = L[MS_SC + 20];
;     f32x4 vs[4], qc[4];
; #pragma unroll
;     for (int s = 0; s < 4; ++s) { vs[s] = *(const LAS f32x4*)(L + MS_V + s * 512 + 4 * c4); qc[s] = (f32x4){0.f, 0.f, 0.f, 0.f}; }
;     const float* Cin = a.in[I_SC] + (size_t)bh * 256 * 512 + 4 * c4; float* Cout = F.out + O_CS + (size_t)bh * 256 * 512 + 4 * c4;
; #pragma unroll 16
;     for (int i = 0; i < 64; ++i) { const int d = 4 * i + rsub;
;         const f32x4 c0 = __builtin_nontemporal_load((const f32x4*)(Cin + (size_t)d * 512));
.LBB0_1057:
	s_andn2_b64 vcc, exec, s[0:1]
	s_cbranch_vccnz .LBB0_986
	v_readlane_b32 s6, v245, 22
	v_readlane_b32 s7, v245, 23
	v_lshrrev_b32_e32 v254, 7, v68
	v_and_b32_e32 v242, 0x7f, v68
	v_lshlrev_b32_e32 v242, 4, v242
	v_lshl_add_u32 v242, v254, 11, v242
	s_lshl_b32 s5, s4, 19
	v_add_u32_e32 v242, s5, v242
	v_mov_b32_e32 v243, 0
	v_lshl_add_u64 v[242:243], s[6:7], 0, v[242:243]
	v_mov_b32_e32 v248, 0x2000
	v_mov_b32_e32 v249, 0
	global_load_dwordx4 v[182:185], v[242:243], off nt
	v_lshl_add_u64 v[242:243], v[242:243], 0, v[248:249]
	global_load_dwordx4 v[186:189], v[242:243], off nt
	v_lshl_add_u64 v[242:243], v[242:243], 0, v[248:249]
	global_load_dwordx4 v[190:193], v[242:243], off nt
	v_lshl_add_u64 v[242:243], v[242:243], 0, v[248:249]
	global_load_dwordx4 v[194:197], v[242:243], off nt
	v_lshl_add_u64 v[242:243], v[242:243], 0, v[248:249]
	global_load_dwordx4 v[198:201], v[242:243], off nt
	v_lshl_add_u64 v[242:243], v[242:243], 0, v[248:249]
	global_load_dwordx4 v[202:205], v[242:243], off nt
	v_lshl_add_u64 v[242:243], v[242:243], 0, v[248:249]
	global_load_dwordx4 v[206:209], v[242:243], off nt
	v_lshl_add_u64 v[242:243], v[242:243], 0, v[248:249]
	global_load_dwordx4 v[210:213], v[242:243], off nt
	v_lshl_add_u64 v[242:243], v[242:243], 0, v[248:249]
	global_load_dwordx4 v[214:217], v[242:243], off nt
	v_lshl_add_u64 v[242:243], v[242:243], 0, v[248:249]
	global_load_dwordx4 v[218:221], v[242:243], off nt
	v_lshl_add_u64 v[242:243], v[242:243], 0, v[248:249]
	global_load_dwordx4 v[222:225], v[242:243], off nt
	v_lshl_add_u64 v[242:243], v[242:243], 0, v[248:249]
	global_load_dwordx4 v[226:229], v[242:243], off nt
	v_lshl_add_u64 v[242:243], v[242:243], 0, v[248:249]
	s_and_b32 s54, s4, -4
	s_and_b32 s60, s4, 3
	s_ashr_i32 s55, s54, 31
	s_add_u32 s52, s54, 0x2000
	v_ashrrev_i32_e32 v40, 7, v68
	s_addc_u32 s53, s55, 0
	v_ashrrev_i32_e32 v41, 31, v40
	v_lshl_add_u64 v[8:9], s[52:53], 0, v[40:41]
	v_readlane_b32 s0, v244, 18
	v_lshlrev_b64 v[6:7], 11, v[8:9]
	v_readlane_b32 s1, v244, 19
	s_lshl_b32 s86, s60, 9
	v_lshlrev_b32_e32 v12, 2, v68
	v_lshl_add_u64 v[10:11], s[0:1], 0, v[6:7]
	v_readlane_b32 s0, v244, 20
	v_readlane_b32 s1, v244, 21
	v_lshl_add_u64 v[10:11], v[10:11], 0, s[86:87]
	v_and_b32_e32 v66, 0x1fc, v12
	v_lshl_add_u64 v[6:7], s[0:1], 0, v[6:7]
	v_lshl_add_u64 v[6:7], v[6:7], 0, s[86:87]
	v_lshl_add_u64 v[10:11], v[10:11], 0, v[66:67]
	v_lshl_add_u64 v[6:7], v[6:7], 0, v[66:67]
	global_load_dword v11, v[10:11], off
	v_readlane_b32 s0, v244, 22
	global_load_dword v6, v[6:7], off
	v_lshlrev_b64 v[38:39], 12, v[8:9]
	v_readlane_b32 s1, v244, 23
	v_lshlrev_b32_e32 v14, 3, v68
	v_and_b32_e32 v66, 0x3f8, v14
	v_lshl_add_u64 v[8:9], s[0:1], 0, v[38:39]
	s_lshl_b32 s0, s60, 10
	s_mov_b32 s1, s87
	v_lshl_add_u64 v[8:9], v[8:9], 0, s[0:1]
	v_add_u32_e32 v7, 0, v14
	v_lshl_add_u64 v[8:9], v[8:9], 0, v[66:67]
	s_movk_i32 s0, 0x100
	v_cmp_gt_i32_e64 s[0:1], s0, v68
	v_ashrrev_i32_e32 v69, 31, v68
	s_waitcnt vmcnt(1)
	v_lshlrev_b32_e32 v10, 16, v11
	v_and_b32_e32 v11, 0xffff0000, v11
	s_waitcnt vmcnt(0)
	v_lshlrev_b32_e32 v12, 16, v6
	v_and_b32_e32 v13, 0xffff0000, v6
	ds_write2st64_b64 v7, v[10:11], v[12:13] offset1:8
	global_load_dwordx2 v[10:11], v[8:9], off
	v_add_u32_e32 v6, v7, v14
	s_waitcnt vmcnt(0)
	v_lshlrev_b32_e32 v8, 16, v10
	v_and_b32_e32 v9, 0xffff0000, v10
	v_lshlrev_b32_e32 v10, 16, v11
	v_and_b32_e32 v11, 0xffff0000, v11
	ds_write_b128 v6, v[8:11] offset:12288
	s_and_saveexec_b64 s[6:7], s[0:1]
	s_cbranch_execnz .LBB0_1079
	s_or_b64 exec, exec, s[6:7]
	v_cmp_gt_i32_e32 vcc, 16, v68
	s_and_saveexec_b64 s[6:7], vcc
	s_cbranch_execnz .LBB0_1080

; __device__ __forceinline__ void mlstm_sample_unit(Frame& F, const Args& a, int b, int h) {
;     ...
;     const float* Cin = a.in[I_SC] + (size_t)bh * 256 * 512 + 4 * c4; float* Cout = F.out + O_CS + (size_t)bh * 256 * 512 + 4 * c4;
; #pragma unroll 16
;     for (int i = 0; i < 64; ++i) { const int d = 4 * i + rsub;
;         const f32x4 c0 = __builtin_nontemporal_load((const f32x4*)(Cin + (size_t)d * 512));
;         f32x4 cn = c0 * decay;
; #pragma unroll
;         for (int s = 0; s < 4; ++s) { cn += vs[s] * L[MS_KW + s * 256 + d]; qc[s] += c0 * L[MS_Q + s * 256 + d]; }
;         __builtin_nontemporal_store(cn, (f32x4*)(Cout + (size_t)d * 512)); }
.LBB0_1075:
	s_waitcnt lgkmcnt(0)
	v_mbcnt_lo_u32_b32 v254, -1, 0
	v_mbcnt_hi_u32_b32 v254, -1, v254
	v_lshl_add_u32 v254, v254, 4, v41
	ds_read_b32 v234, v254 offset:0
	ds_read_b32 v235, v254 offset:1024
	ds_read_b32 v236, v254 offset:2048
	ds_read_b32 v237, v254 offset:3072
	ds_read_b32 v230, v254 offset:8192
	ds_read_b32 v231, v254 offset:9216
	ds_read_b32 v232, v254 offset:10240
	ds_read_b32 v233, v254 offset:11264
	v_add_co_u32_e32 v246, vcc, 0x4f1c040, v46
	s_nop 1
	v_addc_co_u32_e32 v247, vcc, 0, v47, vcc
	s_waitcnt lgkmcnt(0)
	v_readlane_b32 s8, v230, 0
	v_readlane_b32 s30, v231, 0
	v_readlane_b32 s44, v232, 0
	v_readlane_b32 s46, v233, 0
	v_readlane_b32 s50, v234, 0
	v_readlane_b32 s58, v235, 0
	v_readlane_b32 s98, v236, 0
	v_readlane_b32 s100, v237, 0
	s_waitcnt vmcnt(11)
	v_pk_mul_f32 v[238:239], v[18:19], s[8:9] op_sel_hi:[1,0]
	v_pk_mul_f32 v[240:241], v[20:21], s[8:9] op_sel_hi:[1,0]
	v_pk_fma_f32 v[238:239], v[44:45], v[182:183], v[238:239]
	v_pk_fma_f32 v[240:241], v[44:45], v[184:185], v[240:241]
	v_pk_fma_f32 v[238:239], v[14:15], s[30:31], v[238:239] op_sel_hi:[1,0,1]
	v_pk_fma_f32 v[240:241], v[16:17], s[30:31], v[240:241] op_sel_hi:[1,0,1]
	v_pk_fma_f32 v[238:239], v[10:11], s[44:45], v[238:239] op_sel_hi:[1,0,1]
	v_pk_fma_f32 v[240:241], v[12:13], s[44:45], v[240:241] op_sel_hi:[1,0,1]
	v_pk_fma_f32 v[238:239], v[6:7], s[46:47], v[238:239] op_sel_hi:[1,0,1]
	v_pk_fma_f32 v[240:241], v[8:9], s[46:47], v[240:241] op_sel_hi:[1,0,1]
	v_pk_fma_f32 v[34:35], v[182:183], s[50:51], v[34:35] op_sel_hi:[1,0,1]
	v_pk_fma_f32 v[36:37], v[184:185], s[50:51], v[36:37] op_sel_hi:[1,0,1]
	v_pk_fma_f32 v[30:31], v[182:183], s[58:59], v[30:31] op_sel_hi:[1,0,1]
	v_pk_fma_f32 v[32:33], v[184:185], s[58:59], v[32:33] op_sel_hi:[1,0,1]
	v_pk_fma_f32 v[26:27], v[182:183], s[98:99], v[26:27] op_sel_hi:[1,0,1]
	v_pk_fma_f32 v[28:29], v[184:185], s[98:99], v[28:29] op_sel_hi:[1,0,1]
	v_pk_fma_f32 v[22:23], v[182:183], s[100:101], v[22:23] op_sel_hi:[1,0,1]
	v_pk_fma_f32 v[24:25], v[184:185], s[100:101], v[24:25] op_sel_hi:[1,0,1]
	global_store_dwordx4 v[246:247], v[238:241], off nt
	global_load_dwordx4 v[182:185], v[242:243], off nt
	v_lshl_add_u64 v[242:243], v[242:243], 0, v[248:249]
	v_lshl_add_u64 v[246:247], v[246:247], 0, v[248:249]
	v_readlane_b32 s8, v230, 1
	v_readlane_b32 s30, v231, 1
	v_readlane_b32 s44, v232, 1
	v_readlane_b32 s46, v233, 1
	v_readlane_b32 s50, v234, 1
	v_readlane_b32 s58, v235, 1
	v_readlane_b32 s98, v236, 1
	v_readlane_b32 s100, v237, 1
	s_waitcnt vmcnt(12)
	v_pk_mul_f32 v[238:239], v[18:19], s[8:9] op_sel_hi:[1,0]
	v_pk_mul_f32 v[240:241], v[20:21], s[8:9] op_sel_hi:[1,0]
	v_pk_fma_f32 v[238:239], v[44:45], v[186:187], v[238:239]
	v_pk_fma_f32 v[240:241], v[44:45], v[188:189], v[240:241]
	v_pk_fma_f32 v[238:239], v[14:15], s[30:31], v[238:239] op_sel_hi:[1,0,1]
	v_pk_fma_f32 v[240:241], v[16:17], s[30:31], v[240:241] op_sel_hi:[1,0,1]
	v_pk_fma_f32 v[238:239], v[10:11], s[44:45], v[238:239] op_sel_hi:[1,0,1]
	v_pk_fma_f32 v[240:241], v[12:13], s[44:45], v[240:241] op_sel_hi:[1,0,1]
	v_pk_fma_f32 v[238:239], v[6:7], s[46:47], v[238:239] op_sel_hi:[1,0,1]
	v_pk_fma_f32 v[240:241], v[8:9], s[46:47], v[240:241] op_sel_hi:[1,0,1]
	v_pk_fma_f32 v[34:35], v[186:187], s[50:51], v[34:35] op_sel_hi:[1,0,1]
	v_pk_fma_f32 v[36:37], v[188:189], s[50:51], v[36:37] op_sel_hi:[1,0,1]
	v_pk_fma_f32 v[30:31], v[186:187], s[58:59], v[30:31] op_sel_hi:[1,0,1]
	v_pk_fma_f32 v[32:33], v[188:189], s[58:59], v[32:33] op_sel_hi:[1,0,1]
	v_pk_fma_f32 v[26:27], v[186:187], s[98:99], v[26:27] op_sel_hi:[1,0,1]
	v_pk_fma_f32 v[28:29], v[188:189], s[98:99], v[28:29] op_sel_hi:[1,0,1]
	v_pk_fma_f32 v[22:23], v[186:187], s[100:101], v[22:23] op_sel_hi:[1,0,1]
	v_pk_fma_f32 v[24:25], v[188:189], s[100:101], v[24:25] op_sel_hi:[1,0,1]
	global_store_dwordx4 v[246:247], v[238:241], off nt
	global_load_dwordx4 v[186:189], v[242:243], off nt
	v_lshl_add_u64 v[242:243], v[242:243], 0, v[248:249]
	v_lshl_add_u64 v[246:247], v[246:247], 0, v[248:249]
	v_readlane_b32 s8, v230, 2
	v_readlane_b32 s30, v231, 2
	v_readlane_b32 s44, v232, 2
	v_readlane_b32 s46, v233, 2
	v_readlane_b32 s50, v234, 2
	v_readlane_b32 s58, v235, 2
	v_readlane_b32 s98, v236, 2
	v_readlane_b32 s100, v237, 2
	s_waitcnt vmcnt(13)
	v_pk_mul_f32 v[238:239], v[18:19], s[8:9] op_sel_hi:[1,0]
	v_pk_mul_f32 v[240:241], v[20:21], s[8:9] op_sel_hi:[1,0]
	v_pk_fma_f32 v[238:239], v[44:45], v[190:191], v[238:239]
	v_pk_fma_f32 v[240:241], v[44:45], v[192:193], v[240:241]
	v_pk_fma_f32 v[238:239], v[14:15], s[30:31], v[238:239] op_sel_hi:[1,0,1]
	v_pk_fma_f32 v[240:241], v[16:17], s[30:31], v[240:241] op_sel_hi:[1,0,1]
	v_pk_fma_f32 v[238:239], v[10:11], s[44:45], v[238:239] op_sel_hi:[1,0,1]
	v_pk_fma_f32 v[240:241], v[12:13], s[44:45], v[240:241] op_sel_hi:[1,0,1]
	v_pk_fma_f32 v[238:239], v[6:7], s[46:47], v[238:239] op_sel_hi:[1,0,1]
	v_pk_fma_f32 v[240:241], v[8:9], s[46:47], v[240:241] op_sel_hi:[1,0,1]
	v_pk_fma_f32 v[34:35], v[190:191], s[50:51], v[34:35] op_sel_hi:[1,0,1]
	v_pk_fma_f32 v[36:37], v[192:193], s[50:51], v[36:37] op_sel_hi:[1,0,1]
	v_pk_fma_f32 v[30:31], v[190:191], s[58:59], v[30:31] op_sel_hi:[1,0,1]
	v_pk_fma_f32 v[32:33], v[192:193], s[58:59], v[32:33] op_sel_hi:[1,0,1]
	v_pk_fma_f32 v[26:27], v[190:191], s[98:99], v[26:27] op_sel_hi:[1,0,1]
	v_pk_fma_f32 v[28:29], v[192:193], s[98:99], v[28:29] op_sel_hi:[1,0,1]
	v_pk_fma_f32 v[22:23], v[190:191], s[100:101], v[22:23] op_sel_hi:[1,0,1]
	v_pk_fma_f32 v[24:25], v[192:193], s[100:101], v[24:25] op_sel_hi:[1,0,1]
	global_store_dwordx4 v[246:247], v[238:241], off nt
	global_load_dwordx4 v[190:193], v[242:243], off nt
	v_lshl_add_u64 v[242:243], v[242:243], 0, v[248:249]
	v_lshl_add_u64 v[246:247], v[246:247], 0, v[248:249]
	v_readlane_b32 s8, v230, 3
	v_readlane_b32 s30, v231, 3
	v_readlane_b32 s44, v232, 3
	v_readlane_b32 s46, v233, 3
	v_readlane_b32 s50, v234, 3
	v_readlane_b32 s58, v235, 3
	v_readlane_b32 s98, v236, 3
	v_readlane_b32 s100, v237, 3
	s_waitcnt vmcnt(14)
; __device__ __forceinline__ void mlstm_sample_unit(Frame& F, const Args& a, int b, int h) {
;     ...
; #pragma unroll 16
;     for (int i = 0; i < 64; ++i) { const int d = 4 * i + rsub;
;         const f32x4 c0 = __builtin_nontemporal_load((const f32x4*)(Cin + (size_t)d * 512));
;         f32x4 cn = c0 * decay;
; #pragma unroll
;         for (int s = 0; s < 4; ++s) { cn += vs[s] * L[MS_KW + s * 256 + d]; qc[s] += c0 * L[MS_Q + s * 256 + d]; }
;         __builtin_nontemporal_store(cn, (f32x4*)(Cout + (size_t)d * 512)); }
	v_pk_mul_f32 v[238:239], v[18:19], s[8:9] op_sel_hi:[1,0]
	v_pk_mul_f32 v[240:241], v[20:21], s[8:9] op_sel_hi:[1,0]
	v_pk_fma_f32 v[238:239], v[44:45], v[194:195], v[238:239]
	v_pk_fma_f32 v[240:241], v[44:45], v[196:197], v[240:241]
	v_pk_fma_f32 v[238:239], v[14:15], s[30:31], v[238:239] op_sel_hi:[1,0,1]
	v_pk_fma_f32 v[240:241], v[16:17], s[30:31], v[240:241] op_sel_hi:[1,0,1]
	v_pk_fma_f32 v[238:239], v[10:11], s[44:45], v[238:239] op_sel_hi:[1,0,1]
	v_pk_fma_f32 v[240:241], v[12:13], s[44:45], v[240:241] op_sel_hi:[1,0,1]
	v_pk_fma_f32 v[238:239], v[6:7], s[46:47], v[238:239] op_sel_hi:[1,0,1]
	v_pk_fma_f32 v[240:241], v[8:9], s[46:47], v[240:241] op_sel_hi:[1,0,1]
	v_pk_fma_f32 v[34:35], v[194:195], s[50:51], v[34:35] op_sel_hi:[1,0,1]
	v_pk_fma_f32 v[36:37], v[196:197], s[50:51], v[36:37] op_sel_hi:[1,0,1]
	v_pk_fma_f32 v[30:31], v[194:195], s[58:59], v[30:31] op_sel_hi:[1,0,1]
	v_pk_fma_f32 v[32:33], v[196:197], s[58:59], v[32:33] op_sel_hi:[1,0,1]
	v_pk_fma_f32 v[26:27], v[194:195], s[98:99], v[26:27] op_sel_hi:[1,0,1]
	v_pk_fma_f32 v[28:29], v[196:197], s[98:99], v[28:29] op_sel_hi:[1,0,1]
	v_pk_fma_f32 v[22:23], v[194:195], s[100:101], v[22:23] op_sel_hi:[1,0,1]
	v_pk_fma_f32 v[24:25], v[196:197], s[100:101], v[24:25] op_sel_hi:[1,0,1]
	global_store_dwordx4 v[246:247], v[238:241], off nt
	global_load_dwordx4 v[194:197], v[242:243], off nt
	v_lshl_add_u64 v[242:243], v[242:243], 0, v[248:249]
	v_lshl_add_u64 v[246:247], v[246:247], 0, v[248:249]
	v_readlane_b32 s8, v230, 4
	v_readlane_b32 s30, v231, 4
	v_readlane_b32 s44, v232, 4
	v_readlane_b32 s46, v233, 4
	v_readlane_b32 s50, v234, 4
	v_readlane_b32 s58, v235, 4
	v_readlane_b32 s98, v236, 4
	v_readlane_b32 s100, v237, 4
	s_waitcnt vmcnt(15)
	v_pk_mul_f32 v[238:239], v[18:19], s[8:9] op_sel_hi:[1,0]
	v_pk_mul_f32 v[240:241], v[20:21], s[8:9] op_sel_hi:[1,0]
	v_pk_fma_f32 v[238:239], v[44:45], v[198:199], v[238:239]
	v_pk_fma_f32 v[240:241], v[44:45], v[200:201], v[240:241]
	v_pk_fma_f32 v[238:239], v[14:15], s[30:31], v[238:239] op_sel_hi:[1,0,1]
	v_pk_fma_f32 v[240:241], v[16:17], s[30:31], v[240:241] op_sel_hi:[1,0,1]
	v_pk_fma_f32 v[238:239], v[10:11], s[44:45], v[238:239] op_sel_hi:[1,0,1]
	v_pk_fma_f32 v[240:241], v[12:13], s[44:45], v[240:241] op_sel_hi:[1,0,1]
	v_pk_fma_f32 v[238:239], v[6:7], s[46:47], v[238:239] op_sel_hi:[1,0,1]
	v_pk_fma_f32 v[240:241], v[8:9], s[46:47], v[240:241] op_sel_hi:[1,0,1]
	v_pk_fma_f32 v[34:35], v[198:199], s[50:51], v[34:35] op_sel_hi:[1,0,1]
	v_pk_fma_f32 v[36:37], v[200:201], s[50:51], v[36:37] op_sel_hi:[1,0,1]
	v_pk_fma_f32 v[30:31], v[198:199], s[58:59], v[30:31] op_sel_hi:[1,0,1]
	v_pk_fma_f32 v[32:33], v[200:201], s[58:59], v[32:33] op_sel_hi:[1,0,1]
	v_pk_fma_f32 v[26:27], v[198:199], s[98:99], v[26:27] op_sel_hi:[1,0,1]
	v_pk_fma_f32 v[28:29], v[200:201], s[98:99], v[28:29] op_sel_hi:[1,0,1]
	v_pk_fma_f32 v[22:23], v[198:199], s[100:101], v[22:23] op_sel_hi:[1,0,1]
	v_pk_fma_f32 v[24:25], v[200:201], s[100:101], v[24:25] op_sel_hi:[1,0,1]
	global_store_dwordx4 v[246:247], v[238:241], off nt
	global_load_dwordx4 v[198:201], v[242:243], off nt
	v_lshl_add_u64 v[242:243], v[242:243], 0, v[248:249]
	v_lshl_add_u64 v[246:247], v[246:247], 0, v[248:249]
	v_readlane_b32 s8, v230, 5
	v_readlane_b32 s30, v231, 5
	v_readlane_b32 s44, v232, 5
	v_readlane_b32 s46, v233, 5
	v_readlane_b32 s50, v234, 5
	v_readlane_b32 s58, v235, 5
	v_readlane_b32 s98, v236, 5
	v_readlane_b32 s100, v237, 5
	s_waitcnt vmcnt(16)
	v_pk_mul_f32 v[238:239], v[18:19], s[8:9] op_sel_hi:[1,0]
	v_pk_mul_f32 v[240:241], v[20:21], s[8:9] op_sel_hi:[1,0]
	v_pk_fma_f32 v[238:239], v[44:45], v[202:203], v[238:239]
	v_pk_fma_f32 v[240:241], v[44:45], v[204:205], v[240:241]
	v_pk_fma_f32 v[238:239], v[14:15], s[30:31], v[238:239] op_sel_hi:[1,0,1]
	v_pk_fma_f32 v[240:241], v[16:17], s[30:31], v[240:241] op_sel_hi:[1,0,1]
	v_pk_fma_f32 v[238:239], v[10:11], s[44:45], v[238:239] op_sel_hi:[1,0,1]
	v_pk_fma_f32 v[240:241], v[12:13], s[44:45], v[240:241] op_sel_hi:[1,0,1]
	v_pk_fma_f32 v[238:239], v[6:7], s[46:47], v[238:239] op_sel_hi:[1,0,1]
	v_pk_fma_f32 v[240:241], v[8:9], s[46:47], v[240:241] op_sel_hi:[1,0,1]
	v_pk_fma_f32 v[34:35], v[202:203], s[50:51], v[34:35] op_sel_hi:[1,0,1]
	v_pk_fma_f32 v[36:37], v[204:205], s[50:51], v[36:37] op_sel_hi:[1,0,1]
	v_pk_fma_f32 v[30:31], v[202:203], s[58:59], v[30:31] op_sel_hi:[1,0,1]
	v_pk_fma_f32 v[32:33], v[204:205], s[58:59], v[32:33] op_sel_hi:[1,0,1]
	v_pk_fma_f32 v[26:27], v[202:203], s[98:99], v[26:27] op_sel_hi:[1,0,1]
	v_pk_fma_f32 v[28:29], v[204:205], s[98:99], v[28:29] op_sel_hi:[1,0,1]
	v_pk_fma_f32 v[22:23], v[202:203], s[100:101], v[22:23] op_sel_hi:[1,0,1]
	v_pk_fma_f32 v[24:25], v[204:205], s[100:101], v[24:25] op_sel_hi:[1,0,1]
	global_store_dwordx4 v[246:247], v[238:241], off nt
	global_load_dwordx4 v[202:205], v[242:243], off nt
	v_lshl_add_u64 v[242:243], v[242:243], 0, v[248:249]
	v_lshl_add_u64 v[246:247], v[246:247], 0, v[248:249]
	v_readlane_b32 s8, v230, 6
	v_readlane_b32 s30, v231, 6
	v_readlane_b32 s44, v232, 6
	v_readlane_b32 s46, v233, 6
	v_readlane_b32 s50, v234, 6
	v_readlane_b32 s58, v235, 6
	v_readlane_b32 s98, v236, 6
	v_readlane_b32 s100, v237, 6
	s_waitcnt vmcnt(17)
; __device__ __forceinline__ void mlstm_sample_unit(Frame& F, const Args& a, int b, int h) {
;     ...
; #pragma unroll 16
;     for (int i = 0; i < 64; ++i) { const int d = 4 * i + rsub;
;         const f32x4 c0 = __builtin_nontemporal_load((const f32x4*)(Cin + (size_t)d * 512));
;         f32x4 cn = c0 * decay;
; #pragma unroll
;         for (int s = 0; s < 4; ++s) { cn += vs[s] * L[MS_KW + s * 256 + d]; qc[s] += c0 * L[MS_Q + s * 256 + d]; }
;         __builtin_nontemporal_store(cn, (f32x4*)(Cout + (size_t)d * 512)); }
	v_pk_mul_f32 v[238:239], v[18:19], s[8:9] op_sel_hi:[1,0]
	v_pk_mul_f32 v[240:241], v[20:21], s[8:9] op_sel_hi:[1,0]
	v_pk_fma_f32 v[238:239], v[44:45], v[206:207], v[238:239]
	v_pk_fma_f32 v[240:241], v[44:45], v[208:209], v[240:241]
	v_pk_fma_f32 v[238:239], v[14:15], s[30:31], v[238:239] op_sel_hi:[1,0,1]
	v_pk_fma_f32 v[240:241], v[16:17], s[30:31], v[240:241] op_sel_hi:[1,0,1]
	v_pk_fma_f32 v[238:239], v[10:11], s[44:45], v[238:239] op_sel_hi:[1,0,1]
	v_pk_fma_f32 v[240:241], v[12:13], s[44:45], v[240:241] op_sel_hi:[1,0,1]
	v_pk_fma_f32 v[238:239], v[6:7], s[46:47], v[238:239] op_sel_hi:[1,0,1]
	v_pk_fma_f32 v[240:241], v[8:9], s[46:47], v[240:241] op_sel_hi:[1,0,1]
	v_pk_fma_f32 v[34:35], v[206:207], s[50:51], v[34:35] op_sel_hi:[1,0,1]
	v_pk_fma_f32 v[36:37], v[208:209], s[50:51], v[36:37] op_sel_hi:[1,0,1]
	v_pk_fma_f32 v[30:31], v[206:207], s[58:59], v[30:31] op_sel_hi:[1,0,1]
	v_pk_fma_f32 v[32:33], v[208:209], s[58:59], v[32:33] op_sel_hi:[1,0,1]
	v_pk_fma_f32 v[26:27], v[206:207], s[98:99], v[26:27] op_sel_hi:[1,0,1]
	v_pk_fma_f32 v[28:29], v[208:209], s[98:99], v[28:29] op_sel_hi:[1,0,1]
	v_pk_fma_f32 v[22:23], v[206:207], s[100:101], v[22:23] op_sel_hi:[1,0,1]
	v_pk_fma_f32 v[24:25], v[208:209], s[100:101], v[24:25] op_sel_hi:[1,0,1]
	global_store_dwordx4 v[246:247], v[238:241], off nt
	global_load_dwordx4 v[206:209], v[242:243], off nt
	v_lshl_add_u64 v[242:243], v[242:243], 0, v[248:249]
	v_lshl_add_u64 v[246:247], v[246:247], 0, v[248:249]
	v_readlane_b32 s8, v230, 7
	v_readlane_b32 s30, v231, 7
	v_readlane_b32 s44, v232, 7
	v_readlane_b32 s46, v233, 7
	v_readlane_b32 s50, v234, 7
	v_readlane_b32 s58, v235, 7
	v_readlane_b32 s98, v236, 7
	v_readlane_b32 s100, v237, 7
	s_waitcnt vmcnt(18)
	v_pk_mul_f32 v[238:239], v[18:19], s[8:9] op_sel_hi:[1,0]
	v_pk_mul_f32 v[240:241], v[20:21], s[8:9] op_sel_hi:[1,0]
	v_pk_fma_f32 v[238:239], v[44:45], v[210:211], v[238:239]
	v_pk_fma_f32 v[240:241], v[44:45], v[212:213], v[240:241]
	v_pk_fma_f32 v[238:239], v[14:15], s[30:31], v[238:239] op_sel_hi:[1,0,1]
	v_pk_fma_f32 v[240:241], v[16:17], s[30:31], v[240:241] op_sel_hi:[1,0,1]
	v_pk_fma_f32 v[238:239], v[10:11], s[44:45], v[238:239] op_sel_hi:[1,0,1]
	v_pk_fma_f32 v[240:241], v[12:13], s[44:45], v[240:241] op_sel_hi:[1,0,1]
	v_pk_fma_f32 v[238:239], v[6:7], s[46:47], v[238:239] op_sel_hi:[1,0,1]
	v_pk_fma_f32 v[240:241], v[8:9], s[46:47], v[240:241] op_sel_hi:[1,0,1]
	v_pk_fma_f32 v[34:35], v[210:211], s[50:51], v[34:35] op_sel_hi:[1,0,1]
	v_pk_fma_f32 v[36:37], v[212:213], s[50:51], v[36:37] op_sel_hi:[1,0,1]
	v_pk_fma_f32 v[30:31], v[210:211], s[58:59], v[30:31] op_sel_hi:[1,0,1]
	v_pk_fma_f32 v[32:33], v[212:213], s[58:59], v[32:33] op_sel_hi:[1,0,1]
	v_pk_fma_f32 v[26:27], v[210:211], s[98:99], v[26:27] op_sel_hi:[1,0,1]
	v_pk_fma_f32 v[28:29], v[212:213], s[98:99], v[28:29] op_sel_hi:[1,0,1]
	v_pk_fma_f32 v[22:23], v[210:211], s[100:101], v[22:23] op_sel_hi:[1,0,1]
	v_pk_fma_f32 v[24:25], v[212:213], s[100:101], v[24:25] op_sel_hi:[1,0,1]
	global_store_dwordx4 v[246:247], v[238:241], off nt
	global_load_dwordx4 v[210:213], v[242:243], off nt
	v_lshl_add_u64 v[242:243], v[242:243], 0, v[248:249]
	v_lshl_add_u64 v[246:247], v[246:247], 0, v[248:249]
	v_readlane_b32 s8, v230, 8
	v_readlane_b32 s30, v231, 8
	v_readlane_b32 s44, v232, 8
	v_readlane_b32 s46, v233, 8
	v_readlane_b32 s50, v234, 8
	v_readlane_b32 s58, v235, 8
	v_readlane_b32 s98, v236, 8
	v_readlane_b32 s100, v237, 8
	s_waitcnt vmcnt(19)
	v_pk_mul_f32 v[238:239], v[18:19], s[8:9] op_sel_hi:[1,0]
	v_pk_mul_f32 v[240:241], v[20:21], s[8:9] op_sel_hi:[1,0]
	v_pk_fma_f32 v[238:239], v[44:45], v[214:215], v[238:239]
	v_pk_fma_f32 v[240:241], v[44:45], v[216:217], v[240:241]
	v_pk_fma_f32 v[238:239], v[14:15], s[30:31], v[238:239] op_sel_hi:[1,0,1]
	v_pk_fma_f32 v[240:241], v[16:17], s[30:31], v[240:241] op_sel_hi:[1,0,1]
	v_pk_fma_f32 v[238:239], v[10:11], s[44:45], v[238:239] op_sel_hi:[1,0,1]
	v_pk_fma_f32 v[240:241], v[12:13], s[44:45], v[240:241] op_sel_hi:[1,0,1]
	v_pk_fma_f32 v[238:239], v[6:7], s[46:47], v[238:239] op_sel_hi:[1,0,1]
	v_pk_fma_f32 v[240:241], v[8:9], s[46:47], v[240:241] op_sel_hi:[1,0,1]
	v_pk_fma_f32 v[34:35], v[214:215], s[50:51], v[34:35] op_sel_hi:[1,0,1]
	v_pk_fma_f32 v[36:37], v[216:217], s[50:51], v[36:37] op_sel_hi:[1,0,1]
	v_pk_fma_f32 v[30:31], v[214:215], s[58:59], v[30:31] op_sel_hi:[1,0,1]
	v_pk_fma_f32 v[32:33], v[216:217], s[58:59], v[32:33] op_sel_hi:[1,0,1]
	v_pk_fma_f32 v[26:27], v[214:215], s[98:99], v[26:27] op_sel_hi:[1,0,1]
	v_pk_fma_f32 v[28:29], v[216:217], s[98:99], v[28:29] op_sel_hi:[1,0,1]
	v_pk_fma_f32 v[22:23], v[214:215], s[100:101], v[22:23] op_sel_hi:[1,0,1]
	v_pk_fma_f32 v[24:25], v[216:217], s[100:101], v[24:25] op_sel_hi:[1,0,1]
	global_store_dwordx4 v[246:247], v[238:241], off nt
	global_load_dwordx4 v[214:217], v[242:243], off nt
	v_lshl_add_u64 v[242:243], v[242:243], 0, v[248:249]
	v_lshl_add_u64 v[246:247], v[246:247], 0, v[248:249]
	v_readlane_b32 s8, v230, 9
	v_readlane_b32 s30, v231, 9
	v_readlane_b32 s44, v232, 9
	v_readlane_b32 s46, v233, 9
	v_readlane_b32 s50, v234, 9
	v_readlane_b32 s58, v235, 9
	v_readlane_b32 s98, v236, 9
	v_readlane_b32 s100, v237, 9
	s_waitcnt vmcnt(20)
; __device__ __forceinline__ void mlstm_sample_unit(Frame& F, const Args& a, int b, int h) {
;     ...
; #pragma unroll 16
;     for (int i = 0; i < 64; ++i) { const int d = 4 * i + rsub;
;         const f32x4 c0 = __builtin_nontemporal_load((const f32x4*)(Cin + (size_t)d * 512));
;         f32x4 cn = c0 * decay;
; #pragma unroll
;         for (int s = 0; s < 4; ++s) { cn += vs[s] * L[MS_KW + s * 256 + d]; qc[s] += c0 * L[MS_Q + s * 256 + d]; }
;         __builtin_nontemporal_store(cn, (f32x4*)(Cout + (size_t)d * 512)); }
	v_pk_mul_f32 v[238:239], v[18:19], s[8:9] op_sel_hi:[1,0]
	v_pk_mul_f32 v[240:241], v[20:21], s[8:9] op_sel_hi:[1,0]
	v_pk_fma_f32 v[238:239], v[44:45], v[218:219], v[238:239]
	v_pk_fma_f32 v[240:241], v[44:45], v[220:221], v[240:241]
	v_pk_fma_f32 v[238:239], v[14:15], s[30:31], v[238:239] op_sel_hi:[1,0,1]
	v_pk_fma_f32 v[240:241], v[16:17], s[30:31], v[240:241] op_sel_hi:[1,0,1]
	v_pk_fma_f32 v[238:239], v[10:11], s[44:45], v[238:239] op_sel_hi:[1,0,1]
	v_pk_fma_f32 v[240:241], v[12:13], s[44:45], v[240:241] op_sel_hi:[1,0,1]
	v_pk_fma_f32 v[238:239], v[6:7], s[46:47], v[238:239] op_sel_hi:[1,0,1]
	v_pk_fma_f32 v[240:241], v[8:9], s[46:47], v[240:241] op_sel_hi:[1,0,1]
	v_pk_fma_f32 v[34:35], v[218:219], s[50:51], v[34:35] op_sel_hi:[1,0,1]
	v_pk_fma_f32 v[36:37], v[220:221], s[50:51], v[36:37] op_sel_hi:[1,0,1]
	v_pk_fma_f32 v[30:31], v[218:219], s[58:59], v[30:31] op_sel_hi:[1,0,1]
	v_pk_fma_f32 v[32:33], v[220:221], s[58:59], v[32:33] op_sel_hi:[1,0,1]
	v_pk_fma_f32 v[26:27], v[218:219], s[98:99], v[26:27] op_sel_hi:[1,0,1]
	v_pk_fma_f32 v[28:29], v[220:221], s[98:99], v[28:29] op_sel_hi:[1,0,1]
	v_pk_fma_f32 v[22:23], v[218:219], s[100:101], v[22:23] op_sel_hi:[1,0,1]
	v_pk_fma_f32 v[24:25], v[220:221], s[100:101], v[24:25] op_sel_hi:[1,0,1]
	global_store_dwordx4 v[246:247], v[238:241], off nt
	global_load_dwordx4 v[218:221], v[242:243], off nt
	v_lshl_add_u64 v[242:243], v[242:243], 0, v[248:249]
	v_lshl_add_u64 v[246:247], v[246:247], 0, v[248:249]
	v_readlane_b32 s8, v230, 10
	v_readlane_b32 s30, v231, 10
	v_readlane_b32 s44, v232, 10
	v_readlane_b32 s46, v233, 10
	v_readlane_b32 s50, v234, 10
	v_readlane_b32 s58, v235, 10
	v_readlane_b32 s98, v236, 10
	v_readlane_b32 s100, v237, 10
	s_waitcnt vmcnt(21)
	v_pk_mul_f32 v[238:239], v[18:19], s[8:9] op_sel_hi:[1,0]
	v_pk_mul_f32 v[240:241], v[20:21], s[8:9] op_sel_hi:[1,0]
	v_pk_fma_f32 v[238:239], v[44:45], v[222:223], v[238:239]
	v_pk_fma_f32 v[240:241], v[44:45], v[224:225], v[240:241]
	v_pk_fma_f32 v[238:239], v[14:15], s[30:31], v[238:239] op_sel_hi:[1,0,1]
	v_pk_fma_f32 v[240:241], v[16:17], s[30:31], v[240:241] op_sel_hi:[1,0,1]
	v_pk_fma_f32 v[238:239], v[10:11], s[44:45], v[238:239] op_sel_hi:[1,0,1]
	v_pk_fma_f32 v[240:241], v[12:13], s[44:45], v[240:241] op_sel_hi:[1,0,1]
	v_pk_fma_f32 v[238:239], v[6:7], s[46:47], v[238:239] op_sel_hi:[1,0,1]
	v_pk_fma_f32 v[240:241], v[8:9], s[46:47], v[240:241] op_sel_hi:[1,0,1]
	v_pk_fma_f32 v[34:35], v[222:223], s[50:51], v[34:35] op_sel_hi:[1,0,1]
	v_pk_fma_f32 v[36:37], v[224:225], s[50:51], v[36:37] op_sel_hi:[1,0,1]
	v_pk_fma_f32 v[30:31], v[222:223], s[58:59], v[30:31] op_sel_hi:[1,0,1]
	v_pk_fma_f32 v[32:33], v[224:225], s[58:59], v[32:33] op_sel_hi:[1,0,1]
	v_pk_fma_f32 v[26:27], v[222:223], s[98:99], v[26:27] op_sel_hi:[1,0,1]
	v_pk_fma_f32 v[28:29], v[224:225], s[98:99], v[28:29] op_sel_hi:[1,0,1]
	v_pk_fma_f32 v[22:23], v[222:223], s[100:101], v[22:23] op_sel_hi:[1,0,1]
	v_pk_fma_f32 v[24:25], v[224:225], s[100:101], v[24:25] op_sel_hi:[1,0,1]
	global_store_dwordx4 v[246:247], v[238:241], off nt
	global_load_dwordx4 v[222:225], v[242:243], off nt
	v_lshl_add_u64 v[242:243], v[242:243], 0, v[248:249]
	v_lshl_add_u64 v[246:247], v[246:247], 0, v[248:249]
	v_readlane_b32 s8, v230, 11
	v_readlane_b32 s30, v231, 11
	v_readlane_b32 s44, v232, 11
	v_readlane_b32 s46, v233, 11
	v_readlane_b32 s50, v234, 11
	v_readlane_b32 s58, v235, 11
	v_readlane_b32 s98, v236, 11
	v_readlane_b32 s100, v237, 11
	s_waitcnt vmcnt(22)
	v_pk_mul_f32 v[238:239], v[18:19], s[8:9] op_sel_hi:[1,0]
	v_pk_mul_f32 v[240:241], v[20:21], s[8:9] op_sel_hi:[1,0]
	v_pk_fma_f32 v[238:239], v[44:45], v[226:227], v[238:239]
	v_pk_fma_f32 v[240:241], v[44:45], v[228:229], v[240:241]
	v_pk_fma_f32 v[238:239], v[14:15], s[30:31], v[238:239] op_sel_hi:[1,0,1]
	v_pk_fma_f32 v[240:241], v[16:17], s[30:31], v[240:241] op_sel_hi:[1,0,1]
	v_pk_fma_f32 v[238:239], v[10:11], s[44:45], v[238:239] op_sel_hi:[1,0,1]
	v_pk_fma_f32 v[240:241], v[12:13], s[44:45], v[240:241] op_sel_hi:[1,0,1]
	v_pk_fma_f32 v[238:239], v[6:7], s[46:47], v[238:239] op_sel_hi:[1,0,1]
	v_pk_fma_f32 v[240:241], v[8:9], s[46:47], v[240:241] op_sel_hi:[1,0,1]
	v_pk_fma_f32 v[34:35], v[226:227], s[50:51], v[34:35] op_sel_hi:[1,0,1]
	v_pk_fma_f32 v[36:37], v[228:229], s[50:51], v[36:37] op_sel_hi:[1,0,1]
	v_pk_fma_f32 v[30:31], v[226:227], s[58:59], v[30:31] op_sel_hi:[1,0,1]
	v_pk_fma_f32 v[32:33], v[228:229], s[58:59], v[32:33] op_sel_hi:[1,0,1]
	v_pk_fma_f32 v[26:27], v[226:227], s[98:99], v[26:27] op_sel_hi:[1,0,1]
	v_pk_fma_f32 v[28:29], v[228:229], s[98:99], v[28:29] op_sel_hi:[1,0,1]
	v_pk_fma_f32 v[22:23], v[226:227], s[100:101], v[22:23] op_sel_hi:[1,0,1]
	v_pk_fma_f32 v[24:25], v[228:229], s[100:101], v[24:25] op_sel_hi:[1,0,1]
	global_store_dwordx4 v[246:247], v[238:241], off nt
	global_load_dwordx4 v[226:229], v[242:243], off nt
	v_lshl_add_u64 v[242:243], v[242:243], 0, v[248:249]
	v_lshl_add_u64 v[246:247], v[246:247], 0, v[248:249]
	v_readlane_b32 s8, v230, 12
	v_readlane_b32 s30, v231, 12
	v_readlane_b32 s44, v232, 12
	v_readlane_b32 s46, v233, 12
	v_readlane_b32 s50, v234, 12
	v_readlane_b32 s58, v235, 12
	v_readlane_b32 s98, v236, 12
	v_readlane_b32 s100, v237, 12
	s_waitcnt vmcnt(22)
; __device__ __forceinline__ void mlstm_sample_unit(Frame& F, const Args& a, int b, int h) {
;     ...
; #pragma unroll 16
;     for (int i = 0; i < 64; ++i) { const int d = 4 * i + rsub;
;         const f32x4 c0 = __builtin_nontemporal_load((const f32x4*)(Cin + (size_t)d * 512));
;         f32x4 cn = c0 * decay;
; #pragma unroll
;         for (int s = 0; s < 4; ++s) { cn += vs[s] * L[MS_KW + s * 256 + d]; qc[s] += c0 * L[MS_Q + s * 256 + d]; }
;         __builtin_nontemporal_store(cn, (f32x4*)(Cout + (size_t)d * 512)); }
	v_pk_mul_f32 v[238:239], v[18:19], s[8:9] op_sel_hi:[1,0]
	v_pk_mul_f32 v[240:241], v[20:21], s[8:9] op_sel_hi:[1,0]
	v_pk_fma_f32 v[238:239], v[44:45], v[182:183], v[238:239]
	v_pk_fma_f32 v[240:241], v[44:45], v[184:185], v[240:241]
	v_pk_fma_f32 v[238:239], v[14:15], s[30:31], v[238:239] op_sel_hi:[1,0,1]
	v_pk_fma_f32 v[240:241], v[16:17], s[30:31], v[240:241] op_sel_hi:[1,0,1]
	v_pk_fma_f32 v[238:239], v[10:11], s[44:45], v[238:239] op_sel_hi:[1,0,1]
	v_pk_fma_f32 v[240:241], v[12:13], s[44:45], v[240:241] op_sel_hi:[1,0,1]
	v_pk_fma_f32 v[238:239], v[6:7], s[46:47], v[238:239] op_sel_hi:[1,0,1]
	v_pk_fma_f32 v[240:241], v[8:9], s[46:47], v[240:241] op_sel_hi:[1,0,1]
	v_pk_fma_f32 v[34:35], v[182:183], s[50:51], v[34:35] op_sel_hi:[1,0,1]
	v_pk_fma_f32 v[36:37], v[184:185], s[50:51], v[36:37] op_sel_hi:[1,0,1]
	v_pk_fma_f32 v[30:31], v[182:183], s[58:59], v[30:31] op_sel_hi:[1,0,1]
	v_pk_fma_f32 v[32:33], v[184:185], s[58:59], v[32:33] op_sel_hi:[1,0,1]
	v_pk_fma_f32 v[26:27], v[182:183], s[98:99], v[26:27] op_sel_hi:[1,0,1]
	v_pk_fma_f32 v[28:29], v[184:185], s[98:99], v[28:29] op_sel_hi:[1,0,1]
	v_pk_fma_f32 v[22:23], v[182:183], s[100:101], v[22:23] op_sel_hi:[1,0,1]
	v_pk_fma_f32 v[24:25], v[184:185], s[100:101], v[24:25] op_sel_hi:[1,0,1]
	global_store_dwordx4 v[246:247], v[238:241], off nt
	global_load_dwordx4 v[182:185], v[242:243], off nt
	v_lshl_add_u64 v[242:243], v[242:243], 0, v[248:249]
	v_lshl_add_u64 v[246:247], v[246:247], 0, v[248:249]
	v_readlane_b32 s8, v230, 13
	v_readlane_b32 s30, v231, 13
	v_readlane_b32 s44, v232, 13
	v_readlane_b32 s46, v233, 13
	v_readlane_b32 s50, v234, 13
	v_readlane_b32 s58, v235, 13
	v_readlane_b32 s98, v236, 13
	v_readlane_b32 s100, v237, 13
	s_waitcnt vmcnt(22)
	v_pk_mul_f32 v[238:239], v[18:19], s[8:9] op_sel_hi:[1,0]
	v_pk_mul_f32 v[240:241], v[20:21], s[8:9] op_sel_hi:[1,0]
	v_pk_fma_f32 v[238:239], v[44:45], v[186:187], v[238:239]
	v_pk_fma_f32 v[240:241], v[44:45], v[188:189], v[240:241]
	v_pk_fma_f32 v[238:239], v[14:15], s[30:31], v[238:239] op_sel_hi:[1,0,1]
	v_pk_fma_f32 v[240:241], v[16:17], s[30:31], v[240:241] op_sel_hi:[1,0,1]
	v_pk_fma_f32 v[238:239], v[10:11], s[44:45], v[238:239] op_sel_hi:[1,0,1]
	v_pk_fma_f32 v[240:241], v[12:13], s[44:45], v[240:241] op_sel_hi:[1,0,1]
	v_pk_fma_f32 v[238:239], v[6:7], s[46:47], v[238:239] op_sel_hi:[1,0,1]
	v_pk_fma_f32 v[240:241], v[8:9], s[46:47], v[240:241] op_sel_hi:[1,0,1]
	v_pk_fma_f32 v[34:35], v[186:187], s[50:51], v[34:35] op_sel_hi:[1,0,1]
	v_pk_fma_f32 v[36:37], v[188:189], s[50:51], v[36:37] op_sel_hi:[1,0,1]
	v_pk_fma_f32 v[30:31], v[186:187], s[58:59], v[30:31] op_sel_hi:[1,0,1]
	v_pk_fma_f32 v[32:33], v[188:189], s[58:59], v[32:33] op_sel_hi:[1,0,1]
	v_pk_fma_f32 v[26:27], v[186:187], s[98:99], v[26:27] op_sel_hi:[1,0,1]
	v_pk_fma_f32 v[28:29], v[188:189], s[98:99], v[28:29] op_sel_hi:[1,0,1]
	v_pk_fma_f32 v[22:23], v[186:187], s[100:101], v[22:23] op_sel_hi:[1,0,1]
	v_pk_fma_f32 v[24:25], v[188:189], s[100:101], v[24:25] op_sel_hi:[1,0,1]
	global_store_dwordx4 v[246:247], v[238:241], off nt
	global_load_dwordx4 v[186:189], v[242:243], off nt
	v_lshl_add_u64 v[242:243], v[242:243], 0, v[248:249]
	v_lshl_add_u64 v[246:247], v[246:247], 0, v[248:249]
	v_readlane_b32 s8, v230, 14
	v_readlane_b32 s30, v231, 14
	v_readlane_b32 s44, v232, 14
	v_readlane_b32 s46, v233, 14
	v_readlane_b32 s50, v234, 14
	v_readlane_b32 s58, v235, 14
	v_readlane_b32 s98, v236, 14
	v_readlane_b32 s100, v237, 14
	s_waitcnt vmcnt(22)
	v_pk_mul_f32 v[238:239], v[18:19], s[8:9] op_sel_hi:[1,0]
	v_pk_mul_f32 v[240:241], v[20:21], s[8:9] op_sel_hi:[1,0]
	v_pk_fma_f32 v[238:239], v[44:45], v[190:191], v[238:239]
	v_pk_fma_f32 v[240:241], v[44:45], v[192:193], v[240:241]
	v_pk_fma_f32 v[238:239], v[14:15], s[30:31], v[238:239] op_sel_hi:[1,0,1]
	v_pk_fma_f32 v[240:241], v[16:17], s[30:31], v[240:241] op_sel_hi:[1,0,1]
	v_pk_fma_f32 v[238:239], v[10:11], s[44:45], v[238:239] op_sel_hi:[1,0,1]
	v_pk_fma_f32 v[240:241], v[12:13], s[44:45], v[240:241] op_sel_hi:[1,0,1]
	v_pk_fma_f32 v[238:239], v[6:7], s[46:47], v[238:239] op_sel_hi:[1,0,1]
	v_pk_fma_f32 v[240:241], v[8:9], s[46:47], v[240:241] op_sel_hi:[1,0,1]
	v_pk_fma_f32 v[34:35], v[190:191], s[50:51], v[34:35] op_sel_hi:[1,0,1]
	v_pk_fma_f32 v[36:37], v[192:193], s[50:51], v[36:37] op_sel_hi:[1,0,1]
	v_pk_fma_f32 v[30:31], v[190:191], s[58:59], v[30:31] op_sel_hi:[1,0,1]
	v_pk_fma_f32 v[32:33], v[192:193], s[58:59], v[32:33] op_sel_hi:[1,0,1]
	v_pk_fma_f32 v[26:27], v[190:191], s[98:99], v[26:27] op_sel_hi:[1,0,1]
	v_pk_fma_f32 v[28:29], v[192:193], s[98:99], v[28:29] op_sel_hi:[1,0,1]
	v_pk_fma_f32 v[22:23], v[190:191], s[100:101], v[22:23] op_sel_hi:[1,0,1]
	v_pk_fma_f32 v[24:25], v[192:193], s[100:101], v[24:25] op_sel_hi:[1,0,1]
	global_store_dwordx4 v[246:247], v[238:241], off nt
	global_load_dwordx4 v[190:193], v[242:243], off nt
	v_lshl_add_u64 v[242:243], v[242:243], 0, v[248:249]
	v_lshl_add_u64 v[246:247], v[246:247], 0, v[248:249]
	v_readlane_b32 s8, v230, 15
	v_readlane_b32 s30, v231, 15
	v_readlane_b32 s44, v232, 15
	v_readlane_b32 s46, v233, 15
	v_readlane_b32 s50, v234, 15
	v_readlane_b32 s58, v235, 15
	v_readlane_b32 s98, v236, 15
	v_readlane_b32 s100, v237, 15
	s_waitcnt vmcnt(22)
; __device__ __forceinline__ void mlstm_sample_unit(Frame& F, const Args& a, int b, int h) {
;     ...
; #pragma unroll 16
;     for (int i = 0; i < 64; ++i) { const int d = 4 * i + rsub;
;         const f32x4 c0 = __builtin_nontemporal_load((const f32x4*)(Cin + (size_t)d * 512));
;         f32x4 cn = c0 * decay;
; #pragma unroll
;         for (int s = 0; s < 4; ++s) { cn += vs[s] * L[MS_KW + s * 256 + d]; qc[s] += c0 * L[MS_Q + s * 256 + d]; }
;         __builtin_nontemporal_store(cn, (f32x4*)(Cout + (size_t)d * 512)); }
	v_pk_mul_f32 v[238:239], v[18:19], s[8:9] op_sel_hi:[1,0]
	v_pk_mul_f32 v[240:241], v[20:21], s[8:9] op_sel_hi:[1,0]
	v_pk_fma_f32 v[238:239], v[44:45], v[194:195], v[238:239]
	v_pk_fma_f32 v[240:241], v[44:45], v[196:197], v[240:241]
	v_pk_fma_f32 v[238:239], v[14:15], s[30:31], v[238:239] op_sel_hi:[1,0,1]
	v_pk_fma_f32 v[240:241], v[16:17], s[30:31], v[240:241] op_sel_hi:[1,0,1]
	v_pk_fma_f32 v[238:239], v[10:11], s[44:45], v[238:239] op_sel_hi:[1,0,1]
	v_pk_fma_f32 v[240:241], v[12:13], s[44:45], v[240:241] op_sel_hi:[1,0,1]
	v_pk_fma_f32 v[238:239], v[6:7], s[46:47], v[238:239] op_sel_hi:[1,0,1]
	v_pk_fma_f32 v[240:241], v[8:9], s[46:47], v[240:241] op_sel_hi:[1,0,1]
	v_pk_fma_f32 v[34:35], v[194:195], s[50:51], v[34:35] op_sel_hi:[1,0,1]
	v_pk_fma_f32 v[36:37], v[196:197], s[50:51], v[36:37] op_sel_hi:[1,0,1]
	v_pk_fma_f32 v[30:31], v[194:195], s[58:59], v[30:31] op_sel_hi:[1,0,1]
	v_pk_fma_f32 v[32:33], v[196:197], s[58:59], v[32:33] op_sel_hi:[1,0,1]
	v_pk_fma_f32 v[26:27], v[194:195], s[98:99], v[26:27] op_sel_hi:[1,0,1]
	v_pk_fma_f32 v[28:29], v[196:197], s[98:99], v[28:29] op_sel_hi:[1,0,1]
	v_pk_fma_f32 v[22:23], v[194:195], s[100:101], v[22:23] op_sel_hi:[1,0,1]
	v_pk_fma_f32 v[24:25], v[196:197], s[100:101], v[24:25] op_sel_hi:[1,0,1]
	global_store_dwordx4 v[246:247], v[238:241], off nt
	global_load_dwordx4 v[194:197], v[242:243], off nt
	v_lshl_add_u64 v[242:243], v[242:243], 0, v[248:249]
	v_lshl_add_u64 v[246:247], v[246:247], 0, v[248:249]
	v_readlane_b32 s8, v230, 16
	v_readlane_b32 s30, v231, 16
	v_readlane_b32 s44, v232, 16
	v_readlane_b32 s46, v233, 16
	v_readlane_b32 s50, v234, 16
	v_readlane_b32 s58, v235, 16
	v_readlane_b32 s98, v236, 16
	v_readlane_b32 s100, v237, 16
	s_waitcnt vmcnt(22)
	v_pk_mul_f32 v[238:239], v[18:19], s[8:9] op_sel_hi:[1,0]
	v_pk_mul_f32 v[240:241], v[20:21], s[8:9] op_sel_hi:[1,0]
	v_pk_fma_f32 v[238:239], v[44:45], v[198:199], v[238:239]
	v_pk_fma_f32 v[240:241], v[44:45], v[200:201], v[240:241]
	v_pk_fma_f32 v[238:239], v[14:15], s[30:31], v[238:239] op_sel_hi:[1,0,1]
	v_pk_fma_f32 v[240:241], v[16:17], s[30:31], v[240:241] op_sel_hi:[1,0,1]
	v_pk_fma_f32 v[238:239], v[10:11], s[44:45], v[238:239] op_sel_hi:[1,0,1]
	v_pk_fma_f32 v[240:241], v[12:13], s[44:45], v[240:241] op_sel_hi:[1,0,1]
	v_pk_fma_f32 v[238:239], v[6:7], s[46:47], v[238:239] op_sel_hi:[1,0,1]
	v_pk_fma_f32 v[240:241], v[8:9], s[46:47], v[240:241] op_sel_hi:[1,0,1]
	v_pk_fma_f32 v[34:35], v[198:199], s[50:51], v[34:35] op_sel_hi:[1,0,1]
	v_pk_fma_f32 v[36:37], v[200:201], s[50:51], v[36:37] op_sel_hi:[1,0,1]
	v_pk_fma_f32 v[30:31], v[198:199], s[58:59], v[30:31] op_sel_hi:[1,0,1]
	v_pk_fma_f32 v[32:33], v[200:201], s[58:59], v[32:33] op_sel_hi:[1,0,1]
	v_pk_fma_f32 v[26:27], v[198:199], s[98:99], v[26:27] op_sel_hi:[1,0,1]
	v_pk_fma_f32 v[28:29], v[200:201], s[98:99], v[28:29] op_sel_hi:[1,0,1]
	v_pk_fma_f32 v[22:23], v[198:199], s[100:101], v[22:23] op_sel_hi:[1,0,1]
	v_pk_fma_f32 v[24:25], v[200:201], s[100:101], v[24:25] op_sel_hi:[1,0,1]
	global_store_dwordx4 v[246:247], v[238:241], off nt
	global_load_dwordx4 v[198:201], v[242:243], off nt
	v_lshl_add_u64 v[242:243], v[242:243], 0, v[248:249]
	v_lshl_add_u64 v[246:247], v[246:247], 0, v[248:249]
	v_readlane_b32 s8, v230, 17
	v_readlane_b32 s30, v231, 17
	v_readlane_b32 s44, v232, 17
	v_readlane_b32 s46, v233, 17
	v_readlane_b32 s50, v234, 17
	v_readlane_b32 s58, v235, 17
	v_readlane_b32 s98, v236, 17
	v_readlane_b32 s100, v237, 17
	s_waitcnt vmcnt(22)
	v_pk_mul_f32 v[238:239], v[18:19], s[8:9] op_sel_hi:[1,0]
	v_pk_mul_f32 v[240:241], v[20:21], s[8:9] op_sel_hi:[1,0]
	v_pk_fma_f32 v[238:239], v[44:45], v[202:203], v[238:239]
	v_pk_fma_f32 v[240:241], v[44:45], v[204:205], v[240:241]
	v_pk_fma_f32 v[238:239], v[14:15], s[30:31], v[238:239] op_sel_hi:[1,0,1]
	v_pk_fma_f32 v[240:241], v[16:17], s[30:31], v[240:241] op_sel_hi:[1,0,1]
	v_pk_fma_f32 v[238:239], v[10:11], s[44:45], v[238:239] op_sel_hi:[1,0,1]
	v_pk_fma_f32 v[240:241], v[12:13], s[44:45], v[240:241] op_sel_hi:[1,0,1]
	v_pk_fma_f32 v[238:239], v[6:7], s[46:47], v[238:239] op_sel_hi:[1,0,1]
	v_pk_fma_f32 v[240:241], v[8:9], s[46:47], v[240:241] op_sel_hi:[1,0,1]
	v_pk_fma_f32 v[34:35], v[202:203], s[50:51], v[34:35] op_sel_hi:[1,0,1]
	v_pk_fma_f32 v[36:37], v[204:205], s[50:51], v[36:37] op_sel_hi:[1,0,1]
	v_pk_fma_f32 v[30:31], v[202:203], s[58:59], v[30:31] op_sel_hi:[1,0,1]
	v_pk_fma_f32 v[32:33], v[204:205], s[58:59], v[32:33] op_sel_hi:[1,0,1]
	v_pk_fma_f32 v[26:27], v[202:203], s[98:99], v[26:27] op_sel_hi:[1,0,1]
	v_pk_fma_f32 v[28:29], v[204:205], s[98:99], v[28:29] op_sel_hi:[1,0,1]
	v_pk_fma_f32 v[22:23], v[202:203], s[100:101], v[22:23] op_sel_hi:[1,0,1]
	v_pk_fma_f32 v[24:25], v[204:205], s[100:101], v[24:25] op_sel_hi:[1,0,1]
	global_store_dwordx4 v[246:247], v[238:241], off nt
	global_load_dwordx4 v[202:205], v[242:243], off nt
	v_lshl_add_u64 v[242:243], v[242:243], 0, v[248:249]
	v_lshl_add_u64 v[246:247], v[246:247], 0, v[248:249]
	v_readlane_b32 s8, v230, 18
	v_readlane_b32 s30, v231, 18
	v_readlane_b32 s44, v232, 18
	v_readlane_b32 s46, v233, 18
	v_readlane_b32 s50, v234, 18
	v_readlane_b32 s58, v235, 18
	v_readlane_b32 s98, v236, 18
	v_readlane_b32 s100, v237, 18
	s_waitcnt vmcnt(22)
; __device__ __forceinline__ void mlstm_sample_unit(Frame& F, const Args& a, int b, int h) {
;     ...
; #pragma unroll 16
;     for (int i = 0; i < 64; ++i) { const int d = 4 * i + rsub;
;         const f32x4 c0 = __builtin_nontemporal_load((const f32x4*)(Cin + (size_t)d * 512));
;         f32x4 cn = c0 * decay;
; #pragma unroll
;         for (int s = 0; s < 4; ++s) { cn += vs[s] * L[MS_KW + s * 256 + d]; qc[s] += c0 * L[MS_Q + s * 256 + d]; }
;         __builtin_nontemporal_store(cn, (f32x4*)(Cout + (size_t)d * 512)); }
	v_pk_mul_f32 v[238:239], v[18:19], s[8:9] op_sel_hi:[1,0]
	v_pk_mul_f32 v[240:241], v[20:21], s[8:9] op_sel_hi:[1,0]
	v_pk_fma_f32 v[238:239], v[44:45], v[206:207], v[238:239]
	v_pk_fma_f32 v[240:241], v[44:45], v[208:209], v[240:241]
	v_pk_fma_f32 v[238:239], v[14:15], s[30:31], v[238:239] op_sel_hi:[1,0,1]
	v_pk_fma_f32 v[240:241], v[16:17], s[30:31], v[240:241] op_sel_hi:[1,0,1]
	v_pk_fma_f32 v[238:239], v[10:11], s[44:45], v[238:239] op_sel_hi:[1,0,1]
	v_pk_fma_f32 v[240:241], v[12:13], s[44:45], v[240:241] op_sel_hi:[1,0,1]
	v_pk_fma_f32 v[238:239], v[6:7], s[46:47], v[238:239] op_sel_hi:[1,0,1]
	v_pk_fma_f32 v[240:241], v[8:9], s[46:47], v[240:241] op_sel_hi:[1,0,1]
	v_pk_fma_f32 v[34:35], v[206:207], s[50:51], v[34:35] op_sel_hi:[1,0,1]
	v_pk_fma_f32 v[36:37], v[208:209], s[50:51], v[36:37] op_sel_hi:[1,0,1]
	v_pk_fma_f32 v[30:31], v[206:207], s[58:59], v[30:31] op_sel_hi:[1,0,1]
	v_pk_fma_f32 v[32:33], v[208:209], s[58:59], v[32:33] op_sel_hi:[1,0,1]
	v_pk_fma_f32 v[26:27], v[206:207], s[98:99], v[26:27] op_sel_hi:[1,0,1]
	v_pk_fma_f32 v[28:29], v[208:209], s[98:99], v[28:29] op_sel_hi:[1,0,1]
	v_pk_fma_f32 v[22:23], v[206:207], s[100:101], v[22:23] op_sel_hi:[1,0,1]
	v_pk_fma_f32 v[24:25], v[208:209], s[100:101], v[24:25] op_sel_hi:[1,0,1]
	global_store_dwordx4 v[246:247], v[238:241], off nt
	global_load_dwordx4 v[206:209], v[242:243], off nt
	v_lshl_add_u64 v[242:243], v[242:243], 0, v[248:249]
	v_lshl_add_u64 v[246:247], v[246:247], 0, v[248:249]
	v_readlane_b32 s8, v230, 19
	v_readlane_b32 s30, v231, 19
	v_readlane_b32 s44, v232, 19
	v_readlane_b32 s46, v233, 19
	v_readlane_b32 s50, v234, 19
	v_readlane_b32 s58, v235, 19
	v_readlane_b32 s98, v236, 19
	v_readlane_b32 s100, v237, 19
	s_waitcnt vmcnt(22)
	v_pk_mul_f32 v[238:239], v[18:19], s[8:9] op_sel_hi:[1,0]
	v_pk_mul_f32 v[240:241], v[20:21], s[8:9] op_sel_hi:[1,0]
	v_pk_fma_f32 v[238:239], v[44:45], v[210:211], v[238:239]
	v_pk_fma_f32 v[240:241], v[44:45], v[212:213], v[240:241]
	v_pk_fma_f32 v[238:239], v[14:15], s[30:31], v[238:239] op_sel_hi:[1,0,1]
	v_pk_fma_f32 v[240:241], v[16:17], s[30:31], v[240:241] op_sel_hi:[1,0,1]
	v_pk_fma_f32 v[238:239], v[10:11], s[44:45], v[238:239] op_sel_hi:[1,0,1]
	v_pk_fma_f32 v[240:241], v[12:13], s[44:45], v[240:241] op_sel_hi:[1,0,1]
	v_pk_fma_f32 v[238:239], v[6:7], s[46:47], v[238:239] op_sel_hi:[1,0,1]
	v_pk_fma_f32 v[240:241], v[8:9], s[46:47], v[240:241] op_sel_hi:[1,0,1]
	v_pk_fma_f32 v[34:35], v[210:211], s[50:51], v[34:35] op_sel_hi:[1,0,1]
	v_pk_fma_f32 v[36:37], v[212:213], s[50:51], v[36:37] op_sel_hi:[1,0,1]
	v_pk_fma_f32 v[30:31], v[210:211], s[58:59], v[30:31] op_sel_hi:[1,0,1]
	v_pk_fma_f32 v[32:33], v[212:213], s[58:59], v[32:33] op_sel_hi:[1,0,1]
	v_pk_fma_f32 v[26:27], v[210:211], s[98:99], v[26:27] op_sel_hi:[1,0,1]
	v_pk_fma_f32 v[28:29], v[212:213], s[98:99], v[28:29] op_sel_hi:[1,0,1]
	v_pk_fma_f32 v[22:23], v[210:211], s[100:101], v[22:23] op_sel_hi:[1,0,1]
	v_pk_fma_f32 v[24:25], v[212:213], s[100:101], v[24:25] op_sel_hi:[1,0,1]
	global_store_dwordx4 v[246:247], v[238:241], off nt
	global_load_dwordx4 v[210:213], v[242:243], off nt
	v_lshl_add_u64 v[242:243], v[242:243], 0, v[248:249]
	v_lshl_add_u64 v[246:247], v[246:247], 0, v[248:249]
	v_readlane_b32 s8, v230, 20
	v_readlane_b32 s30, v231, 20
	v_readlane_b32 s44, v232, 20
	v_readlane_b32 s46, v233, 20
	v_readlane_b32 s50, v234, 20
	v_readlane_b32 s58, v235, 20
	v_readlane_b32 s98, v236, 20
	v_readlane_b32 s100, v237, 20
	s_waitcnt vmcnt(22)
	v_pk_mul_f32 v[238:239], v[18:19], s[8:9] op_sel_hi:[1,0]
	v_pk_mul_f32 v[240:241], v[20:21], s[8:9] op_sel_hi:[1,0]
	v_pk_fma_f32 v[238:239], v[44:45], v[214:215], v[238:239]
	v_pk_fma_f32 v[240:241], v[44:45], v[216:217], v[240:241]
	v_pk_fma_f32 v[238:239], v[14:15], s[30:31], v[238:239] op_sel_hi:[1,0,1]
	v_pk_fma_f32 v[240:241], v[16:17], s[30:31], v[240:241] op_sel_hi:[1,0,1]
	v_pk_fma_f32 v[238:239], v[10:11], s[44:45], v[238:239] op_sel_hi:[1,0,1]
	v_pk_fma_f32 v[240:241], v[12:13], s[44:45], v[240:241] op_sel_hi:[1,0,1]
	v_pk_fma_f32 v[238:239], v[6:7], s[46:47], v[238:239] op_sel_hi:[1,0,1]
	v_pk_fma_f32 v[240:241], v[8:9], s[46:47], v[240:241] op_sel_hi:[1,0,1]
	v_pk_fma_f32 v[34:35], v[214:215], s[50:51], v[34:35] op_sel_hi:[1,0,1]
	v_pk_fma_f32 v[36:37], v[216:217], s[50:51], v[36:37] op_sel_hi:[1,0,1]
	v_pk_fma_f32 v[30:31], v[214:215], s[58:59], v[30:31] op_sel_hi:[1,0,1]
	v_pk_fma_f32 v[32:33], v[216:217], s[58:59], v[32:33] op_sel_hi:[1,0,1]
	v_pk_fma_f32 v[26:27], v[214:215], s[98:99], v[26:27] op_sel_hi:[1,0,1]
	v_pk_fma_f32 v[28:29], v[216:217], s[98:99], v[28:29] op_sel_hi:[1,0,1]
	v_pk_fma_f32 v[22:23], v[214:215], s[100:101], v[22:23] op_sel_hi:[1,0,1]
	v_pk_fma_f32 v[24:25], v[216:217], s[100:101], v[24:25] op_sel_hi:[1,0,1]
	global_store_dwordx4 v[246:247], v[238:241], off nt
	global_load_dwordx4 v[214:217], v[242:243], off nt
	v_lshl_add_u64 v[242:243], v[242:243], 0, v[248:249]
	v_lshl_add_u64 v[246:247], v[246:247], 0, v[248:249]
	v_readlane_b32 s8, v230, 21
	v_readlane_b32 s30, v231, 21
	v_readlane_b32 s44, v232, 21
	v_readlane_b32 s46, v233, 21
	v_readlane_b32 s50, v234, 21
	v_readlane_b32 s58, v235, 21
	v_readlane_b32 s98, v236, 21
	v_readlane_b32 s100, v237, 21
	s_waitcnt vmcnt(22)
; __device__ __forceinline__ void mlstm_sample_unit(Frame& F, const Args& a, int b, int h) {
;     ...
; #pragma unroll 16
;     for (int i = 0; i < 64; ++i) { const int d = 4 * i + rsub;
;         const f32x4 c0 = __builtin_nontemporal_load((const f32x4*)(Cin + (size_t)d * 512));
;         f32x4 cn = c0 * decay;
; #pragma unroll
;         for (int s = 0; s < 4; ++s) { cn += vs[s] * L[MS_KW + s * 256 + d]; qc[s] += c0 * L[MS_Q + s * 256 + d]; }
;         __builtin_nontemporal_store(cn, (f32x4*)(Cout + (size_t)d * 512)); }
	v_pk_mul_f32 v[238:239], v[18:19], s[8:9] op_sel_hi:[1,0]
	v_pk_mul_f32 v[240:241], v[20:21], s[8:9] op_sel_hi:[1,0]
	v_pk_fma_f32 v[238:239], v[44:45], v[218:219], v[238:239]
	v_pk_fma_f32 v[240:241], v[44:45], v[220:221], v[240:241]
	v_pk_fma_f32 v[238:239], v[14:15], s[30:31], v[238:239] op_sel_hi:[1,0,1]
	v_pk_fma_f32 v[240:241], v[16:17], s[30:31], v[240:241] op_sel_hi:[1,0,1]
	v_pk_fma_f32 v[238:239], v[10:11], s[44:45], v[238:239] op_sel_hi:[1,0,1]
	v_pk_fma_f32 v[240:241], v[12:13], s[44:45], v[240:241] op_sel_hi:[1,0,1]
	v_pk_fma_f32 v[238:239], v[6:7], s[46:47], v[238:239] op_sel_hi:[1,0,1]
	v_pk_fma_f32 v[240:241], v[8:9], s[46:47], v[240:241] op_sel_hi:[1,0,1]
	v_pk_fma_f32 v[34:35], v[218:219], s[50:51], v[34:35] op_sel_hi:[1,0,1]
	v_pk_fma_f32 v[36:37], v[220:221], s[50:51], v[36:37] op_sel_hi:[1,0,1]
	v_pk_fma_f32 v[30:31], v[218:219], s[58:59], v[30:31] op_sel_hi:[1,0,1]
	v_pk_fma_f32 v[32:33], v[220:221], s[58:59], v[32:33] op_sel_hi:[1,0,1]
	v_pk_fma_f32 v[26:27], v[218:219], s[98:99], v[26:27] op_sel_hi:[1,0,1]
	v_pk_fma_f32 v[28:29], v[220:221], s[98:99], v[28:29] op_sel_hi:[1,0,1]
	v_pk_fma_f32 v[22:23], v[218:219], s[100:101], v[22:23] op_sel_hi:[1,0,1]
	v_pk_fma_f32 v[24:25], v[220:221], s[100:101], v[24:25] op_sel_hi:[1,0,1]
	global_store_dwordx4 v[246:247], v[238:241], off nt
	global_load_dwordx4 v[218:221], v[242:243], off nt
	v_lshl_add_u64 v[242:243], v[242:243], 0, v[248:249]
	v_lshl_add_u64 v[246:247], v[246:247], 0, v[248:249]
	v_readlane_b32 s8, v230, 22
	v_readlane_b32 s30, v231, 22
	v_readlane_b32 s44, v232, 22
	v_readlane_b32 s46, v233, 22
	v_readlane_b32 s50, v234, 22
	v_readlane_b32 s58, v235, 22
	v_readlane_b32 s98, v236, 22
	v_readlane_b32 s100, v237, 22
	s_waitcnt vmcnt(22)
	v_pk_mul_f32 v[238:239], v[18:19], s[8:9] op_sel_hi:[1,0]
	v_pk_mul_f32 v[240:241], v[20:21], s[8:9] op_sel_hi:[1,0]
	v_pk_fma_f32 v[238:239], v[44:45], v[222:223], v[238:239]
	v_pk_fma_f32 v[240:241], v[44:45], v[224:225], v[240:241]
	v_pk_fma_f32 v[238:239], v[14:15], s[30:31], v[238:239] op_sel_hi:[1,0,1]
	v_pk_fma_f32 v[240:241], v[16:17], s[30:31], v[240:241] op_sel_hi:[1,0,1]
	v_pk_fma_f32 v[238:239], v[10:11], s[44:45], v[238:239] op_sel_hi:[1,0,1]
	v_pk_fma_f32 v[240:241], v[12:13], s[44:45], v[240:241] op_sel_hi:[1,0,1]
	v_pk_fma_f32 v[238:239], v[6:7], s[46:47], v[238:239] op_sel_hi:[1,0,1]
	v_pk_fma_f32 v[240:241], v[8:9], s[46:47], v[240:241] op_sel_hi:[1,0,1]
	v_pk_fma_f32 v[34:35], v[222:223], s[50:51], v[34:35] op_sel_hi:[1,0,1]
	v_pk_fma_f32 v[36:37], v[224:225], s[50:51], v[36:37] op_sel_hi:[1,0,1]
	v_pk_fma_f32 v[30:31], v[222:223], s[58:59], v[30:31] op_sel_hi:[1,0,1]
	v_pk_fma_f32 v[32:33], v[224:225], s[58:59], v[32:33] op_sel_hi:[1,0,1]
	v_pk_fma_f32 v[26:27], v[222:223], s[98:99], v[26:27] op_sel_hi:[1,0,1]
	v_pk_fma_f32 v[28:29], v[224:225], s[98:99], v[28:29] op_sel_hi:[1,0,1]
	v_pk_fma_f32 v[22:23], v[222:223], s[100:101], v[22:23] op_sel_hi:[1,0,1]
	v_pk_fma_f32 v[24:25], v[224:225], s[100:101], v[24:25] op_sel_hi:[1,0,1]
	global_store_dwordx4 v[246:247], v[238:241], off nt
	global_load_dwordx4 v[222:225], v[242:243], off nt
	v_lshl_add_u64 v[242:243], v[242:243], 0, v[248:249]
	v_lshl_add_u64 v[246:247], v[246:247], 0, v[248:249]
	v_readlane_b32 s8, v230, 23
	v_readlane_b32 s30, v231, 23
	v_readlane_b32 s44, v232, 23
	v_readlane_b32 s46, v233, 23
	v_readlane_b32 s50, v234, 23
	v_readlane_b32 s58, v235, 23
	v_readlane_b32 s98, v236, 23
	v_readlane_b32 s100, v237, 23
	s_waitcnt vmcnt(22)
	v_pk_mul_f32 v[238:239], v[18:19], s[8:9] op_sel_hi:[1,0]
	v_pk_mul_f32 v[240:241], v[20:21], s[8:9] op_sel_hi:[1,0]
	v_pk_fma_f32 v[238:239], v[44:45], v[226:227], v[238:239]
	v_pk_fma_f32 v[240:241], v[44:45], v[228:229], v[240:241]
	v_pk_fma_f32 v[238:239], v[14:15], s[30:31], v[238:239] op_sel_hi:[1,0,1]
	v_pk_fma_f32 v[240:241], v[16:17], s[30:31], v[240:241] op_sel_hi:[1,0,1]
	v_pk_fma_f32 v[238:239], v[10:11], s[44:45], v[238:239] op_sel_hi:[1,0,1]
	v_pk_fma_f32 v[240:241], v[12:13], s[44:45], v[240:241] op_sel_hi:[1,0,1]
	v_pk_fma_f32 v[238:239], v[6:7], s[46:47], v[238:239] op_sel_hi:[1,0,1]
	v_pk_fma_f32 v[240:241], v[8:9], s[46:47], v[240:241] op_sel_hi:[1,0,1]
	v_pk_fma_f32 v[34:35], v[226:227], s[50:51], v[34:35] op_sel_hi:[1,0,1]
	v_pk_fma_f32 v[36:37], v[228:229], s[50:51], v[36:37] op_sel_hi:[1,0,1]
	v_pk_fma_f32 v[30:31], v[226:227], s[58:59], v[30:31] op_sel_hi:[1,0,1]
	v_pk_fma_f32 v[32:33], v[228:229], s[58:59], v[32:33] op_sel_hi:[1,0,1]
	v_pk_fma_f32 v[26:27], v[226:227], s[98:99], v[26:27] op_sel_hi:[1,0,1]
	v_pk_fma_f32 v[28:29], v[228:229], s[98:99], v[28:29] op_sel_hi:[1,0,1]
	v_pk_fma_f32 v[22:23], v[226:227], s[100:101], v[22:23] op_sel_hi:[1,0,1]
	v_pk_fma_f32 v[24:25], v[228:229], s[100:101], v[24:25] op_sel_hi:[1,0,1]
	global_store_dwordx4 v[246:247], v[238:241], off nt
	global_load_dwordx4 v[226:229], v[242:243], off nt
	v_lshl_add_u64 v[242:243], v[242:243], 0, v[248:249]
	v_lshl_add_u64 v[246:247], v[246:247], 0, v[248:249]
	v_readlane_b32 s8, v230, 24
	v_readlane_b32 s30, v231, 24
	v_readlane_b32 s44, v232, 24
	v_readlane_b32 s46, v233, 24
	v_readlane_b32 s50, v234, 24
	v_readlane_b32 s58, v235, 24
	v_readlane_b32 s98, v236, 24
	v_readlane_b32 s100, v237, 24
	s_waitcnt vmcnt(22)
; __device__ __forceinline__ void mlstm_sample_unit(Frame& F, const Args& a, int b, int h) {
;     ...
; #pragma unroll 16
;     for (int i = 0; i < 64; ++i) { const int d = 4 * i + rsub;
;         const f32x4 c0 = __builtin_nontemporal_load((const f32x4*)(Cin + (size_t)d * 512));
;         f32x4 cn = c0 * decay;
; #pragma unroll
;         for (int s = 0; s < 4; ++s) { cn += vs[s] * L[MS_KW + s * 256 + d]; qc[s] += c0 * L[MS_Q + s * 256 + d]; }
;         __builtin_nontemporal_store(cn, (f32x4*)(Cout + (size_t)d * 512)); }
	v_pk_mul_f32 v[238:239], v[18:19], s[8:9] op_sel_hi:[1,0]
	v_pk_mul_f32 v[240:241], v[20:21], s[8:9] op_sel_hi:[1,0]
	v_pk_fma_f32 v[238:239], v[44:45], v[182:183], v[238:239]
	v_pk_fma_f32 v[240:241], v[44:45], v[184:185], v[240:241]
	v_pk_fma_f32 v[238:239], v[14:15], s[30:31], v[238:239] op_sel_hi:[1,0,1]
	v_pk_fma_f32 v[240:241], v[16:17], s[30:31], v[240:241] op_sel_hi:[1,0,1]
	v_pk_fma_f32 v[238:239], v[10:11], s[44:45], v[238:239] op_sel_hi:[1,0,1]
	v_pk_fma_f32 v[240:241], v[12:13], s[44:45], v[240:241] op_sel_hi:[1,0,1]
	v_pk_fma_f32 v[238:239], v[6:7], s[46:47], v[238:239] op_sel_hi:[1,0,1]
	v_pk_fma_f32 v[240:241], v[8:9], s[46:47], v[240:241] op_sel_hi:[1,0,1]
	v_pk_fma_f32 v[34:35], v[182:183], s[50:51], v[34:35] op_sel_hi:[1,0,1]
	v_pk_fma_f32 v[36:37], v[184:185], s[50:51], v[36:37] op_sel_hi:[1,0,1]
	v_pk_fma_f32 v[30:31], v[182:183], s[58:59], v[30:31] op_sel_hi:[1,0,1]
	v_pk_fma_f32 v[32:33], v[184:185], s[58:59], v[32:33] op_sel_hi:[1,0,1]
	v_pk_fma_f32 v[26:27], v[182:183], s[98:99], v[26:27] op_sel_hi:[1,0,1]
	v_pk_fma_f32 v[28:29], v[184:185], s[98:99], v[28:29] op_sel_hi:[1,0,1]
	v_pk_fma_f32 v[22:23], v[182:183], s[100:101], v[22:23] op_sel_hi:[1,0,1]
	v_pk_fma_f32 v[24:25], v[184:185], s[100:101], v[24:25] op_sel_hi:[1,0,1]
	global_store_dwordx4 v[246:247], v[238:241], off nt
	global_load_dwordx4 v[182:185], v[242:243], off nt
	v_lshl_add_u64 v[242:243], v[242:243], 0, v[248:249]
	v_lshl_add_u64 v[246:247], v[246:247], 0, v[248:249]
	v_readlane_b32 s8, v230, 25
	v_readlane_b32 s30, v231, 25
	v_readlane_b32 s44, v232, 25
	v_readlane_b32 s46, v233, 25
	v_readlane_b32 s50, v234, 25
	v_readlane_b32 s58, v235, 25
	v_readlane_b32 s98, v236, 25
	v_readlane_b32 s100, v237, 25
	s_waitcnt vmcnt(22)
	v_pk_mul_f32 v[238:239], v[18:19], s[8:9] op_sel_hi:[1,0]
	v_pk_mul_f32 v[240:241], v[20:21], s[8:9] op_sel_hi:[1,0]
	v_pk_fma_f32 v[238:239], v[44:45], v[186:187], v[238:239]
	v_pk_fma_f32 v[240:241], v[44:45], v[188:189], v[240:241]
	v_pk_fma_f32 v[238:239], v[14:15], s[30:31], v[238:239] op_sel_hi:[1,0,1]
	v_pk_fma_f32 v[240:241], v[16:17], s[30:31], v[240:241] op_sel_hi:[1,0,1]
	v_pk_fma_f32 v[238:239], v[10:11], s[44:45], v[238:239] op_sel_hi:[1,0,1]
	v_pk_fma_f32 v[240:241], v[12:13], s[44:45], v[240:241] op_sel_hi:[1,0,1]
	v_pk_fma_f32 v[238:239], v[6:7], s[46:47], v[238:239] op_sel_hi:[1,0,1]
	v_pk_fma_f32 v[240:241], v[8:9], s[46:47], v[240:241] op_sel_hi:[1,0,1]
	v_pk_fma_f32 v[34:35], v[186:187], s[50:51], v[34:35] op_sel_hi:[1,0,1]
	v_pk_fma_f32 v[36:37], v[188:189], s[50:51], v[36:37] op_sel_hi:[1,0,1]
	v_pk_fma_f32 v[30:31], v[186:187], s[58:59], v[30:31] op_sel_hi:[1,0,1]
	v_pk_fma_f32 v[32:33], v[188:189], s[58:59], v[32:33] op_sel_hi:[1,0,1]
	v_pk_fma_f32 v[26:27], v[186:187], s[98:99], v[26:27] op_sel_hi:[1,0,1]
	v_pk_fma_f32 v[28:29], v[188:189], s[98:99], v[28:29] op_sel_hi:[1,0,1]
	v_pk_fma_f32 v[22:23], v[186:187], s[100:101], v[22:23] op_sel_hi:[1,0,1]
	v_pk_fma_f32 v[24:25], v[188:189], s[100:101], v[24:25] op_sel_hi:[1,0,1]
	global_store_dwordx4 v[246:247], v[238:241], off nt
	global_load_dwordx4 v[186:189], v[242:243], off nt
	v_lshl_add_u64 v[242:243], v[242:243], 0, v[248:249]
	v_lshl_add_u64 v[246:247], v[246:247], 0, v[248:249]
	v_readlane_b32 s8, v230, 26
	v_readlane_b32 s30, v231, 26
	v_readlane_b32 s44, v232, 26
	v_readlane_b32 s46, v233, 26
	v_readlane_b32 s50, v234, 26
	v_readlane_b32 s58, v235, 26
	v_readlane_b32 s98, v236, 26
	v_readlane_b32 s100, v237, 26
	s_waitcnt vmcnt(22)
	v_pk_mul_f32 v[238:239], v[18:19], s[8:9] op_sel_hi:[1,0]
	v_pk_mul_f32 v[240:241], v[20:21], s[8:9] op_sel_hi:[1,0]
	v_pk_fma_f32 v[238:239], v[44:45], v[190:191], v[238:239]
	v_pk_fma_f32 v[240:241], v[44:45], v[192:193], v[240:241]
	v_pk_fma_f32 v[238:239], v[14:15], s[30:31], v[238:239] op_sel_hi:[1,0,1]
	v_pk_fma_f32 v[240:241], v[16:17], s[30:31], v[240:241] op_sel_hi:[1,0,1]
	v_pk_fma_f32 v[238:239], v[10:11], s[44:45], v[238:239] op_sel_hi:[1,0,1]
	v_pk_fma_f32 v[240:241], v[12:13], s[44:45], v[240:241] op_sel_hi:[1,0,1]
	v_pk_fma_f32 v[238:239], v[6:7], s[46:47], v[238:239] op_sel_hi:[1,0,1]
	v_pk_fma_f32 v[240:241], v[8:9], s[46:47], v[240:241] op_sel_hi:[1,0,1]
	v_pk_fma_f32 v[34:35], v[190:191], s[50:51], v[34:35] op_sel_hi:[1,0,1]
	v_pk_fma_f32 v[36:37], v[192:193], s[50:51], v[36:37] op_sel_hi:[1,0,1]
	v_pk_fma_f32 v[30:31], v[190:191], s[58:59], v[30:31] op_sel_hi:[1,0,1]
	v_pk_fma_f32 v[32:33], v[192:193], s[58:59], v[32:33] op_sel_hi:[1,0,1]
	v_pk_fma_f32 v[26:27], v[190:191], s[98:99], v[26:27] op_sel_hi:[1,0,1]
	v_pk_fma_f32 v[28:29], v[192:193], s[98:99], v[28:29] op_sel_hi:[1,0,1]
	v_pk_fma_f32 v[22:23], v[190:191], s[100:101], v[22:23] op_sel_hi:[1,0,1]
	v_pk_fma_f32 v[24:25], v[192:193], s[100:101], v[24:25] op_sel_hi:[1,0,1]
	global_store_dwordx4 v[246:247], v[238:241], off nt
	global_load_dwordx4 v[190:193], v[242:243], off nt
	v_lshl_add_u64 v[242:243], v[242:243], 0, v[248:249]
	v_lshl_add_u64 v[246:247], v[246:247], 0, v[248:249]
	v_readlane_b32 s8, v230, 27
	v_readlane_b32 s30, v231, 27
	v_readlane_b32 s44, v232, 27
	v_readlane_b32 s46, v233, 27
	v_readlane_b32 s50, v234, 27
	v_readlane_b32 s58, v235, 27
	v_readlane_b32 s98, v236, 27
	v_readlane_b32 s100, v237, 27
	s_waitcnt vmcnt(22)
; __device__ __forceinline__ void mlstm_sample_unit(Frame& F, const Args& a, int b, int h) {
;     ...
; #pragma unroll 16
;     for (int i = 0; i < 64; ++i) { const int d = 4 * i + rsub;
;         const f32x4 c0 = __builtin_nontemporal_load((const f32x4*)(Cin + (size_t)d * 512));
;         f32x4 cn = c0 * decay;
; #pragma unroll
;         for (int s = 0; s < 4; ++s) { cn += vs[s] * L[MS_KW + s * 256 + d]; qc[s] += c0 * L[MS_Q + s * 256 + d]; }
;         __builtin_nontemporal_store(cn, (f32x4*)(Cout + (size_t)d * 512)); }
	v_pk_mul_f32 v[238:239], v[18:19], s[8:9] op_sel_hi:[1,0]
	v_pk_mul_f32 v[240:241], v[20:21], s[8:9] op_sel_hi:[1,0]
	v_pk_fma_f32 v[238:239], v[44:45], v[194:195], v[238:239]
	v_pk_fma_f32 v[240:241], v[44:45], v[196:197], v[240:241]
	v_pk_fma_f32 v[238:239], v[14:15], s[30:31], v[238:239] op_sel_hi:[1,0,1]
	v_pk_fma_f32 v[240:241], v[16:17], s[30:31], v[240:241] op_sel_hi:[1,0,1]
	v_pk_fma_f32 v[238:239], v[10:11], s[44:45], v[238:239] op_sel_hi:[1,0,1]
	v_pk_fma_f32 v[240:241], v[12:13], s[44:45], v[240:241] op_sel_hi:[1,0,1]
	v_pk_fma_f32 v[238:239], v[6:7], s[46:47], v[238:239] op_sel_hi:[1,0,1]
	v_pk_fma_f32 v[240:241], v[8:9], s[46:47], v[240:241] op_sel_hi:[1,0,1]
	v_pk_fma_f32 v[34:35], v[194:195], s[50:51], v[34:35] op_sel_hi:[1,0,1]
	v_pk_fma_f32 v[36:37], v[196:197], s[50:51], v[36:37] op_sel_hi:[1,0,1]
	v_pk_fma_f32 v[30:31], v[194:195], s[58:59], v[30:31] op_sel_hi:[1,0,1]
	v_pk_fma_f32 v[32:33], v[196:197], s[58:59], v[32:33] op_sel_hi:[1,0,1]
	v_pk_fma_f32 v[26:27], v[194:195], s[98:99], v[26:27] op_sel_hi:[1,0,1]
	v_pk_fma_f32 v[28:29], v[196:197], s[98:99], v[28:29] op_sel_hi:[1,0,1]
	v_pk_fma_f32 v[22:23], v[194:195], s[100:101], v[22:23] op_sel_hi:[1,0,1]
	v_pk_fma_f32 v[24:25], v[196:197], s[100:101], v[24:25] op_sel_hi:[1,0,1]
	global_store_dwordx4 v[246:247], v[238:241], off nt
	global_load_dwordx4 v[194:197], v[242:243], off nt
	v_lshl_add_u64 v[242:243], v[242:243], 0, v[248:249]
	v_lshl_add_u64 v[246:247], v[246:247], 0, v[248:249]
	v_readlane_b32 s8, v230, 28
	v_readlane_b32 s30, v231, 28
	v_readlane_b32 s44, v232, 28
	v_readlane_b32 s46, v233, 28
	v_readlane_b32 s50, v234, 28
	v_readlane_b32 s58, v235, 28
	v_readlane_b32 s98, v236, 28
	v_readlane_b32 s100, v237, 28
	s_waitcnt vmcnt(22)
	v_pk_mul_f32 v[238:239], v[18:19], s[8:9] op_sel_hi:[1,0]
	v_pk_mul_f32 v[240:241], v[20:21], s[8:9] op_sel_hi:[1,0]
	v_pk_fma_f32 v[238:239], v[44:45], v[198:199], v[238:239]
	v_pk_fma_f32 v[240:241], v[44:45], v[200:201], v[240:241]
	v_pk_fma_f32 v[238:239], v[14:15], s[30:31], v[238:239] op_sel_hi:[1,0,1]
	v_pk_fma_f32 v[240:241], v[16:17], s[30:31], v[240:241] op_sel_hi:[1,0,1]
	v_pk_fma_f32 v[238:239], v[10:11], s[44:45], v[238:239] op_sel_hi:[1,0,1]
	v_pk_fma_f32 v[240:241], v[12:13], s[44:45], v[240:241] op_sel_hi:[1,0,1]
	v_pk_fma_f32 v[238:239], v[6:7], s[46:47], v[238:239] op_sel_hi:[1,0,1]
	v_pk_fma_f32 v[240:241], v[8:9], s[46:47], v[240:241] op_sel_hi:[1,0,1]
	v_pk_fma_f32 v[34:35], v[198:199], s[50:51], v[34:35] op_sel_hi:[1,0,1]
	v_pk_fma_f32 v[36:37], v[200:201], s[50:51], v[36:37] op_sel_hi:[1,0,1]
	v_pk_fma_f32 v[30:31], v[198:199], s[58:59], v[30:31] op_sel_hi:[1,0,1]
	v_pk_fma_f32 v[32:33], v[200:201], s[58:59], v[32:33] op_sel_hi:[1,0,1]
	v_pk_fma_f32 v[26:27], v[198:199], s[98:99], v[26:27] op_sel_hi:[1,0,1]
	v_pk_fma_f32 v[28:29], v[200:201], s[98:99], v[28:29] op_sel_hi:[1,0,1]
	v_pk_fma_f32 v[22:23], v[198:199], s[100:101], v[22:23] op_sel_hi:[1,0,1]
	v_pk_fma_f32 v[24:25], v[200:201], s[100:101], v[24:25] op_sel_hi:[1,0,1]
	global_store_dwordx4 v[246:247], v[238:241], off nt
	global_load_dwordx4 v[198:201], v[242:243], off nt
	v_lshl_add_u64 v[242:243], v[242:243], 0, v[248:249]
	v_lshl_add_u64 v[246:247], v[246:247], 0, v[248:249]
	v_readlane_b32 s8, v230, 29
	v_readlane_b32 s30, v231, 29
	v_readlane_b32 s44, v232, 29
	v_readlane_b32 s46, v233, 29
	v_readlane_b32 s50, v234, 29
	v_readlane_b32 s58, v235, 29
	v_readlane_b32 s98, v236, 29
	v_readlane_b32 s100, v237, 29
	s_waitcnt vmcnt(22)
	v_pk_mul_f32 v[238:239], v[18:19], s[8:9] op_sel_hi:[1,0]
	v_pk_mul_f32 v[240:241], v[20:21], s[8:9] op_sel_hi:[1,0]
	v_pk_fma_f32 v[238:239], v[44:45], v[202:203], v[238:239]
	v_pk_fma_f32 v[240:241], v[44:45], v[204:205], v[240:241]
	v_pk_fma_f32 v[238:239], v[14:15], s[30:31], v[238:239] op_sel_hi:[1,0,1]
	v_pk_fma_f32 v[240:241], v[16:17], s[30:31], v[240:241] op_sel_hi:[1,0,1]
	v_pk_fma_f32 v[238:239], v[10:11], s[44:45], v[238:239] op_sel_hi:[1,0,1]
	v_pk_fma_f32 v[240:241], v[12:13], s[44:45], v[240:241] op_sel_hi:[1,0,1]
	v_pk_fma_f32 v[238:239], v[6:7], s[46:47], v[238:239] op_sel_hi:[1,0,1]
	v_pk_fma_f32 v[240:241], v[8:9], s[46:47], v[240:241] op_sel_hi:[1,0,1]
	v_pk_fma_f32 v[34:35], v[202:203], s[50:51], v[34:35] op_sel_hi:[1,0,1]
	v_pk_fma_f32 v[36:37], v[204:205], s[50:51], v[36:37] op_sel_hi:[1,0,1]
	v_pk_fma_f32 v[30:31], v[202:203], s[58:59], v[30:31] op_sel_hi:[1,0,1]
	v_pk_fma_f32 v[32:33], v[204:205], s[58:59], v[32:33] op_sel_hi:[1,0,1]
	v_pk_fma_f32 v[26:27], v[202:203], s[98:99], v[26:27] op_sel_hi:[1,0,1]
	v_pk_fma_f32 v[28:29], v[204:205], s[98:99], v[28:29] op_sel_hi:[1,0,1]
	v_pk_fma_f32 v[22:23], v[202:203], s[100:101], v[22:23] op_sel_hi:[1,0,1]
	v_pk_fma_f32 v[24:25], v[204:205], s[100:101], v[24:25] op_sel_hi:[1,0,1]
	global_store_dwordx4 v[246:247], v[238:241], off nt
	global_load_dwordx4 v[202:205], v[242:243], off nt
	v_lshl_add_u64 v[242:243], v[242:243], 0, v[248:249]
	v_lshl_add_u64 v[246:247], v[246:247], 0, v[248:249]
	v_readlane_b32 s8, v230, 30
	v_readlane_b32 s30, v231, 30
	v_readlane_b32 s44, v232, 30
	v_readlane_b32 s46, v233, 30
	v_readlane_b32 s50, v234, 30
	v_readlane_b32 s58, v235, 30
	v_readlane_b32 s98, v236, 30
	v_readlane_b32 s100, v237, 30
	s_waitcnt vmcnt(22)
; __device__ __forceinline__ void mlstm_sample_unit(Frame& F, const Args& a, int b, int h) {
;     ...
; #pragma unroll 16
;     for (int i = 0; i < 64; ++i) { const int d = 4 * i + rsub;
;         const f32x4 c0 = __builtin_nontemporal_load((const f32x4*)(Cin + (size_t)d * 512));
;         f32x4 cn = c0 * decay;
; #pragma unroll
;         for (int s = 0; s < 4; ++s) { cn += vs[s] * L[MS_KW + s * 256 + d]; qc[s] += c0 * L[MS_Q + s * 256 + d]; }
;         __builtin_nontemporal_store(cn, (f32x4*)(Cout + (size_t)d * 512)); }
	v_pk_mul_f32 v[238:239], v[18:19], s[8:9] op_sel_hi:[1,0]
	v_pk_mul_f32 v[240:241], v[20:21], s[8:9] op_sel_hi:[1,0]
	v_pk_fma_f32 v[238:239], v[44:45], v[206:207], v[238:239]
	v_pk_fma_f32 v[240:241], v[44:45], v[208:209], v[240:241]
	v_pk_fma_f32 v[238:239], v[14:15], s[30:31], v[238:239] op_sel_hi:[1,0,1]
	v_pk_fma_f32 v[240:241], v[16:17], s[30:31], v[240:241] op_sel_hi:[1,0,1]
	v_pk_fma_f32 v[238:239], v[10:11], s[44:45], v[238:239] op_sel_hi:[1,0,1]
	v_pk_fma_f32 v[240:241], v[12:13], s[44:45], v[240:241] op_sel_hi:[1,0,1]
	v_pk_fma_f32 v[238:239], v[6:7], s[46:47], v[238:239] op_sel_hi:[1,0,1]
	v_pk_fma_f32 v[240:241], v[8:9], s[46:47], v[240:241] op_sel_hi:[1,0,1]
	v_pk_fma_f32 v[34:35], v[206:207], s[50:51], v[34:35] op_sel_hi:[1,0,1]
	v_pk_fma_f32 v[36:37], v[208:209], s[50:51], v[36:37] op_sel_hi:[1,0,1]
	v_pk_fma_f32 v[30:31], v[206:207], s[58:59], v[30:31] op_sel_hi:[1,0,1]
	v_pk_fma_f32 v[32:33], v[208:209], s[58:59], v[32:33] op_sel_hi:[1,0,1]
	v_pk_fma_f32 v[26:27], v[206:207], s[98:99], v[26:27] op_sel_hi:[1,0,1]
	v_pk_fma_f32 v[28:29], v[208:209], s[98:99], v[28:29] op_sel_hi:[1,0,1]
	v_pk_fma_f32 v[22:23], v[206:207], s[100:101], v[22:23] op_sel_hi:[1,0,1]
	v_pk_fma_f32 v[24:25], v[208:209], s[100:101], v[24:25] op_sel_hi:[1,0,1]
	global_store_dwordx4 v[246:247], v[238:241], off nt
	global_load_dwordx4 v[206:209], v[242:243], off nt
	v_lshl_add_u64 v[242:243], v[242:243], 0, v[248:249]
	v_lshl_add_u64 v[246:247], v[246:247], 0, v[248:249]
	v_readlane_b32 s8, v230, 31
	v_readlane_b32 s30, v231, 31
	v_readlane_b32 s44, v232, 31
	v_readlane_b32 s46, v233, 31
	v_readlane_b32 s50, v234, 31
	v_readlane_b32 s58, v235, 31
	v_readlane_b32 s98, v236, 31
	v_readlane_b32 s100, v237, 31
	s_waitcnt vmcnt(22)
	v_pk_mul_f32 v[238:239], v[18:19], s[8:9] op_sel_hi:[1,0]
	v_pk_mul_f32 v[240:241], v[20:21], s[8:9] op_sel_hi:[1,0]
	v_pk_fma_f32 v[238:239], v[44:45], v[210:211], v[238:239]
	v_pk_fma_f32 v[240:241], v[44:45], v[212:213], v[240:241]
	v_pk_fma_f32 v[238:239], v[14:15], s[30:31], v[238:239] op_sel_hi:[1,0,1]
	v_pk_fma_f32 v[240:241], v[16:17], s[30:31], v[240:241] op_sel_hi:[1,0,1]
	v_pk_fma_f32 v[238:239], v[10:11], s[44:45], v[238:239] op_sel_hi:[1,0,1]
	v_pk_fma_f32 v[240:241], v[12:13], s[44:45], v[240:241] op_sel_hi:[1,0,1]
	v_pk_fma_f32 v[238:239], v[6:7], s[46:47], v[238:239] op_sel_hi:[1,0,1]
	v_pk_fma_f32 v[240:241], v[8:9], s[46:47], v[240:241] op_sel_hi:[1,0,1]
	v_pk_fma_f32 v[34:35], v[210:211], s[50:51], v[34:35] op_sel_hi:[1,0,1]
	v_pk_fma_f32 v[36:37], v[212:213], s[50:51], v[36:37] op_sel_hi:[1,0,1]
	v_pk_fma_f32 v[30:31], v[210:211], s[58:59], v[30:31] op_sel_hi:[1,0,1]
	v_pk_fma_f32 v[32:33], v[212:213], s[58:59], v[32:33] op_sel_hi:[1,0,1]
	v_pk_fma_f32 v[26:27], v[210:211], s[98:99], v[26:27] op_sel_hi:[1,0,1]
	v_pk_fma_f32 v[28:29], v[212:213], s[98:99], v[28:29] op_sel_hi:[1,0,1]
	v_pk_fma_f32 v[22:23], v[210:211], s[100:101], v[22:23] op_sel_hi:[1,0,1]
	v_pk_fma_f32 v[24:25], v[212:213], s[100:101], v[24:25] op_sel_hi:[1,0,1]
	global_store_dwordx4 v[246:247], v[238:241], off nt
	global_load_dwordx4 v[210:213], v[242:243], off nt
	v_lshl_add_u64 v[242:243], v[242:243], 0, v[248:249]
	v_lshl_add_u64 v[246:247], v[246:247], 0, v[248:249]
	v_readlane_b32 s8, v230, 32
	v_readlane_b32 s30, v231, 32
	v_readlane_b32 s44, v232, 32
	v_readlane_b32 s46, v233, 32
	v_readlane_b32 s50, v234, 32
	v_readlane_b32 s58, v235, 32
	v_readlane_b32 s98, v236, 32
	v_readlane_b32 s100, v237, 32
	s_waitcnt vmcnt(22)
	v_pk_mul_f32 v[238:239], v[18:19], s[8:9] op_sel_hi:[1,0]
	v_pk_mul_f32 v[240:241], v[20:21], s[8:9] op_sel_hi:[1,0]
	v_pk_fma_f32 v[238:239], v[44:45], v[214:215], v[238:239]
	v_pk_fma_f32 v[240:241], v[44:45], v[216:217], v[240:241]
	v_pk_fma_f32 v[238:239], v[14:15], s[30:31], v[238:239] op_sel_hi:[1,0,1]
	v_pk_fma_f32 v[240:241], v[16:17], s[30:31], v[240:241] op_sel_hi:[1,0,1]
	v_pk_fma_f32 v[238:239], v[10:11], s[44:45], v[238:239] op_sel_hi:[1,0,1]
	v_pk_fma_f32 v[240:241], v[12:13], s[44:45], v[240:241] op_sel_hi:[1,0,1]
	v_pk_fma_f32 v[238:239], v[6:7], s[46:47], v[238:239] op_sel_hi:[1,0,1]
	v_pk_fma_f32 v[240:241], v[8:9], s[46:47], v[240:241] op_sel_hi:[1,0,1]
	v_pk_fma_f32 v[34:35], v[214:215], s[50:51], v[34:35] op_sel_hi:[1,0,1]
	v_pk_fma_f32 v[36:37], v[216:217], s[50:51], v[36:37] op_sel_hi:[1,0,1]
	v_pk_fma_f32 v[30:31], v[214:215], s[58:59], v[30:31] op_sel_hi:[1,0,1]
	v_pk_fma_f32 v[32:33], v[216:217], s[58:59], v[32:33] op_sel_hi:[1,0,1]
	v_pk_fma_f32 v[26:27], v[214:215], s[98:99], v[26:27] op_sel_hi:[1,0,1]
	v_pk_fma_f32 v[28:29], v[216:217], s[98:99], v[28:29] op_sel_hi:[1,0,1]
	v_pk_fma_f32 v[22:23], v[214:215], s[100:101], v[22:23] op_sel_hi:[1,0,1]
	v_pk_fma_f32 v[24:25], v[216:217], s[100:101], v[24:25] op_sel_hi:[1,0,1]
	global_store_dwordx4 v[246:247], v[238:241], off nt
	global_load_dwordx4 v[214:217], v[242:243], off nt
	v_lshl_add_u64 v[242:243], v[242:243], 0, v[248:249]
	v_lshl_add_u64 v[246:247], v[246:247], 0, v[248:249]
	v_readlane_b32 s8, v230, 33
	v_readlane_b32 s30, v231, 33
	v_readlane_b32 s44, v232, 33
	v_readlane_b32 s46, v233, 33
	v_readlane_b32 s50, v234, 33
	v_readlane_b32 s58, v235, 33
	v_readlane_b32 s98, v236, 33
	v_readlane_b32 s100, v237, 33
	s_waitcnt vmcnt(22)
; __device__ __forceinline__ void mlstm_sample_unit(Frame& F, const Args& a, int b, int h) {
;     ...
; #pragma unroll 16
;     for (int i = 0; i < 64; ++i) { const int d = 4 * i + rsub;
;         const f32x4 c0 = __builtin_nontemporal_load((const f32x4*)(Cin + (size_t)d * 512));
;         f32x4 cn = c0 * decay;
; #pragma unroll
;         for (int s = 0; s < 4; ++s) { cn += vs[s] * L[MS_KW + s * 256 + d]; qc[s] += c0 * L[MS_Q + s * 256 + d]; }
;         __builtin_nontemporal_store(cn, (f32x4*)(Cout + (size_t)d * 512)); }
	v_pk_mul_f32 v[238:239], v[18:19], s[8:9] op_sel_hi:[1,0]
	v_pk_mul_f32 v[240:241], v[20:21], s[8:9] op_sel_hi:[1,0]
	v_pk_fma_f32 v[238:239], v[44:45], v[218:219], v[238:239]
	v_pk_fma_f32 v[240:241], v[44:45], v[220:221], v[240:241]
	v_pk_fma_f32 v[238:239], v[14:15], s[30:31], v[238:239] op_sel_hi:[1,0,1]
	v_pk_fma_f32 v[240:241], v[16:17], s[30:31], v[240:241] op_sel_hi:[1,0,1]
	v_pk_fma_f32 v[238:239], v[10:11], s[44:45], v[238:239] op_sel_hi:[1,0,1]
	v_pk_fma_f32 v[240:241], v[12:13], s[44:45], v[240:241] op_sel_hi:[1,0,1]
	v_pk_fma_f32 v[238:239], v[6:7], s[46:47], v[238:239] op_sel_hi:[1,0,1]
	v_pk_fma_f32 v[240:241], v[8:9], s[46:47], v[240:241] op_sel_hi:[1,0,1]
	v_pk_fma_f32 v[34:35], v[218:219], s[50:51], v[34:35] op_sel_hi:[1,0,1]
	v_pk_fma_f32 v[36:37], v[220:221], s[50:51], v[36:37] op_sel_hi:[1,0,1]
	v_pk_fma_f32 v[30:31], v[218:219], s[58:59], v[30:31] op_sel_hi:[1,0,1]
	v_pk_fma_f32 v[32:33], v[220:221], s[58:59], v[32:33] op_sel_hi:[1,0,1]
	v_pk_fma_f32 v[26:27], v[218:219], s[98:99], v[26:27] op_sel_hi:[1,0,1]
	v_pk_fma_f32 v[28:29], v[220:221], s[98:99], v[28:29] op_sel_hi:[1,0,1]
	v_pk_fma_f32 v[22:23], v[218:219], s[100:101], v[22:23] op_sel_hi:[1,0,1]
	v_pk_fma_f32 v[24:25], v[220:221], s[100:101], v[24:25] op_sel_hi:[1,0,1]
	global_store_dwordx4 v[246:247], v[238:241], off nt
	global_load_dwordx4 v[218:221], v[242:243], off nt
	v_lshl_add_u64 v[242:243], v[242:243], 0, v[248:249]
	v_lshl_add_u64 v[246:247], v[246:247], 0, v[248:249]
	v_readlane_b32 s8, v230, 34
	v_readlane_b32 s30, v231, 34
	v_readlane_b32 s44, v232, 34
	v_readlane_b32 s46, v233, 34
	v_readlane_b32 s50, v234, 34
	v_readlane_b32 s58, v235, 34
	v_readlane_b32 s98, v236, 34
	v_readlane_b32 s100, v237, 34
	s_waitcnt vmcnt(22)
	v_pk_mul_f32 v[238:239], v[18:19], s[8:9] op_sel_hi:[1,0]
	v_pk_mul_f32 v[240:241], v[20:21], s[8:9] op_sel_hi:[1,0]
	v_pk_fma_f32 v[238:239], v[44:45], v[222:223], v[238:239]
	v_pk_fma_f32 v[240:241], v[44:45], v[224:225], v[240:241]
	v_pk_fma_f32 v[238:239], v[14:15], s[30:31], v[238:239] op_sel_hi:[1,0,1]
	v_pk_fma_f32 v[240:241], v[16:17], s[30:31], v[240:241] op_sel_hi:[1,0,1]
	v_pk_fma_f32 v[238:239], v[10:11], s[44:45], v[238:239] op_sel_hi:[1,0,1]
	v_pk_fma_f32 v[240:241], v[12:13], s[44:45], v[240:241] op_sel_hi:[1,0,1]
	v_pk_fma_f32 v[238:239], v[6:7], s[46:47], v[238:239] op_sel_hi:[1,0,1]
	v_pk_fma_f32 v[240:241], v[8:9], s[46:47], v[240:241] op_sel_hi:[1,0,1]
	v_pk_fma_f32 v[34:35], v[222:223], s[50:51], v[34:35] op_sel_hi:[1,0,1]
	v_pk_fma_f32 v[36:37], v[224:225], s[50:51], v[36:37] op_sel_hi:[1,0,1]
	v_pk_fma_f32 v[30:31], v[222:223], s[58:59], v[30:31] op_sel_hi:[1,0,1]
	v_pk_fma_f32 v[32:33], v[224:225], s[58:59], v[32:33] op_sel_hi:[1,0,1]
	v_pk_fma_f32 v[26:27], v[222:223], s[98:99], v[26:27] op_sel_hi:[1,0,1]
	v_pk_fma_f32 v[28:29], v[224:225], s[98:99], v[28:29] op_sel_hi:[1,0,1]
	v_pk_fma_f32 v[22:23], v[222:223], s[100:101], v[22:23] op_sel_hi:[1,0,1]
	v_pk_fma_f32 v[24:25], v[224:225], s[100:101], v[24:25] op_sel_hi:[1,0,1]
	global_store_dwordx4 v[246:247], v[238:241], off nt
	global_load_dwordx4 v[222:225], v[242:243], off nt
	v_lshl_add_u64 v[242:243], v[242:243], 0, v[248:249]
	v_lshl_add_u64 v[246:247], v[246:247], 0, v[248:249]
	v_readlane_b32 s8, v230, 35
	v_readlane_b32 s30, v231, 35
	v_readlane_b32 s44, v232, 35
	v_readlane_b32 s46, v233, 35
	v_readlane_b32 s50, v234, 35
	v_readlane_b32 s58, v235, 35
	v_readlane_b32 s98, v236, 35
	v_readlane_b32 s100, v237, 35
	s_waitcnt vmcnt(22)
	v_pk_mul_f32 v[238:239], v[18:19], s[8:9] op_sel_hi:[1,0]
	v_pk_mul_f32 v[240:241], v[20:21], s[8:9] op_sel_hi:[1,0]
	v_pk_fma_f32 v[238:239], v[44:45], v[226:227], v[238:239]
	v_pk_fma_f32 v[240:241], v[44:45], v[228:229], v[240:241]
	v_pk_fma_f32 v[238:239], v[14:15], s[30:31], v[238:239] op_sel_hi:[1,0,1]
	v_pk_fma_f32 v[240:241], v[16:17], s[30:31], v[240:241] op_sel_hi:[1,0,1]
	v_pk_fma_f32 v[238:239], v[10:11], s[44:45], v[238:239] op_sel_hi:[1,0,1]
	v_pk_fma_f32 v[240:241], v[12:13], s[44:45], v[240:241] op_sel_hi:[1,0,1]
	v_pk_fma_f32 v[238:239], v[6:7], s[46:47], v[238:239] op_sel_hi:[1,0,1]
	v_pk_fma_f32 v[240:241], v[8:9], s[46:47], v[240:241] op_sel_hi:[1,0,1]
	v_pk_fma_f32 v[34:35], v[226:227], s[50:51], v[34:35] op_sel_hi:[1,0,1]
	v_pk_fma_f32 v[36:37], v[228:229], s[50:51], v[36:37] op_sel_hi:[1,0,1]
	v_pk_fma_f32 v[30:31], v[226:227], s[58:59], v[30:31] op_sel_hi:[1,0,1]
	v_pk_fma_f32 v[32:33], v[228:229], s[58:59], v[32:33] op_sel_hi:[1,0,1]
	v_pk_fma_f32 v[26:27], v[226:227], s[98:99], v[26:27] op_sel_hi:[1,0,1]
	v_pk_fma_f32 v[28:29], v[228:229], s[98:99], v[28:29] op_sel_hi:[1,0,1]
	v_pk_fma_f32 v[22:23], v[226:227], s[100:101], v[22:23] op_sel_hi:[1,0,1]
	v_pk_fma_f32 v[24:25], v[228:229], s[100:101], v[24:25] op_sel_hi:[1,0,1]
	global_store_dwordx4 v[246:247], v[238:241], off nt
	global_load_dwordx4 v[226:229], v[242:243], off nt
	v_lshl_add_u64 v[242:243], v[242:243], 0, v[248:249]
	v_lshl_add_u64 v[246:247], v[246:247], 0, v[248:249]
	v_readlane_b32 s8, v230, 36
	v_readlane_b32 s30, v231, 36
	v_readlane_b32 s44, v232, 36
	v_readlane_b32 s46, v233, 36
	v_readlane_b32 s50, v234, 36
	v_readlane_b32 s58, v235, 36
	v_readlane_b32 s98, v236, 36
	v_readlane_b32 s100, v237, 36
	s_waitcnt vmcnt(22)
; __device__ __forceinline__ void mlstm_sample_unit(Frame& F, const Args& a, int b, int h) {
;     ...
; #pragma unroll 16
;     for (int i = 0; i < 64; ++i) { const int d = 4 * i + rsub;
;         const f32x4 c0 = __builtin_nontemporal_load((const f32x4*)(Cin + (size_t)d * 512));
;         f32x4 cn = c0 * decay;
; #pragma unroll
;         for (int s = 0; s < 4; ++s) { cn += vs[s] * L[MS_KW + s * 256 + d]; qc[s] += c0 * L[MS_Q + s * 256 + d]; }
;         __builtin_nontemporal_store(cn, (f32x4*)(Cout + (size_t)d * 512)); }
	v_pk_mul_f32 v[238:239], v[18:19], s[8:9] op_sel_hi:[1,0]
	v_pk_mul_f32 v[240:241], v[20:21], s[8:9] op_sel_hi:[1,0]
	v_pk_fma_f32 v[238:239], v[44:45], v[182:183], v[238:239]
	v_pk_fma_f32 v[240:241], v[44:45], v[184:185], v[240:241]
	v_pk_fma_f32 v[238:239], v[14:15], s[30:31], v[238:239] op_sel_hi:[1,0,1]
	v_pk_fma_f32 v[240:241], v[16:17], s[30:31], v[240:241] op_sel_hi:[1,0,1]
	v_pk_fma_f32 v[238:239], v[10:11], s[44:45], v[238:239] op_sel_hi:[1,0,1]
	v_pk_fma_f32 v[240:241], v[12:13], s[44:45], v[240:241] op_sel_hi:[1,0,1]
	v_pk_fma_f32 v[238:239], v[6:7], s[46:47], v[238:239] op_sel_hi:[1,0,1]
	v_pk_fma_f32 v[240:241], v[8:9], s[46:47], v[240:241] op_sel_hi:[1,0,1]
	v_pk_fma_f32 v[34:35], v[182:183], s[50:51], v[34:35] op_sel_hi:[1,0,1]
	v_pk_fma_f32 v[36:37], v[184:185], s[50:51], v[36:37] op_sel_hi:[1,0,1]
	v_pk_fma_f32 v[30:31], v[182:183], s[58:59], v[30:31] op_sel_hi:[1,0,1]
	v_pk_fma_f32 v[32:33], v[184:185], s[58:59], v[32:33] op_sel_hi:[1,0,1]
	v_pk_fma_f32 v[26:27], v[182:183], s[98:99], v[26:27] op_sel_hi:[1,0,1]
	v_pk_fma_f32 v[28:29], v[184:185], s[98:99], v[28:29] op_sel_hi:[1,0,1]
	v_pk_fma_f32 v[22:23], v[182:183], s[100:101], v[22:23] op_sel_hi:[1,0,1]
	v_pk_fma_f32 v[24:25], v[184:185], s[100:101], v[24:25] op_sel_hi:[1,0,1]
	global_store_dwordx4 v[246:247], v[238:241], off nt
	global_load_dwordx4 v[182:185], v[242:243], off nt
	v_lshl_add_u64 v[242:243], v[242:243], 0, v[248:249]
	v_lshl_add_u64 v[246:247], v[246:247], 0, v[248:249]
	v_readlane_b32 s8, v230, 37
	v_readlane_b32 s30, v231, 37
	v_readlane_b32 s44, v232, 37
	v_readlane_b32 s46, v233, 37
	v_readlane_b32 s50, v234, 37
	v_readlane_b32 s58, v235, 37
	v_readlane_b32 s98, v236, 37
	v_readlane_b32 s100, v237, 37
	s_waitcnt vmcnt(22)
	v_pk_mul_f32 v[238:239], v[18:19], s[8:9] op_sel_hi:[1,0]
	v_pk_mul_f32 v[240:241], v[20:21], s[8:9] op_sel_hi:[1,0]
	v_pk_fma_f32 v[238:239], v[44:45], v[186:187], v[238:239]
	v_pk_fma_f32 v[240:241], v[44:45], v[188:189], v[240:241]
	v_pk_fma_f32 v[238:239], v[14:15], s[30:31], v[238:239] op_sel_hi:[1,0,1]
	v_pk_fma_f32 v[240:241], v[16:17], s[30:31], v[240:241] op_sel_hi:[1,0,1]
	v_pk_fma_f32 v[238:239], v[10:11], s[44:45], v[238:239] op_sel_hi:[1,0,1]
	v_pk_fma_f32 v[240:241], v[12:13], s[44:45], v[240:241] op_sel_hi:[1,0,1]
	v_pk_fma_f32 v[238:239], v[6:7], s[46:47], v[238:239] op_sel_hi:[1,0,1]
	v_pk_fma_f32 v[240:241], v[8:9], s[46:47], v[240:241] op_sel_hi:[1,0,1]
	v_pk_fma_f32 v[34:35], v[186:187], s[50:51], v[34:35] op_sel_hi:[1,0,1]
	v_pk_fma_f32 v[36:37], v[188:189], s[50:51], v[36:37] op_sel_hi:[1,0,1]
	v_pk_fma_f32 v[30:31], v[186:187], s[58:59], v[30:31] op_sel_hi:[1,0,1]
	v_pk_fma_f32 v[32:33], v[188:189], s[58:59], v[32:33] op_sel_hi:[1,0,1]
	v_pk_fma_f32 v[26:27], v[186:187], s[98:99], v[26:27] op_sel_hi:[1,0,1]
	v_pk_fma_f32 v[28:29], v[188:189], s[98:99], v[28:29] op_sel_hi:[1,0,1]
	v_pk_fma_f32 v[22:23], v[186:187], s[100:101], v[22:23] op_sel_hi:[1,0,1]
	v_pk_fma_f32 v[24:25], v[188:189], s[100:101], v[24:25] op_sel_hi:[1,0,1]
	global_store_dwordx4 v[246:247], v[238:241], off nt
	global_load_dwordx4 v[186:189], v[242:243], off nt
	v_lshl_add_u64 v[242:243], v[242:243], 0, v[248:249]
	v_lshl_add_u64 v[246:247], v[246:247], 0, v[248:249]
	v_readlane_b32 s8, v230, 38
	v_readlane_b32 s30, v231, 38
	v_readlane_b32 s44, v232, 38
	v_readlane_b32 s46, v233, 38
	v_readlane_b32 s50, v234, 38
	v_readlane_b32 s58, v235, 38
	v_readlane_b32 s98, v236, 38
	v_readlane_b32 s100, v237, 38
	s_waitcnt vmcnt(22)
	v_pk_mul_f32 v[238:239], v[18:19], s[8:9] op_sel_hi:[1,0]
	v_pk_mul_f32 v[240:241], v[20:21], s[8:9] op_sel_hi:[1,0]
	v_pk_fma_f32 v[238:239], v[44:45], v[190:191], v[238:239]
	v_pk_fma_f32 v[240:241], v[44:45], v[192:193], v[240:241]
	v_pk_fma_f32 v[238:239], v[14:15], s[30:31], v[238:239] op_sel_hi:[1,0,1]
	v_pk_fma_f32 v[240:241], v[16:17], s[30:31], v[240:241] op_sel_hi:[1,0,1]
	v_pk_fma_f32 v[238:239], v[10:11], s[44:45], v[238:239] op_sel_hi:[1,0,1]
	v_pk_fma_f32 v[240:241], v[12:13], s[44:45], v[240:241] op_sel_hi:[1,0,1]
	v_pk_fma_f32 v[238:239], v[6:7], s[46:47], v[238:239] op_sel_hi:[1,0,1]
	v_pk_fma_f32 v[240:241], v[8:9], s[46:47], v[240:241] op_sel_hi:[1,0,1]
	v_pk_fma_f32 v[34:35], v[190:191], s[50:51], v[34:35] op_sel_hi:[1,0,1]
	v_pk_fma_f32 v[36:37], v[192:193], s[50:51], v[36:37] op_sel_hi:[1,0,1]
	v_pk_fma_f32 v[30:31], v[190:191], s[58:59], v[30:31] op_sel_hi:[1,0,1]
	v_pk_fma_f32 v[32:33], v[192:193], s[58:59], v[32:33] op_sel_hi:[1,0,1]
	v_pk_fma_f32 v[26:27], v[190:191], s[98:99], v[26:27] op_sel_hi:[1,0,1]
	v_pk_fma_f32 v[28:29], v[192:193], s[98:99], v[28:29] op_sel_hi:[1,0,1]
	v_pk_fma_f32 v[22:23], v[190:191], s[100:101], v[22:23] op_sel_hi:[1,0,1]
	v_pk_fma_f32 v[24:25], v[192:193], s[100:101], v[24:25] op_sel_hi:[1,0,1]
	global_store_dwordx4 v[246:247], v[238:241], off nt
	global_load_dwordx4 v[190:193], v[242:243], off nt
	v_lshl_add_u64 v[242:243], v[242:243], 0, v[248:249]
	v_lshl_add_u64 v[246:247], v[246:247], 0, v[248:249]
	v_readlane_b32 s8, v230, 39
	v_readlane_b32 s30, v231, 39
	v_readlane_b32 s44, v232, 39
	v_readlane_b32 s46, v233, 39
	v_readlane_b32 s50, v234, 39
	v_readlane_b32 s58, v235, 39
	v_readlane_b32 s98, v236, 39
	v_readlane_b32 s100, v237, 39
	s_waitcnt vmcnt(22)
; __device__ __forceinline__ void mlstm_sample_unit(Frame& F, const Args& a, int b, int h) {
;     ...
; #pragma unroll 16
;     for (int i = 0; i < 64; ++i) { const int d = 4 * i + rsub;
;         const f32x4 c0 = __builtin_nontemporal_load((const f32x4*)(Cin + (size_t)d * 512));
;         f32x4 cn = c0 * decay;
; #pragma unroll
;         for (int s = 0; s < 4; ++s) { cn += vs[s] * L[MS_KW + s * 256 + d]; qc[s] += c0 * L[MS_Q + s * 256 + d]; }
;         __builtin_nontemporal_store(cn, (f32x4*)(Cout + (size_t)d * 512)); }
	v_pk_mul_f32 v[238:239], v[18:19], s[8:9] op_sel_hi:[1,0]
	v_pk_mul_f32 v[240:241], v[20:21], s[8:9] op_sel_hi:[1,0]
	v_pk_fma_f32 v[238:239], v[44:45], v[194:195], v[238:239]
	v_pk_fma_f32 v[240:241], v[44:45], v[196:197], v[240:241]
	v_pk_fma_f32 v[238:239], v[14:15], s[30:31], v[238:239] op_sel_hi:[1,0,1]
	v_pk_fma_f32 v[240:241], v[16:17], s[30:31], v[240:241] op_sel_hi:[1,0,1]
	v_pk_fma_f32 v[238:239], v[10:11], s[44:45], v[238:239] op_sel_hi:[1,0,1]
	v_pk_fma_f32 v[240:241], v[12:13], s[44:45], v[240:241] op_sel_hi:[1,0,1]
	v_pk_fma_f32 v[238:239], v[6:7], s[46:47], v[238:239] op_sel_hi:[1,0,1]
	v_pk_fma_f32 v[240:241], v[8:9], s[46:47], v[240:241] op_sel_hi:[1,0,1]
	v_pk_fma_f32 v[34:35], v[194:195], s[50:51], v[34:35] op_sel_hi:[1,0,1]
	v_pk_fma_f32 v[36:37], v[196:197], s[50:51], v[36:37] op_sel_hi:[1,0,1]
	v_pk_fma_f32 v[30:31], v[194:195], s[58:59], v[30:31] op_sel_hi:[1,0,1]
	v_pk_fma_f32 v[32:33], v[196:197], s[58:59], v[32:33] op_sel_hi:[1,0,1]
	v_pk_fma_f32 v[26:27], v[194:195], s[98:99], v[26:27] op_sel_hi:[1,0,1]
	v_pk_fma_f32 v[28:29], v[196:197], s[98:99], v[28:29] op_sel_hi:[1,0,1]
	v_pk_fma_f32 v[22:23], v[194:195], s[100:101], v[22:23] op_sel_hi:[1,0,1]
	v_pk_fma_f32 v[24:25], v[196:197], s[100:101], v[24:25] op_sel_hi:[1,0,1]
	global_store_dwordx4 v[246:247], v[238:241], off nt
	global_load_dwordx4 v[194:197], v[242:243], off nt
	v_lshl_add_u64 v[242:243], v[242:243], 0, v[248:249]
	v_lshl_add_u64 v[246:247], v[246:247], 0, v[248:249]
	v_readlane_b32 s8, v230, 40
	v_readlane_b32 s30, v231, 40
	v_readlane_b32 s44, v232, 40
	v_readlane_b32 s46, v233, 40
	v_readlane_b32 s50, v234, 40
	v_readlane_b32 s58, v235, 40
	v_readlane_b32 s98, v236, 40
	v_readlane_b32 s100, v237, 40
	s_waitcnt vmcnt(22)
	v_pk_mul_f32 v[238:239], v[18:19], s[8:9] op_sel_hi:[1,0]
	v_pk_mul_f32 v[240:241], v[20:21], s[8:9] op_sel_hi:[1,0]
	v_pk_fma_f32 v[238:239], v[44:45], v[198:199], v[238:239]
	v_pk_fma_f32 v[240:241], v[44:45], v[200:201], v[240:241]
	v_pk_fma_f32 v[238:239], v[14:15], s[30:31], v[238:239] op_sel_hi:[1,0,1]
	v_pk_fma_f32 v[240:241], v[16:17], s[30:31], v[240:241] op_sel_hi:[1,0,1]
	v_pk_fma_f32 v[238:239], v[10:11], s[44:45], v[238:239] op_sel_hi:[1,0,1]
	v_pk_fma_f32 v[240:241], v[12:13], s[44:45], v[240:241] op_sel_hi:[1,0,1]
	v_pk_fma_f32 v[238:239], v[6:7], s[46:47], v[238:239] op_sel_hi:[1,0,1]
	v_pk_fma_f32 v[240:241], v[8:9], s[46:47], v[240:241] op_sel_hi:[1,0,1]
	v_pk_fma_f32 v[34:35], v[198:199], s[50:51], v[34:35] op_sel_hi:[1,0,1]
	v_pk_fma_f32 v[36:37], v[200:201], s[50:51], v[36:37] op_sel_hi:[1,0,1]
	v_pk_fma_f32 v[30:31], v[198:199], s[58:59], v[30:31] op_sel_hi:[1,0,1]
	v_pk_fma_f32 v[32:33], v[200:201], s[58:59], v[32:33] op_sel_hi:[1,0,1]
	v_pk_fma_f32 v[26:27], v[198:199], s[98:99], v[26:27] op_sel_hi:[1,0,1]
	v_pk_fma_f32 v[28:29], v[200:201], s[98:99], v[28:29] op_sel_hi:[1,0,1]
	v_pk_fma_f32 v[22:23], v[198:199], s[100:101], v[22:23] op_sel_hi:[1,0,1]
	v_pk_fma_f32 v[24:25], v[200:201], s[100:101], v[24:25] op_sel_hi:[1,0,1]
	global_store_dwordx4 v[246:247], v[238:241], off nt
	global_load_dwordx4 v[198:201], v[242:243], off nt
	v_lshl_add_u64 v[242:243], v[242:243], 0, v[248:249]
	v_lshl_add_u64 v[246:247], v[246:247], 0, v[248:249]
	v_readlane_b32 s8, v230, 41
	v_readlane_b32 s30, v231, 41
	v_readlane_b32 s44, v232, 41
	v_readlane_b32 s46, v233, 41
	v_readlane_b32 s50, v234, 41
	v_readlane_b32 s58, v235, 41
	v_readlane_b32 s98, v236, 41
	v_readlane_b32 s100, v237, 41
	s_waitcnt vmcnt(22)
	v_pk_mul_f32 v[238:239], v[18:19], s[8:9] op_sel_hi:[1,0]
	v_pk_mul_f32 v[240:241], v[20:21], s[8:9] op_sel_hi:[1,0]
	v_pk_fma_f32 v[238:239], v[44:45], v[202:203], v[238:239]
	v_pk_fma_f32 v[240:241], v[44:45], v[204:205], v[240:241]
	v_pk_fma_f32 v[238:239], v[14:15], s[30:31], v[238:239] op_sel_hi:[1,0,1]
	v_pk_fma_f32 v[240:241], v[16:17], s[30:31], v[240:241] op_sel_hi:[1,0,1]
	v_pk_fma_f32 v[238:239], v[10:11], s[44:45], v[238:239] op_sel_hi:[1,0,1]
	v_pk_fma_f32 v[240:241], v[12:13], s[44:45], v[240:241] op_sel_hi:[1,0,1]
	v_pk_fma_f32 v[238:239], v[6:7], s[46:47], v[238:239] op_sel_hi:[1,0,1]
	v_pk_fma_f32 v[240:241], v[8:9], s[46:47], v[240:241] op_sel_hi:[1,0,1]
	v_pk_fma_f32 v[34:35], v[202:203], s[50:51], v[34:35] op_sel_hi:[1,0,1]
	v_pk_fma_f32 v[36:37], v[204:205], s[50:51], v[36:37] op_sel_hi:[1,0,1]
	v_pk_fma_f32 v[30:31], v[202:203], s[58:59], v[30:31] op_sel_hi:[1,0,1]
	v_pk_fma_f32 v[32:33], v[204:205], s[58:59], v[32:33] op_sel_hi:[1,0,1]
	v_pk_fma_f32 v[26:27], v[202:203], s[98:99], v[26:27] op_sel_hi:[1,0,1]
	v_pk_fma_f32 v[28:29], v[204:205], s[98:99], v[28:29] op_sel_hi:[1,0,1]
	v_pk_fma_f32 v[22:23], v[202:203], s[100:101], v[22:23] op_sel_hi:[1,0,1]
	v_pk_fma_f32 v[24:25], v[204:205], s[100:101], v[24:25] op_sel_hi:[1,0,1]
	global_store_dwordx4 v[246:247], v[238:241], off nt
	global_load_dwordx4 v[202:205], v[242:243], off nt
	v_lshl_add_u64 v[242:243], v[242:243], 0, v[248:249]
	v_lshl_add_u64 v[246:247], v[246:247], 0, v[248:249]
	v_readlane_b32 s8, v230, 42
	v_readlane_b32 s30, v231, 42
	v_readlane_b32 s44, v232, 42
	v_readlane_b32 s46, v233, 42
	v_readlane_b32 s50, v234, 42
	v_readlane_b32 s58, v235, 42
	v_readlane_b32 s98, v236, 42
	v_readlane_b32 s100, v237, 42
	s_waitcnt vmcnt(22)
; __device__ __forceinline__ void mlstm_sample_unit(Frame& F, const Args& a, int b, int h) {
;     ...
; #pragma unroll 16
;     for (int i = 0; i < 64; ++i) { const int d = 4 * i + rsub;
;         const f32x4 c0 = __builtin_nontemporal_load((const f32x4*)(Cin + (size_t)d * 512));
;         f32x4 cn = c0 * decay;
; #pragma unroll
;         for (int s = 0; s < 4; ++s) { cn += vs[s] * L[MS_KW + s * 256 + d]; qc[s] += c0 * L[MS_Q + s * 256 + d]; }
;         __builtin_nontemporal_store(cn, (f32x4*)(Cout + (size_t)d * 512)); }
	v_pk_mul_f32 v[238:239], v[18:19], s[8:9] op_sel_hi:[1,0]
	v_pk_mul_f32 v[240:241], v[20:21], s[8:9] op_sel_hi:[1,0]
	v_pk_fma_f32 v[238:239], v[44:45], v[206:207], v[238:239]
	v_pk_fma_f32 v[240:241], v[44:45], v[208:209], v[240:241]
	v_pk_fma_f32 v[238:239], v[14:15], s[30:31], v[238:239] op_sel_hi:[1,0,1]
	v_pk_fma_f32 v[240:241], v[16:17], s[30:31], v[240:241] op_sel_hi:[1,0,1]
	v_pk_fma_f32 v[238:239], v[10:11], s[44:45], v[238:239] op_sel_hi:[1,0,1]
	v_pk_fma_f32 v[240:241], v[12:13], s[44:45], v[240:241] op_sel_hi:[1,0,1]
	v_pk_fma_f32 v[238:239], v[6:7], s[46:47], v[238:239] op_sel_hi:[1,0,1]
	v_pk_fma_f32 v[240:241], v[8:9], s[46:47], v[240:241] op_sel_hi:[1,0,1]
	v_pk_fma_f32 v[34:35], v[206:207], s[50:51], v[34:35] op_sel_hi:[1,0,1]
	v_pk_fma_f32 v[36:37], v[208:209], s[50:51], v[36:37] op_sel_hi:[1,0,1]
	v_pk_fma_f32 v[30:31], v[206:207], s[58:59], v[30:31] op_sel_hi:[1,0,1]
	v_pk_fma_f32 v[32:33], v[208:209], s[58:59], v[32:33] op_sel_hi:[1,0,1]
	v_pk_fma_f32 v[26:27], v[206:207], s[98:99], v[26:27] op_sel_hi:[1,0,1]
	v_pk_fma_f32 v[28:29], v[208:209], s[98:99], v[28:29] op_sel_hi:[1,0,1]
	v_pk_fma_f32 v[22:23], v[206:207], s[100:101], v[22:23] op_sel_hi:[1,0,1]
	v_pk_fma_f32 v[24:25], v[208:209], s[100:101], v[24:25] op_sel_hi:[1,0,1]
	global_store_dwordx4 v[246:247], v[238:241], off nt
	global_load_dwordx4 v[206:209], v[242:243], off nt
	v_lshl_add_u64 v[242:243], v[242:243], 0, v[248:249]
	v_lshl_add_u64 v[246:247], v[246:247], 0, v[248:249]
	v_readlane_b32 s8, v230, 43
	v_readlane_b32 s30, v231, 43
	v_readlane_b32 s44, v232, 43
	v_readlane_b32 s46, v233, 43
	v_readlane_b32 s50, v234, 43
	v_readlane_b32 s58, v235, 43
	v_readlane_b32 s98, v236, 43
	v_readlane_b32 s100, v237, 43
	s_waitcnt vmcnt(22)
	v_pk_mul_f32 v[238:239], v[18:19], s[8:9] op_sel_hi:[1,0]
	v_pk_mul_f32 v[240:241], v[20:21], s[8:9] op_sel_hi:[1,0]
	v_pk_fma_f32 v[238:239], v[44:45], v[210:211], v[238:239]
	v_pk_fma_f32 v[240:241], v[44:45], v[212:213], v[240:241]
	v_pk_fma_f32 v[238:239], v[14:15], s[30:31], v[238:239] op_sel_hi:[1,0,1]
	v_pk_fma_f32 v[240:241], v[16:17], s[30:31], v[240:241] op_sel_hi:[1,0,1]
	v_pk_fma_f32 v[238:239], v[10:11], s[44:45], v[238:239] op_sel_hi:[1,0,1]
	v_pk_fma_f32 v[240:241], v[12:13], s[44:45], v[240:241] op_sel_hi:[1,0,1]
	v_pk_fma_f32 v[238:239], v[6:7], s[46:47], v[238:239] op_sel_hi:[1,0,1]
	v_pk_fma_f32 v[240:241], v[8:9], s[46:47], v[240:241] op_sel_hi:[1,0,1]
	v_pk_fma_f32 v[34:35], v[210:211], s[50:51], v[34:35] op_sel_hi:[1,0,1]
	v_pk_fma_f32 v[36:37], v[212:213], s[50:51], v[36:37] op_sel_hi:[1,0,1]
	v_pk_fma_f32 v[30:31], v[210:211], s[58:59], v[30:31] op_sel_hi:[1,0,1]
	v_pk_fma_f32 v[32:33], v[212:213], s[58:59], v[32:33] op_sel_hi:[1,0,1]
	v_pk_fma_f32 v[26:27], v[210:211], s[98:99], v[26:27] op_sel_hi:[1,0,1]
	v_pk_fma_f32 v[28:29], v[212:213], s[98:99], v[28:29] op_sel_hi:[1,0,1]
	v_pk_fma_f32 v[22:23], v[210:211], s[100:101], v[22:23] op_sel_hi:[1,0,1]
	v_pk_fma_f32 v[24:25], v[212:213], s[100:101], v[24:25] op_sel_hi:[1,0,1]
	global_store_dwordx4 v[246:247], v[238:241], off nt
	global_load_dwordx4 v[210:213], v[242:243], off nt
	v_lshl_add_u64 v[242:243], v[242:243], 0, v[248:249]
	v_lshl_add_u64 v[246:247], v[246:247], 0, v[248:249]
	v_readlane_b32 s8, v230, 44
	v_readlane_b32 s30, v231, 44
	v_readlane_b32 s44, v232, 44
	v_readlane_b32 s46, v233, 44
	v_readlane_b32 s50, v234, 44
	v_readlane_b32 s58, v235, 44
	v_readlane_b32 s98, v236, 44
	v_readlane_b32 s100, v237, 44
	s_waitcnt vmcnt(22)
	v_pk_mul_f32 v[238:239], v[18:19], s[8:9] op_sel_hi:[1,0]
	v_pk_mul_f32 v[240:241], v[20:21], s[8:9] op_sel_hi:[1,0]
	v_pk_fma_f32 v[238:239], v[44:45], v[214:215], v[238:239]
	v_pk_fma_f32 v[240:241], v[44:45], v[216:217], v[240:241]
	v_pk_fma_f32 v[238:239], v[14:15], s[30:31], v[238:239] op_sel_hi:[1,0,1]
	v_pk_fma_f32 v[240:241], v[16:17], s[30:31], v[240:241] op_sel_hi:[1,0,1]
	v_pk_fma_f32 v[238:239], v[10:11], s[44:45], v[238:239] op_sel_hi:[1,0,1]
	v_pk_fma_f32 v[240:241], v[12:13], s[44:45], v[240:241] op_sel_hi:[1,0,1]
	v_pk_fma_f32 v[238:239], v[6:7], s[46:47], v[238:239] op_sel_hi:[1,0,1]
	v_pk_fma_f32 v[240:241], v[8:9], s[46:47], v[240:241] op_sel_hi:[1,0,1]
	v_pk_fma_f32 v[34:35], v[214:215], s[50:51], v[34:35] op_sel_hi:[1,0,1]
	v_pk_fma_f32 v[36:37], v[216:217], s[50:51], v[36:37] op_sel_hi:[1,0,1]
	v_pk_fma_f32 v[30:31], v[214:215], s[58:59], v[30:31] op_sel_hi:[1,0,1]
	v_pk_fma_f32 v[32:33], v[216:217], s[58:59], v[32:33] op_sel_hi:[1,0,1]
	v_pk_fma_f32 v[26:27], v[214:215], s[98:99], v[26:27] op_sel_hi:[1,0,1]
	v_pk_fma_f32 v[28:29], v[216:217], s[98:99], v[28:29] op_sel_hi:[1,0,1]
	v_pk_fma_f32 v[22:23], v[214:215], s[100:101], v[22:23] op_sel_hi:[1,0,1]
	v_pk_fma_f32 v[24:25], v[216:217], s[100:101], v[24:25] op_sel_hi:[1,0,1]
	global_store_dwordx4 v[246:247], v[238:241], off nt
	global_load_dwordx4 v[214:217], v[242:243], off nt
	v_lshl_add_u64 v[242:243], v[242:243], 0, v[248:249]
	v_lshl_add_u64 v[246:247], v[246:247], 0, v[248:249]
	v_readlane_b32 s8, v230, 45
	v_readlane_b32 s30, v231, 45
	v_readlane_b32 s44, v232, 45
	v_readlane_b32 s46, v233, 45
	v_readlane_b32 s50, v234, 45
	v_readlane_b32 s58, v235, 45
	v_readlane_b32 s98, v236, 45
	v_readlane_b32 s100, v237, 45
	s_waitcnt vmcnt(22)
; __device__ __forceinline__ void mlstm_sample_unit(Frame& F, const Args& a, int b, int h) {
;     ...
; #pragma unroll 16
;     for (int i = 0; i < 64; ++i) { const int d = 4 * i + rsub;
;         const f32x4 c0 = __builtin_nontemporal_load((const f32x4*)(Cin + (size_t)d * 512));
;         f32x4 cn = c0 * decay;
; #pragma unroll
;         for (int s = 0; s < 4; ++s) { cn += vs[s] * L[MS_KW + s * 256 + d]; qc[s] += c0 * L[MS_Q + s * 256 + d]; }
;         __builtin_nontemporal_store(cn, (f32x4*)(Cout + (size_t)d * 512)); }
	v_pk_mul_f32 v[238:239], v[18:19], s[8:9] op_sel_hi:[1,0]
	v_pk_mul_f32 v[240:241], v[20:21], s[8:9] op_sel_hi:[1,0]
	v_pk_fma_f32 v[238:239], v[44:45], v[218:219], v[238:239]
	v_pk_fma_f32 v[240:241], v[44:45], v[220:221], v[240:241]
	v_pk_fma_f32 v[238:239], v[14:15], s[30:31], v[238:239] op_sel_hi:[1,0,1]
	v_pk_fma_f32 v[240:241], v[16:17], s[30:31], v[240:241] op_sel_hi:[1,0,1]
	v_pk_fma_f32 v[238:239], v[10:11], s[44:45], v[238:239] op_sel_hi:[1,0,1]
	v_pk_fma_f32 v[240:241], v[12:13], s[44:45], v[240:241] op_sel_hi:[1,0,1]
	v_pk_fma_f32 v[238:239], v[6:7], s[46:47], v[238:239] op_sel_hi:[1,0,1]
	v_pk_fma_f32 v[240:241], v[8:9], s[46:47], v[240:241] op_sel_hi:[1,0,1]
	v_pk_fma_f32 v[34:35], v[218:219], s[50:51], v[34:35] op_sel_hi:[1,0,1]
	v_pk_fma_f32 v[36:37], v[220:221], s[50:51], v[36:37] op_sel_hi:[1,0,1]
	v_pk_fma_f32 v[30:31], v[218:219], s[58:59], v[30:31] op_sel_hi:[1,0,1]
	v_pk_fma_f32 v[32:33], v[220:221], s[58:59], v[32:33] op_sel_hi:[1,0,1]
	v_pk_fma_f32 v[26:27], v[218:219], s[98:99], v[26:27] op_sel_hi:[1,0,1]
	v_pk_fma_f32 v[28:29], v[220:221], s[98:99], v[28:29] op_sel_hi:[1,0,1]
	v_pk_fma_f32 v[22:23], v[218:219], s[100:101], v[22:23] op_sel_hi:[1,0,1]
	v_pk_fma_f32 v[24:25], v[220:221], s[100:101], v[24:25] op_sel_hi:[1,0,1]
	global_store_dwordx4 v[246:247], v[238:241], off nt
	global_load_dwordx4 v[218:221], v[242:243], off nt
	v_lshl_add_u64 v[242:243], v[242:243], 0, v[248:249]
	v_lshl_add_u64 v[246:247], v[246:247], 0, v[248:249]
	v_readlane_b32 s8, v230, 46
	v_readlane_b32 s30, v231, 46
	v_readlane_b32 s44, v232, 46
	v_readlane_b32 s46, v233, 46
	v_readlane_b32 s50, v234, 46
	v_readlane_b32 s58, v235, 46
	v_readlane_b32 s98, v236, 46
	v_readlane_b32 s100, v237, 46
	s_waitcnt vmcnt(22)
	v_pk_mul_f32 v[238:239], v[18:19], s[8:9] op_sel_hi:[1,0]
	v_pk_mul_f32 v[240:241], v[20:21], s[8:9] op_sel_hi:[1,0]
	v_pk_fma_f32 v[238:239], v[44:45], v[222:223], v[238:239]
	v_pk_fma_f32 v[240:241], v[44:45], v[224:225], v[240:241]
	v_pk_fma_f32 v[238:239], v[14:15], s[30:31], v[238:239] op_sel_hi:[1,0,1]
	v_pk_fma_f32 v[240:241], v[16:17], s[30:31], v[240:241] op_sel_hi:[1,0,1]
	v_pk_fma_f32 v[238:239], v[10:11], s[44:45], v[238:239] op_sel_hi:[1,0,1]
	v_pk_fma_f32 v[240:241], v[12:13], s[44:45], v[240:241] op_sel_hi:[1,0,1]
	v_pk_fma_f32 v[238:239], v[6:7], s[46:47], v[238:239] op_sel_hi:[1,0,1]
	v_pk_fma_f32 v[240:241], v[8:9], s[46:47], v[240:241] op_sel_hi:[1,0,1]
	v_pk_fma_f32 v[34:35], v[222:223], s[50:51], v[34:35] op_sel_hi:[1,0,1]
	v_pk_fma_f32 v[36:37], v[224:225], s[50:51], v[36:37] op_sel_hi:[1,0,1]
	v_pk_fma_f32 v[30:31], v[222:223], s[58:59], v[30:31] op_sel_hi:[1,0,1]
	v_pk_fma_f32 v[32:33], v[224:225], s[58:59], v[32:33] op_sel_hi:[1,0,1]
	v_pk_fma_f32 v[26:27], v[222:223], s[98:99], v[26:27] op_sel_hi:[1,0,1]
	v_pk_fma_f32 v[28:29], v[224:225], s[98:99], v[28:29] op_sel_hi:[1,0,1]
	v_pk_fma_f32 v[22:23], v[222:223], s[100:101], v[22:23] op_sel_hi:[1,0,1]
	v_pk_fma_f32 v[24:25], v[224:225], s[100:101], v[24:25] op_sel_hi:[1,0,1]
	global_store_dwordx4 v[246:247], v[238:241], off nt
	global_load_dwordx4 v[222:225], v[242:243], off nt
	v_lshl_add_u64 v[242:243], v[242:243], 0, v[248:249]
	v_lshl_add_u64 v[246:247], v[246:247], 0, v[248:249]
	v_readlane_b32 s8, v230, 47
	v_readlane_b32 s30, v231, 47
	v_readlane_b32 s44, v232, 47
	v_readlane_b32 s46, v233, 47
	v_readlane_b32 s50, v234, 47
	v_readlane_b32 s58, v235, 47
	v_readlane_b32 s98, v236, 47
	v_readlane_b32 s100, v237, 47
	s_waitcnt vmcnt(22)
	v_pk_mul_f32 v[238:239], v[18:19], s[8:9] op_sel_hi:[1,0]
	v_pk_mul_f32 v[240:241], v[20:21], s[8:9] op_sel_hi:[1,0]
	v_pk_fma_f32 v[238:239], v[44:45], v[226:227], v[238:239]
	v_pk_fma_f32 v[240:241], v[44:45], v[228:229], v[240:241]
	v_pk_fma_f32 v[238:239], v[14:15], s[30:31], v[238:239] op_sel_hi:[1,0,1]
	v_pk_fma_f32 v[240:241], v[16:17], s[30:31], v[240:241] op_sel_hi:[1,0,1]
	v_pk_fma_f32 v[238:239], v[10:11], s[44:45], v[238:239] op_sel_hi:[1,0,1]
	v_pk_fma_f32 v[240:241], v[12:13], s[44:45], v[240:241] op_sel_hi:[1,0,1]
	v_pk_fma_f32 v[238:239], v[6:7], s[46:47], v[238:239] op_sel_hi:[1,0,1]
	v_pk_fma_f32 v[240:241], v[8:9], s[46:47], v[240:241] op_sel_hi:[1,0,1]
	v_pk_fma_f32 v[34:35], v[226:227], s[50:51], v[34:35] op_sel_hi:[1,0,1]
	v_pk_fma_f32 v[36:37], v[228:229], s[50:51], v[36:37] op_sel_hi:[1,0,1]
	v_pk_fma_f32 v[30:31], v[226:227], s[58:59], v[30:31] op_sel_hi:[1,0,1]
	v_pk_fma_f32 v[32:33], v[228:229], s[58:59], v[32:33] op_sel_hi:[1,0,1]
	v_pk_fma_f32 v[26:27], v[226:227], s[98:99], v[26:27] op_sel_hi:[1,0,1]
	v_pk_fma_f32 v[28:29], v[228:229], s[98:99], v[28:29] op_sel_hi:[1,0,1]
	v_pk_fma_f32 v[22:23], v[226:227], s[100:101], v[22:23] op_sel_hi:[1,0,1]
	v_pk_fma_f32 v[24:25], v[228:229], s[100:101], v[24:25] op_sel_hi:[1,0,1]
	global_store_dwordx4 v[246:247], v[238:241], off nt
	global_load_dwordx4 v[226:229], v[242:243], off nt
	v_lshl_add_u64 v[242:243], v[242:243], 0, v[248:249]
	v_lshl_add_u64 v[246:247], v[246:247], 0, v[248:249]
	v_readlane_b32 s8, v230, 48
	v_readlane_b32 s30, v231, 48
	v_readlane_b32 s44, v232, 48
	v_readlane_b32 s46, v233, 48
	v_readlane_b32 s50, v234, 48
	v_readlane_b32 s58, v235, 48
	v_readlane_b32 s98, v236, 48
	v_readlane_b32 s100, v237, 48
	s_waitcnt vmcnt(22)
; __device__ __forceinline__ void mlstm_sample_unit(Frame& F, const Args& a, int b, int h) {
;     ...
; #pragma unroll 16
;     for (int i = 0; i < 64; ++i) { const int d = 4 * i + rsub;
;         const f32x4 c0 = __builtin_nontemporal_load((const f32x4*)(Cin + (size_t)d * 512));
;         f32x4 cn = c0 * decay;
; #pragma unroll
;         for (int s = 0; s < 4; ++s) { cn += vs[s] * L[MS_KW + s * 256 + d]; qc[s] += c0 * L[MS_Q + s * 256 + d]; }
;         __builtin_nontemporal_store(cn, (f32x4*)(Cout + (size_t)d * 512)); }
	v_pk_mul_f32 v[238:239], v[18:19], s[8:9] op_sel_hi:[1,0]
	v_pk_mul_f32 v[240:241], v[20:21], s[8:9] op_sel_hi:[1,0]
	v_pk_fma_f32 v[238:239], v[44:45], v[182:183], v[238:239]
	v_pk_fma_f32 v[240:241], v[44:45], v[184:185], v[240:241]
	v_pk_fma_f32 v[238:239], v[14:15], s[30:31], v[238:239] op_sel_hi:[1,0,1]
	v_pk_fma_f32 v[240:241], v[16:17], s[30:31], v[240:241] op_sel_hi:[1,0,1]
	v_pk_fma_f32 v[238:239], v[10:11], s[44:45], v[238:239] op_sel_hi:[1,0,1]
	v_pk_fma_f32 v[240:241], v[12:13], s[44:45], v[240:241] op_sel_hi:[1,0,1]
	v_pk_fma_f32 v[238:239], v[6:7], s[46:47], v[238:239] op_sel_hi:[1,0,1]
	v_pk_fma_f32 v[240:241], v[8:9], s[46:47], v[240:241] op_sel_hi:[1,0,1]
	v_pk_fma_f32 v[34:35], v[182:183], s[50:51], v[34:35] op_sel_hi:[1,0,1]
	v_pk_fma_f32 v[36:37], v[184:185], s[50:51], v[36:37] op_sel_hi:[1,0,1]
	v_pk_fma_f32 v[30:31], v[182:183], s[58:59], v[30:31] op_sel_hi:[1,0,1]
	v_pk_fma_f32 v[32:33], v[184:185], s[58:59], v[32:33] op_sel_hi:[1,0,1]
	v_pk_fma_f32 v[26:27], v[182:183], s[98:99], v[26:27] op_sel_hi:[1,0,1]
	v_pk_fma_f32 v[28:29], v[184:185], s[98:99], v[28:29] op_sel_hi:[1,0,1]
	v_pk_fma_f32 v[22:23], v[182:183], s[100:101], v[22:23] op_sel_hi:[1,0,1]
	v_pk_fma_f32 v[24:25], v[184:185], s[100:101], v[24:25] op_sel_hi:[1,0,1]
	global_store_dwordx4 v[246:247], v[238:241], off nt
	global_load_dwordx4 v[182:185], v[242:243], off nt
	v_lshl_add_u64 v[242:243], v[242:243], 0, v[248:249]
	v_lshl_add_u64 v[246:247], v[246:247], 0, v[248:249]
	v_readlane_b32 s8, v230, 49
	v_readlane_b32 s30, v231, 49
	v_readlane_b32 s44, v232, 49
	v_readlane_b32 s46, v233, 49
	v_readlane_b32 s50, v234, 49
	v_readlane_b32 s58, v235, 49
	v_readlane_b32 s98, v236, 49
	v_readlane_b32 s100, v237, 49
	s_waitcnt vmcnt(22)
	v_pk_mul_f32 v[238:239], v[18:19], s[8:9] op_sel_hi:[1,0]
	v_pk_mul_f32 v[240:241], v[20:21], s[8:9] op_sel_hi:[1,0]
	v_pk_fma_f32 v[238:239], v[44:45], v[186:187], v[238:239]
	v_pk_fma_f32 v[240:241], v[44:45], v[188:189], v[240:241]
	v_pk_fma_f32 v[238:239], v[14:15], s[30:31], v[238:239] op_sel_hi:[1,0,1]
	v_pk_fma_f32 v[240:241], v[16:17], s[30:31], v[240:241] op_sel_hi:[1,0,1]
	v_pk_fma_f32 v[238:239], v[10:11], s[44:45], v[238:239] op_sel_hi:[1,0,1]
	v_pk_fma_f32 v[240:241], v[12:13], s[44:45], v[240:241] op_sel_hi:[1,0,1]
	v_pk_fma_f32 v[238:239], v[6:7], s[46:47], v[238:239] op_sel_hi:[1,0,1]
	v_pk_fma_f32 v[240:241], v[8:9], s[46:47], v[240:241] op_sel_hi:[1,0,1]
	v_pk_fma_f32 v[34:35], v[186:187], s[50:51], v[34:35] op_sel_hi:[1,0,1]
	v_pk_fma_f32 v[36:37], v[188:189], s[50:51], v[36:37] op_sel_hi:[1,0,1]
	v_pk_fma_f32 v[30:31], v[186:187], s[58:59], v[30:31] op_sel_hi:[1,0,1]
	v_pk_fma_f32 v[32:33], v[188:189], s[58:59], v[32:33] op_sel_hi:[1,0,1]
	v_pk_fma_f32 v[26:27], v[186:187], s[98:99], v[26:27] op_sel_hi:[1,0,1]
	v_pk_fma_f32 v[28:29], v[188:189], s[98:99], v[28:29] op_sel_hi:[1,0,1]
	v_pk_fma_f32 v[22:23], v[186:187], s[100:101], v[22:23] op_sel_hi:[1,0,1]
	v_pk_fma_f32 v[24:25], v[188:189], s[100:101], v[24:25] op_sel_hi:[1,0,1]
	global_store_dwordx4 v[246:247], v[238:241], off nt
	global_load_dwordx4 v[186:189], v[242:243], off nt
	v_lshl_add_u64 v[242:243], v[242:243], 0, v[248:249]
	v_lshl_add_u64 v[246:247], v[246:247], 0, v[248:249]
	v_readlane_b32 s8, v230, 50
	v_readlane_b32 s30, v231, 50
	v_readlane_b32 s44, v232, 50
	v_readlane_b32 s46, v233, 50
	v_readlane_b32 s50, v234, 50
	v_readlane_b32 s58, v235, 50
	v_readlane_b32 s98, v236, 50
	v_readlane_b32 s100, v237, 50
	s_waitcnt vmcnt(22)
	v_pk_mul_f32 v[238:239], v[18:19], s[8:9] op_sel_hi:[1,0]
	v_pk_mul_f32 v[240:241], v[20:21], s[8:9] op_sel_hi:[1,0]
	v_pk_fma_f32 v[238:239], v[44:45], v[190:191], v[238:239]
	v_pk_fma_f32 v[240:241], v[44:45], v[192:193], v[240:241]
	v_pk_fma_f32 v[238:239], v[14:15], s[30:31], v[238:239] op_sel_hi:[1,0,1]
	v_pk_fma_f32 v[240:241], v[16:17], s[30:31], v[240:241] op_sel_hi:[1,0,1]
	v_pk_fma_f32 v[238:239], v[10:11], s[44:45], v[238:239] op_sel_hi:[1,0,1]
	v_pk_fma_f32 v[240:241], v[12:13], s[44:45], v[240:241] op_sel_hi:[1,0,1]
	v_pk_fma_f32 v[238:239], v[6:7], s[46:47], v[238:239] op_sel_hi:[1,0,1]
	v_pk_fma_f32 v[240:241], v[8:9], s[46:47], v[240:241] op_sel_hi:[1,0,1]
	v_pk_fma_f32 v[34:35], v[190:191], s[50:51], v[34:35] op_sel_hi:[1,0,1]
	v_pk_fma_f32 v[36:37], v[192:193], s[50:51], v[36:37] op_sel_hi:[1,0,1]
	v_pk_fma_f32 v[30:31], v[190:191], s[58:59], v[30:31] op_sel_hi:[1,0,1]
	v_pk_fma_f32 v[32:33], v[192:193], s[58:59], v[32:33] op_sel_hi:[1,0,1]
	v_pk_fma_f32 v[26:27], v[190:191], s[98:99], v[26:27] op_sel_hi:[1,0,1]
	v_pk_fma_f32 v[28:29], v[192:193], s[98:99], v[28:29] op_sel_hi:[1,0,1]
	v_pk_fma_f32 v[22:23], v[190:191], s[100:101], v[22:23] op_sel_hi:[1,0,1]
	v_pk_fma_f32 v[24:25], v[192:193], s[100:101], v[24:25] op_sel_hi:[1,0,1]
	global_store_dwordx4 v[246:247], v[238:241], off nt
	global_load_dwordx4 v[190:193], v[242:243], off nt
	v_lshl_add_u64 v[242:243], v[242:243], 0, v[248:249]
	v_lshl_add_u64 v[246:247], v[246:247], 0, v[248:249]
	v_readlane_b32 s8, v230, 51
	v_readlane_b32 s30, v231, 51
	v_readlane_b32 s44, v232, 51
	v_readlane_b32 s46, v233, 51
	v_readlane_b32 s50, v234, 51
	v_readlane_b32 s58, v235, 51
	v_readlane_b32 s98, v236, 51
	v_readlane_b32 s100, v237, 51
	s_waitcnt vmcnt(22)
; __device__ __forceinline__ void mlstm_sample_unit(Frame& F, const Args& a, int b, int h) {
;     ...
; #pragma unroll 16
;     for (int i = 0; i < 64; ++i) { const int d = 4 * i + rsub;
;         const f32x4 c0 = __builtin_nontemporal_load((const f32x4*)(Cin + (size_t)d * 512));
;         f32x4 cn = c0 * decay;
; #pragma unroll
;         for (int s = 0; s < 4; ++s) { cn += vs[s] * L[MS_KW + s * 256 + d]; qc[s] += c0 * L[MS_Q + s * 256 + d]; }
;         __builtin_nontemporal_store(cn, (f32x4*)(Cout + (size_t)d * 512)); }
	v_pk_mul_f32 v[238:239], v[18:19], s[8:9] op_sel_hi:[1,0]
	v_pk_mul_f32 v[240:241], v[20:21], s[8:9] op_sel_hi:[1,0]
	v_pk_fma_f32 v[238:239], v[44:45], v[194:195], v[238:239]
	v_pk_fma_f32 v[240:241], v[44:45], v[196:197], v[240:241]
	v_pk_fma_f32 v[238:239], v[14:15], s[30:31], v[238:239] op_sel_hi:[1,0,1]
	v_pk_fma_f32 v[240:241], v[16:17], s[30:31], v[240:241] op_sel_hi:[1,0,1]
	v_pk_fma_f32 v[238:239], v[10:11], s[44:45], v[238:239] op_sel_hi:[1,0,1]
	v_pk_fma_f32 v[240:241], v[12:13], s[44:45], v[240:241] op_sel_hi:[1,0,1]
	v_pk_fma_f32 v[238:239], v[6:7], s[46:47], v[238:239] op_sel_hi:[1,0,1]
	v_pk_fma_f32 v[240:241], v[8:9], s[46:47], v[240:241] op_sel_hi:[1,0,1]
	v_pk_fma_f32 v[34:35], v[194:195], s[50:51], v[34:35] op_sel_hi:[1,0,1]
	v_pk_fma_f32 v[36:37], v[196:197], s[50:51], v[36:37] op_sel_hi:[1,0,1]
	v_pk_fma_f32 v[30:31], v[194:195], s[58:59], v[30:31] op_sel_hi:[1,0,1]
	v_pk_fma_f32 v[32:33], v[196:197], s[58:59], v[32:33] op_sel_hi:[1,0,1]
	v_pk_fma_f32 v[26:27], v[194:195], s[98:99], v[26:27] op_sel_hi:[1,0,1]
	v_pk_fma_f32 v[28:29], v[196:197], s[98:99], v[28:29] op_sel_hi:[1,0,1]
	v_pk_fma_f32 v[22:23], v[194:195], s[100:101], v[22:23] op_sel_hi:[1,0,1]
	v_pk_fma_f32 v[24:25], v[196:197], s[100:101], v[24:25] op_sel_hi:[1,0,1]
	global_store_dwordx4 v[246:247], v[238:241], off nt
	global_load_dwordx4 v[194:197], v[242:243], off nt
	v_lshl_add_u64 v[242:243], v[242:243], 0, v[248:249]
	v_lshl_add_u64 v[246:247], v[246:247], 0, v[248:249]
	v_readlane_b32 s8, v230, 52
	v_readlane_b32 s30, v231, 52
	v_readlane_b32 s44, v232, 52
	v_readlane_b32 s46, v233, 52
	v_readlane_b32 s50, v234, 52
	v_readlane_b32 s58, v235, 52
	v_readlane_b32 s98, v236, 52
	v_readlane_b32 s100, v237, 52
	s_waitcnt vmcnt(22)
	v_pk_mul_f32 v[238:239], v[18:19], s[8:9] op_sel_hi:[1,0]
	v_pk_mul_f32 v[240:241], v[20:21], s[8:9] op_sel_hi:[1,0]
	v_pk_fma_f32 v[238:239], v[44:45], v[198:199], v[238:239]
	v_pk_fma_f32 v[240:241], v[44:45], v[200:201], v[240:241]
	v_pk_fma_f32 v[238:239], v[14:15], s[30:31], v[238:239] op_sel_hi:[1,0,1]
	v_pk_fma_f32 v[240:241], v[16:17], s[30:31], v[240:241] op_sel_hi:[1,0,1]
	v_pk_fma_f32 v[238:239], v[10:11], s[44:45], v[238:239] op_sel_hi:[1,0,1]
	v_pk_fma_f32 v[240:241], v[12:13], s[44:45], v[240:241] op_sel_hi:[1,0,1]
	v_pk_fma_f32 v[238:239], v[6:7], s[46:47], v[238:239] op_sel_hi:[1,0,1]
	v_pk_fma_f32 v[240:241], v[8:9], s[46:47], v[240:241] op_sel_hi:[1,0,1]
	v_pk_fma_f32 v[34:35], v[198:199], s[50:51], v[34:35] op_sel_hi:[1,0,1]
	v_pk_fma_f32 v[36:37], v[200:201], s[50:51], v[36:37] op_sel_hi:[1,0,1]
	v_pk_fma_f32 v[30:31], v[198:199], s[58:59], v[30:31] op_sel_hi:[1,0,1]
	v_pk_fma_f32 v[32:33], v[200:201], s[58:59], v[32:33] op_sel_hi:[1,0,1]
	v_pk_fma_f32 v[26:27], v[198:199], s[98:99], v[26:27] op_sel_hi:[1,0,1]
	v_pk_fma_f32 v[28:29], v[200:201], s[98:99], v[28:29] op_sel_hi:[1,0,1]
	v_pk_fma_f32 v[22:23], v[198:199], s[100:101], v[22:23] op_sel_hi:[1,0,1]
	v_pk_fma_f32 v[24:25], v[200:201], s[100:101], v[24:25] op_sel_hi:[1,0,1]
	global_store_dwordx4 v[246:247], v[238:241], off nt
	v_lshl_add_u64 v[246:247], v[246:247], 0, v[248:249]
	v_readlane_b32 s8, v230, 53
	v_readlane_b32 s30, v231, 53
	v_readlane_b32 s44, v232, 53
	v_readlane_b32 s46, v233, 53
	v_readlane_b32 s50, v234, 53
	v_readlane_b32 s58, v235, 53
	v_readlane_b32 s98, v236, 53
	v_readlane_b32 s100, v237, 53
	s_waitcnt vmcnt(21)
	v_pk_mul_f32 v[238:239], v[18:19], s[8:9] op_sel_hi:[1,0]
	v_pk_mul_f32 v[240:241], v[20:21], s[8:9] op_sel_hi:[1,0]
	v_pk_fma_f32 v[238:239], v[44:45], v[202:203], v[238:239]
	v_pk_fma_f32 v[240:241], v[44:45], v[204:205], v[240:241]
	v_pk_fma_f32 v[238:239], v[14:15], s[30:31], v[238:239] op_sel_hi:[1,0,1]
	v_pk_fma_f32 v[240:241], v[16:17], s[30:31], v[240:241] op_sel_hi:[1,0,1]
	v_pk_fma_f32 v[238:239], v[10:11], s[44:45], v[238:239] op_sel_hi:[1,0,1]
	v_pk_fma_f32 v[240:241], v[12:13], s[44:45], v[240:241] op_sel_hi:[1,0,1]
	v_pk_fma_f32 v[238:239], v[6:7], s[46:47], v[238:239] op_sel_hi:[1,0,1]
	v_pk_fma_f32 v[240:241], v[8:9], s[46:47], v[240:241] op_sel_hi:[1,0,1]
	v_pk_fma_f32 v[34:35], v[202:203], s[50:51], v[34:35] op_sel_hi:[1,0,1]
	v_pk_fma_f32 v[36:37], v[204:205], s[50:51], v[36:37] op_sel_hi:[1,0,1]
	v_pk_fma_f32 v[30:31], v[202:203], s[58:59], v[30:31] op_sel_hi:[1,0,1]
	v_pk_fma_f32 v[32:33], v[204:205], s[58:59], v[32:33] op_sel_hi:[1,0,1]
	v_pk_fma_f32 v[26:27], v[202:203], s[98:99], v[26:27] op_sel_hi:[1,0,1]
	v_pk_fma_f32 v[28:29], v[204:205], s[98:99], v[28:29] op_sel_hi:[1,0,1]
	v_pk_fma_f32 v[22:23], v[202:203], s[100:101], v[22:23] op_sel_hi:[1,0,1]
	v_pk_fma_f32 v[24:25], v[204:205], s[100:101], v[24:25] op_sel_hi:[1,0,1]
	global_store_dwordx4 v[246:247], v[238:241], off nt
	v_lshl_add_u64 v[246:247], v[246:247], 0, v[248:249]
	v_readlane_b32 s8, v230, 54
	v_readlane_b32 s30, v231, 54
	v_readlane_b32 s44, v232, 54
	v_readlane_b32 s46, v233, 54
	v_readlane_b32 s50, v234, 54
	v_readlane_b32 s58, v235, 54
	v_readlane_b32 s98, v236, 54
	v_readlane_b32 s100, v237, 54
	s_waitcnt vmcnt(20)
; __device__ __forceinline__ void mlstm_sample_unit(Frame& F, const Args& a, int b, int h) {
;     ...
; #pragma unroll 16
;     for (int i = 0; i < 64; ++i) { const int d = 4 * i + rsub;
;         const f32x4 c0 = __builtin_nontemporal_load((const f32x4*)(Cin + (size_t)d * 512));
;         f32x4 cn = c0 * decay;
; #pragma unroll
;         for (int s = 0; s < 4; ++s) { cn += vs[s] * L[MS_KW + s * 256 + d]; qc[s] += c0 * L[MS_Q + s * 256 + d]; }
;         __builtin_nontemporal_store(cn, (f32x4*)(Cout + (size_t)d * 512)); }
	v_pk_mul_f32 v[238:239], v[18:19], s[8:9] op_sel_hi:[1,0]
	v_pk_mul_f32 v[240:241], v[20:21], s[8:9] op_sel_hi:[1,0]
	v_pk_fma_f32 v[238:239], v[44:45], v[206:207], v[238:239]
	v_pk_fma_f32 v[240:241], v[44:45], v[208:209], v[240:241]
	v_pk_fma_f32 v[238:239], v[14:15], s[30:31], v[238:239] op_sel_hi:[1,0,1]
	v_pk_fma_f32 v[240:241], v[16:17], s[30:31], v[240:241] op_sel_hi:[1,0,1]
	v_pk_fma_f32 v[238:239], v[10:11], s[44:45], v[238:239] op_sel_hi:[1,0,1]
	v_pk_fma_f32 v[240:241], v[12:13], s[44:45], v[240:241] op_sel_hi:[1,0,1]
	v_pk_fma_f32 v[238:239], v[6:7], s[46:47], v[238:239] op_sel_hi:[1,0,1]
	v_pk_fma_f32 v[240:241], v[8:9], s[46:47], v[240:241] op_sel_hi:[1,0,1]
	v_pk_fma_f32 v[34:35], v[206:207], s[50:51], v[34:35] op_sel_hi:[1,0,1]
	v_pk_fma_f32 v[36:37], v[208:209], s[50:51], v[36:37] op_sel_hi:[1,0,1]
	v_pk_fma_f32 v[30:31], v[206:207], s[58:59], v[30:31] op_sel_hi:[1,0,1]
	v_pk_fma_f32 v[32:33], v[208:209], s[58:59], v[32:33] op_sel_hi:[1,0,1]
	v_pk_fma_f32 v[26:27], v[206:207], s[98:99], v[26:27] op_sel_hi:[1,0,1]
	v_pk_fma_f32 v[28:29], v[208:209], s[98:99], v[28:29] op_sel_hi:[1,0,1]
	v_pk_fma_f32 v[22:23], v[206:207], s[100:101], v[22:23] op_sel_hi:[1,0,1]
	v_pk_fma_f32 v[24:25], v[208:209], s[100:101], v[24:25] op_sel_hi:[1,0,1]
	global_store_dwordx4 v[246:247], v[238:241], off nt
	v_lshl_add_u64 v[246:247], v[246:247], 0, v[248:249]
	v_readlane_b32 s8, v230, 55
	v_readlane_b32 s30, v231, 55
	v_readlane_b32 s44, v232, 55
	v_readlane_b32 s46, v233, 55
	v_readlane_b32 s50, v234, 55
	v_readlane_b32 s58, v235, 55
	v_readlane_b32 s98, v236, 55
	v_readlane_b32 s100, v237, 55
	s_waitcnt vmcnt(19)
	v_pk_mul_f32 v[238:239], v[18:19], s[8:9] op_sel_hi:[1,0]
	v_pk_mul_f32 v[240:241], v[20:21], s[8:9] op_sel_hi:[1,0]
	v_pk_fma_f32 v[238:239], v[44:45], v[210:211], v[238:239]
	v_pk_fma_f32 v[240:241], v[44:45], v[212:213], v[240:241]
	v_pk_fma_f32 v[238:239], v[14:15], s[30:31], v[238:239] op_sel_hi:[1,0,1]
	v_pk_fma_f32 v[240:241], v[16:17], s[30:31], v[240:241] op_sel_hi:[1,0,1]
	v_pk_fma_f32 v[238:239], v[10:11], s[44:45], v[238:239] op_sel_hi:[1,0,1]
	v_pk_fma_f32 v[240:241], v[12:13], s[44:45], v[240:241] op_sel_hi:[1,0,1]
	v_pk_fma_f32 v[238:239], v[6:7], s[46:47], v[238:239] op_sel_hi:[1,0,1]
	v_pk_fma_f32 v[240:241], v[8:9], s[46:47], v[240:241] op_sel_hi:[1,0,1]
	v_pk_fma_f32 v[34:35], v[210:211], s[50:51], v[34:35] op_sel_hi:[1,0,1]
	v_pk_fma_f32 v[36:37], v[212:213], s[50:51], v[36:37] op_sel_hi:[1,0,1]
	v_pk_fma_f32 v[30:31], v[210:211], s[58:59], v[30:31] op_sel_hi:[1,0,1]
	v_pk_fma_f32 v[32:33], v[212:213], s[58:59], v[32:33] op_sel_hi:[1,0,1]
	v_pk_fma_f32 v[26:27], v[210:211], s[98:99], v[26:27] op_sel_hi:[1,0,1]
	v_pk_fma_f32 v[28:29], v[212:213], s[98:99], v[28:29] op_sel_hi:[1,0,1]
	v_pk_fma_f32 v[22:23], v[210:211], s[100:101], v[22:23] op_sel_hi:[1,0,1]
	v_pk_fma_f32 v[24:25], v[212:213], s[100:101], v[24:25] op_sel_hi:[1,0,1]
	global_store_dwordx4 v[246:247], v[238:241], off nt
	v_lshl_add_u64 v[246:247], v[246:247], 0, v[248:249]
	v_readlane_b32 s8, v230, 56
	v_readlane_b32 s30, v231, 56
	v_readlane_b32 s44, v232, 56
	v_readlane_b32 s46, v233, 56
	v_readlane_b32 s50, v234, 56
	v_readlane_b32 s58, v235, 56
	v_readlane_b32 s98, v236, 56
	v_readlane_b32 s100, v237, 56
	s_waitcnt vmcnt(18)
	v_pk_mul_f32 v[238:239], v[18:19], s[8:9] op_sel_hi:[1,0]
	v_pk_mul_f32 v[240:241], v[20:21], s[8:9] op_sel_hi:[1,0]
	v_pk_fma_f32 v[238:239], v[44:45], v[214:215], v[238:239]
	v_pk_fma_f32 v[240:241], v[44:45], v[216:217], v[240:241]
	v_pk_fma_f32 v[238:239], v[14:15], s[30:31], v[238:239] op_sel_hi:[1,0,1]
	v_pk_fma_f32 v[240:241], v[16:17], s[30:31], v[240:241] op_sel_hi:[1,0,1]
	v_pk_fma_f32 v[238:239], v[10:11], s[44:45], v[238:239] op_sel_hi:[1,0,1]
	v_pk_fma_f32 v[240:241], v[12:13], s[44:45], v[240:241] op_sel_hi:[1,0,1]
	v_pk_fma_f32 v[238:239], v[6:7], s[46:47], v[238:239] op_sel_hi:[1,0,1]
	v_pk_fma_f32 v[240:241], v[8:9], s[46:47], v[240:241] op_sel_hi:[1,0,1]
	v_pk_fma_f32 v[34:35], v[214:215], s[50:51], v[34:35] op_sel_hi:[1,0,1]
	v_pk_fma_f32 v[36:37], v[216:217], s[50:51], v[36:37] op_sel_hi:[1,0,1]
	v_pk_fma_f32 v[30:31], v[214:215], s[58:59], v[30:31] op_sel_hi:[1,0,1]
	v_pk_fma_f32 v[32:33], v[216:217], s[58:59], v[32:33] op_sel_hi:[1,0,1]
	v_pk_fma_f32 v[26:27], v[214:215], s[98:99], v[26:27] op_sel_hi:[1,0,1]
	v_pk_fma_f32 v[28:29], v[216:217], s[98:99], v[28:29] op_sel_hi:[1,0,1]
	v_pk_fma_f32 v[22:23], v[214:215], s[100:101], v[22:23] op_sel_hi:[1,0,1]
	v_pk_fma_f32 v[24:25], v[216:217], s[100:101], v[24:25] op_sel_hi:[1,0,1]
	global_store_dwordx4 v[246:247], v[238:241], off nt
	v_lshl_add_u64 v[246:247], v[246:247], 0, v[248:249]
	v_readlane_b32 s8, v230, 57
	v_readlane_b32 s30, v231, 57
	v_readlane_b32 s44, v232, 57
	v_readlane_b32 s46, v233, 57
	v_readlane_b32 s50, v234, 57
	v_readlane_b32 s58, v235, 57
	v_readlane_b32 s98, v236, 57
	v_readlane_b32 s100, v237, 57
	s_waitcnt vmcnt(17)
; __device__ __forceinline__ void mlstm_sample_unit(Frame& F, const Args& a, int b, int h) {
;     ...
; #pragma unroll 16
;     for (int i = 0; i < 64; ++i) { const int d = 4 * i + rsub;
;         const f32x4 c0 = __builtin_nontemporal_load((const f32x4*)(Cin + (size_t)d * 512));
;         f32x4 cn = c0 * decay;
; #pragma unroll
;         for (int s = 0; s < 4; ++s) { cn += vs[s] * L[MS_KW + s * 256 + d]; qc[s] += c0 * L[MS_Q + s * 256 + d]; }
;         __builtin_nontemporal_store(cn, (f32x4*)(Cout + (size_t)d * 512)); }
	v_pk_mul_f32 v[238:239], v[18:19], s[8:9] op_sel_hi:[1,0]
	v_pk_mul_f32 v[240:241], v[20:21], s[8:9] op_sel_hi:[1,0]
	v_pk_fma_f32 v[238:239], v[44:45], v[218:219], v[238:239]
	v_pk_fma_f32 v[240:241], v[44:45], v[220:221], v[240:241]
	v_pk_fma_f32 v[238:239], v[14:15], s[30:31], v[238:239] op_sel_hi:[1,0,1]
	v_pk_fma_f32 v[240:241], v[16:17], s[30:31], v[240:241] op_sel_hi:[1,0,1]
	v_pk_fma_f32 v[238:239], v[10:11], s[44:45], v[238:239] op_sel_hi:[1,0,1]
	v_pk_fma_f32 v[240:241], v[12:13], s[44:45], v[240:241] op_sel_hi:[1,0,1]
	v_pk_fma_f32 v[238:239], v[6:7], s[46:47], v[238:239] op_sel_hi:[1,0,1]
	v_pk_fma_f32 v[240:241], v[8:9], s[46:47], v[240:241] op_sel_hi:[1,0,1]
	v_pk_fma_f32 v[34:35], v[218:219], s[50:51], v[34:35] op_sel_hi:[1,0,1]
	v_pk_fma_f32 v[36:37], v[220:221], s[50:51], v[36:37] op_sel_hi:[1,0,1]
	v_pk_fma_f32 v[30:31], v[218:219], s[58:59], v[30:31] op_sel_hi:[1,0,1]
	v_pk_fma_f32 v[32:33], v[220:221], s[58:59], v[32:33] op_sel_hi:[1,0,1]
	v_pk_fma_f32 v[26:27], v[218:219], s[98:99], v[26:27] op_sel_hi:[1,0,1]
	v_pk_fma_f32 v[28:29], v[220:221], s[98:99], v[28:29] op_sel_hi:[1,0,1]
	v_pk_fma_f32 v[22:23], v[218:219], s[100:101], v[22:23] op_sel_hi:[1,0,1]
	v_pk_fma_f32 v[24:25], v[220:221], s[100:101], v[24:25] op_sel_hi:[1,0,1]
	global_store_dwordx4 v[246:247], v[238:241], off nt
	v_lshl_add_u64 v[246:247], v[246:247], 0, v[248:249]
	v_readlane_b32 s8, v230, 58
	v_readlane_b32 s30, v231, 58
	v_readlane_b32 s44, v232, 58
	v_readlane_b32 s46, v233, 58
	v_readlane_b32 s50, v234, 58
	v_readlane_b32 s58, v235, 58
	v_readlane_b32 s98, v236, 58
	v_readlane_b32 s100, v237, 58
	s_waitcnt vmcnt(16)
	v_pk_mul_f32 v[238:239], v[18:19], s[8:9] op_sel_hi:[1,0]
	v_pk_mul_f32 v[240:241], v[20:21], s[8:9] op_sel_hi:[1,0]
	v_pk_fma_f32 v[238:239], v[44:45], v[222:223], v[238:239]
	v_pk_fma_f32 v[240:241], v[44:45], v[224:225], v[240:241]
	v_pk_fma_f32 v[238:239], v[14:15], s[30:31], v[238:239] op_sel_hi:[1,0,1]
	v_pk_fma_f32 v[240:241], v[16:17], s[30:31], v[240:241] op_sel_hi:[1,0,1]
	v_pk_fma_f32 v[238:239], v[10:11], s[44:45], v[238:239] op_sel_hi:[1,0,1]
	v_pk_fma_f32 v[240:241], v[12:13], s[44:45], v[240:241] op_sel_hi:[1,0,1]
	v_pk_fma_f32 v[238:239], v[6:7], s[46:47], v[238:239] op_sel_hi:[1,0,1]
	v_pk_fma_f32 v[240:241], v[8:9], s[46:47], v[240:241] op_sel_hi:[1,0,1]
	v_pk_fma_f32 v[34:35], v[222:223], s[50:51], v[34:35] op_sel_hi:[1,0,1]
	v_pk_fma_f32 v[36:37], v[224:225], s[50:51], v[36:37] op_sel_hi:[1,0,1]
	v_pk_fma_f32 v[30:31], v[222:223], s[58:59], v[30:31] op_sel_hi:[1,0,1]
	v_pk_fma_f32 v[32:33], v[224:225], s[58:59], v[32:33] op_sel_hi:[1,0,1]
	v_pk_fma_f32 v[26:27], v[222:223], s[98:99], v[26:27] op_sel_hi:[1,0,1]
	v_pk_fma_f32 v[28:29], v[224:225], s[98:99], v[28:29] op_sel_hi:[1,0,1]
	v_pk_fma_f32 v[22:23], v[222:223], s[100:101], v[22:23] op_sel_hi:[1,0,1]
	v_pk_fma_f32 v[24:25], v[224:225], s[100:101], v[24:25] op_sel_hi:[1,0,1]
	global_store_dwordx4 v[246:247], v[238:241], off nt
	v_lshl_add_u64 v[246:247], v[246:247], 0, v[248:249]
	v_readlane_b32 s8, v230, 59
	v_readlane_b32 s30, v231, 59
	v_readlane_b32 s44, v232, 59
	v_readlane_b32 s46, v233, 59
	v_readlane_b32 s50, v234, 59
	v_readlane_b32 s58, v235, 59
	v_readlane_b32 s98, v236, 59
	v_readlane_b32 s100, v237, 59
	s_waitcnt vmcnt(15)
	v_pk_mul_f32 v[238:239], v[18:19], s[8:9] op_sel_hi:[1,0]
	v_pk_mul_f32 v[240:241], v[20:21], s[8:9] op_sel_hi:[1,0]
	v_pk_fma_f32 v[238:239], v[44:45], v[226:227], v[238:239]
	v_pk_fma_f32 v[240:241], v[44:45], v[228:229], v[240:241]
	v_pk_fma_f32 v[238:239], v[14:15], s[30:31], v[238:239] op_sel_hi:[1,0,1]
	v_pk_fma_f32 v[240:241], v[16:17], s[30:31], v[240:241] op_sel_hi:[1,0,1]
	v_pk_fma_f32 v[238:239], v[10:11], s[44:45], v[238:239] op_sel_hi:[1,0,1]
	v_pk_fma_f32 v[240:241], v[12:13], s[44:45], v[240:241] op_sel_hi:[1,0,1]
	v_pk_fma_f32 v[238:239], v[6:7], s[46:47], v[238:239] op_sel_hi:[1,0,1]
	v_pk_fma_f32 v[240:241], v[8:9], s[46:47], v[240:241] op_sel_hi:[1,0,1]
	v_pk_fma_f32 v[34:35], v[226:227], s[50:51], v[34:35] op_sel_hi:[1,0,1]
	v_pk_fma_f32 v[36:37], v[228:229], s[50:51], v[36:37] op_sel_hi:[1,0,1]
	v_pk_fma_f32 v[30:31], v[226:227], s[58:59], v[30:31] op_sel_hi:[1,0,1]
	v_pk_fma_f32 v[32:33], v[228:229], s[58:59], v[32:33] op_sel_hi:[1,0,1]
	v_pk_fma_f32 v[26:27], v[226:227], s[98:99], v[26:27] op_sel_hi:[1,0,1]
	v_pk_fma_f32 v[28:29], v[228:229], s[98:99], v[28:29] op_sel_hi:[1,0,1]
	v_pk_fma_f32 v[22:23], v[226:227], s[100:101], v[22:23] op_sel_hi:[1,0,1]
	v_pk_fma_f32 v[24:25], v[228:229], s[100:101], v[24:25] op_sel_hi:[1,0,1]
	global_store_dwordx4 v[246:247], v[238:241], off nt
	v_lshl_add_u64 v[246:247], v[246:247], 0, v[248:249]
	v_readlane_b32 s8, v230, 60
	v_readlane_b32 s30, v231, 60
	v_readlane_b32 s44, v232, 60
	v_readlane_b32 s46, v233, 60
	v_readlane_b32 s50, v234, 60
	v_readlane_b32 s58, v235, 60
	v_readlane_b32 s98, v236, 60
	v_readlane_b32 s100, v237, 60
	s_waitcnt vmcnt(14)
; #define LAS __attribute__((address_space(3)))
; __device__ __forceinline__ void mlstm_sample_unit(Frame& F, const Args& a, int b, int h) {
;     ...
; #pragma unroll 16
;     for (int i = 0; i < 64; ++i) { const int d = 4 * i + rsub;
;         const f32x4 c0 = __builtin_nontemporal_load((const f32x4*)(Cin + (size_t)d * 512));
;         f32x4 cn = c0 * decay;
; #pragma unroll
;         for (int s = 0; s < 4; ++s) { cn += vs[s] * L[MS_KW + s * 256 + d]; qc[s] += c0 * L[MS_Q + s * 256 + d]; }
;         __builtin_nontemporal_store(cn, (f32x4*)(Cout + (size_t)d * 512)); }
; #pragma unroll
;     for (int t = 0; t < 4; ++t) *(LAS f32x4*)(L + MS_RED + (rsub * 4 + t) * 512 + 4 * c4) = qc[t];
;     __syncthreads();
	v_pk_mul_f32 v[238:239], v[18:19], s[8:9] op_sel_hi:[1,0]
	v_pk_mul_f32 v[240:241], v[20:21], s[8:9] op_sel_hi:[1,0]
	v_pk_fma_f32 v[238:239], v[44:45], v[182:183], v[238:239]
	v_pk_fma_f32 v[240:241], v[44:45], v[184:185], v[240:241]
	v_pk_fma_f32 v[238:239], v[14:15], s[30:31], v[238:239] op_sel_hi:[1,0,1]
	v_pk_fma_f32 v[240:241], v[16:17], s[30:31], v[240:241] op_sel_hi:[1,0,1]
	v_pk_fma_f32 v[238:239], v[10:11], s[44:45], v[238:239] op_sel_hi:[1,0,1]
	v_pk_fma_f32 v[240:241], v[12:13], s[44:45], v[240:241] op_sel_hi:[1,0,1]
	v_pk_fma_f32 v[238:239], v[6:7], s[46:47], v[238:239] op_sel_hi:[1,0,1]
	v_pk_fma_f32 v[240:241], v[8:9], s[46:47], v[240:241] op_sel_hi:[1,0,1]
	v_pk_fma_f32 v[34:35], v[182:183], s[50:51], v[34:35] op_sel_hi:[1,0,1]
	v_pk_fma_f32 v[36:37], v[184:185], s[50:51], v[36:37] op_sel_hi:[1,0,1]
	v_pk_fma_f32 v[30:31], v[182:183], s[58:59], v[30:31] op_sel_hi:[1,0,1]
	v_pk_fma_f32 v[32:33], v[184:185], s[58:59], v[32:33] op_sel_hi:[1,0,1]
	v_pk_fma_f32 v[26:27], v[182:183], s[98:99], v[26:27] op_sel_hi:[1,0,1]
	v_pk_fma_f32 v[28:29], v[184:185], s[98:99], v[28:29] op_sel_hi:[1,0,1]
	v_pk_fma_f32 v[22:23], v[182:183], s[100:101], v[22:23] op_sel_hi:[1,0,1]
	v_pk_fma_f32 v[24:25], v[184:185], s[100:101], v[24:25] op_sel_hi:[1,0,1]
	global_store_dwordx4 v[246:247], v[238:241], off nt
	v_lshl_add_u64 v[246:247], v[246:247], 0, v[248:249]
	v_readlane_b32 s8, v230, 61
	v_readlane_b32 s30, v231, 61
	v_readlane_b32 s44, v232, 61
	v_readlane_b32 s46, v233, 61
	v_readlane_b32 s50, v234, 61
	v_readlane_b32 s58, v235, 61
	v_readlane_b32 s98, v236, 61
	v_readlane_b32 s100, v237, 61
	s_waitcnt vmcnt(13)
	v_pk_mul_f32 v[238:239], v[18:19], s[8:9] op_sel_hi:[1,0]
	v_pk_mul_f32 v[240:241], v[20:21], s[8:9] op_sel_hi:[1,0]
	v_pk_fma_f32 v[238:239], v[44:45], v[186:187], v[238:239]
	v_pk_fma_f32 v[240:241], v[44:45], v[188:189], v[240:241]
	v_pk_fma_f32 v[238:239], v[14:15], s[30:31], v[238:239] op_sel_hi:[1,0,1]
	v_pk_fma_f32 v[240:241], v[16:17], s[30:31], v[240:241] op_sel_hi:[1,0,1]
	v_pk_fma_f32 v[238:239], v[10:11], s[44:45], v[238:239] op_sel_hi:[1,0,1]
	v_pk_fma_f32 v[240:241], v[12:13], s[44:45], v[240:241] op_sel_hi:[1,0,1]
	v_pk_fma_f32 v[238:239], v[6:7], s[46:47], v[238:239] op_sel_hi:[1,0,1]
	v_pk_fma_f32 v[240:241], v[8:9], s[46:47], v[240:241] op_sel_hi:[1,0,1]
	v_pk_fma_f32 v[34:35], v[186:187], s[50:51], v[34:35] op_sel_hi:[1,0,1]
	v_pk_fma_f32 v[36:37], v[188:189], s[50:51], v[36:37] op_sel_hi:[1,0,1]
	v_pk_fma_f32 v[30:31], v[186:187], s[58:59], v[30:31] op_sel_hi:[1,0,1]
	v_pk_fma_f32 v[32:33], v[188:189], s[58:59], v[32:33] op_sel_hi:[1,0,1]
	v_pk_fma_f32 v[26:27], v[186:187], s[98:99], v[26:27] op_sel_hi:[1,0,1]
	v_pk_fma_f32 v[28:29], v[188:189], s[98:99], v[28:29] op_sel_hi:[1,0,1]
	v_pk_fma_f32 v[22:23], v[186:187], s[100:101], v[22:23] op_sel_hi:[1,0,1]
	v_pk_fma_f32 v[24:25], v[188:189], s[100:101], v[24:25] op_sel_hi:[1,0,1]
	global_store_dwordx4 v[246:247], v[238:241], off nt
	v_lshl_add_u64 v[246:247], v[246:247], 0, v[248:249]
	v_readlane_b32 s8, v230, 62
	v_readlane_b32 s30, v231, 62
	v_readlane_b32 s44, v232, 62
	v_readlane_b32 s46, v233, 62
	v_readlane_b32 s50, v234, 62
	v_readlane_b32 s58, v235, 62
	v_readlane_b32 s98, v236, 62
	v_readlane_b32 s100, v237, 62
	s_waitcnt vmcnt(12)
	v_pk_mul_f32 v[238:239], v[18:19], s[8:9] op_sel_hi:[1,0]
	v_pk_mul_f32 v[240:241], v[20:21], s[8:9] op_sel_hi:[1,0]
	v_pk_fma_f32 v[238:239], v[44:45], v[190:191], v[238:239]
	v_pk_fma_f32 v[240:241], v[44:45], v[192:193], v[240:241]
	v_pk_fma_f32 v[238:239], v[14:15], s[30:31], v[238:239] op_sel_hi:[1,0,1]
	v_pk_fma_f32 v[240:241], v[16:17], s[30:31], v[240:241] op_sel_hi:[1,0,1]
	v_pk_fma_f32 v[238:239], v[10:11], s[44:45], v[238:239] op_sel_hi:[1,0,1]
	v_pk_fma_f32 v[240:241], v[12:13], s[44:45], v[240:241] op_sel_hi:[1,0,1]
	v_pk_fma_f32 v[238:239], v[6:7], s[46:47], v[238:239] op_sel_hi:[1,0,1]
	v_pk_fma_f32 v[240:241], v[8:9], s[46:47], v[240:241] op_sel_hi:[1,0,1]
	v_pk_fma_f32 v[34:35], v[190:191], s[50:51], v[34:35] op_sel_hi:[1,0,1]
	v_pk_fma_f32 v[36:37], v[192:193], s[50:51], v[36:37] op_sel_hi:[1,0,1]
	v_pk_fma_f32 v[30:31], v[190:191], s[58:59], v[30:31] op_sel_hi:[1,0,1]
	v_pk_fma_f32 v[32:33], v[192:193], s[58:59], v[32:33] op_sel_hi:[1,0,1]
	v_pk_fma_f32 v[26:27], v[190:191], s[98:99], v[26:27] op_sel_hi:[1,0,1]
	v_pk_fma_f32 v[28:29], v[192:193], s[98:99], v[28:29] op_sel_hi:[1,0,1]
	v_pk_fma_f32 v[22:23], v[190:191], s[100:101], v[22:23] op_sel_hi:[1,0,1]
	v_pk_fma_f32 v[24:25], v[192:193], s[100:101], v[24:25] op_sel_hi:[1,0,1]
	global_store_dwordx4 v[246:247], v[238:241], off nt
	v_lshl_add_u64 v[246:247], v[246:247], 0, v[248:249]
	v_readlane_b32 s8, v230, 63
	v_readlane_b32 s30, v231, 63
	v_readlane_b32 s44, v232, 63
	v_readlane_b32 s46, v233, 63
	v_readlane_b32 s50, v234, 63
	v_readlane_b32 s58, v235, 63
	v_readlane_b32 s98, v236, 63
	v_readlane_b32 s100, v237, 63
	s_waitcnt vmcnt(11)
	v_pk_mul_f32 v[238:239], v[18:19], s[8:9] op_sel_hi:[1,0]
	v_pk_mul_f32 v[240:241], v[20:21], s[8:9] op_sel_hi:[1,0]
	v_pk_fma_f32 v[238:239], v[44:45], v[194:195], v[238:239]
	v_pk_fma_f32 v[240:241], v[44:45], v[196:197], v[240:241]
	v_pk_fma_f32 v[238:239], v[14:15], s[30:31], v[238:239] op_sel_hi:[1,0,1]
	v_pk_fma_f32 v[240:241], v[16:17], s[30:31], v[240:241] op_sel_hi:[1,0,1]
	v_pk_fma_f32 v[238:239], v[10:11], s[44:45], v[238:239] op_sel_hi:[1,0,1]
	v_pk_fma_f32 v[240:241], v[12:13], s[44:45], v[240:241] op_sel_hi:[1,0,1]
	v_pk_fma_f32 v[238:239], v[6:7], s[46:47], v[238:239] op_sel_hi:[1,0,1]
	v_pk_fma_f32 v[240:241], v[8:9], s[46:47], v[240:241] op_sel_hi:[1,0,1]
	v_pk_fma_f32 v[34:35], v[194:195], s[50:51], v[34:35] op_sel_hi:[1,0,1]
	v_pk_fma_f32 v[36:37], v[196:197], s[50:51], v[36:37] op_sel_hi:[1,0,1]
	v_pk_fma_f32 v[30:31], v[194:195], s[58:59], v[30:31] op_sel_hi:[1,0,1]
	v_pk_fma_f32 v[32:33], v[196:197], s[58:59], v[32:33] op_sel_hi:[1,0,1]
	v_pk_fma_f32 v[26:27], v[194:195], s[98:99], v[26:27] op_sel_hi:[1,0,1]
	v_pk_fma_f32 v[28:29], v[196:197], s[98:99], v[28:29] op_sel_hi:[1,0,1]
	v_pk_fma_f32 v[22:23], v[194:195], s[100:101], v[22:23] op_sel_hi:[1,0,1]
	v_pk_fma_f32 v[24:25], v[196:197], s[100:101], v[24:25] op_sel_hi:[1,0,1]
	global_store_dwordx4 v[246:247], v[238:241], off nt
	v_lshl_add_u64 v[246:247], v[246:247], 0, v[248:249]
	v_mov_b32_e32 v43, v42
	s_mov_b32 s16, 0x4f3a000
	s_mov_b64 s[6:7], 0x80000
	v_lshlrev_b32_e32 v41, 13, v40
	v_add3_u32 v41, 0, v41, v79
	ds_write_b128 v41, v[34:37] offset:22528
	ds_write_b128 v41, v[30:33] offset:24576
	ds_write_b128 v41, v[26:29] offset:26624
	ds_write_b128 v41, v[22:25] offset:28672
	v_lshlrev_b32_e32 v22, 11, v40
	v_add3_u32 v30, 0, v22, v79
	s_waitcnt lgkmcnt(0)
	s_barrier
; #define GAS __attribute__((address_space(1)))
; #define LAS __attribute__((address_space(3)))
; __device__ __forceinline__ unsigned pk2(float lo, float hi) { return f2bf(lo) | (f2bf(hi) << 16); }
; __device__ __forceinline__ void mlstm_sample_unit(Frame& F, const Args& a, int b, int h) {
;     ...
;     { const int t = rsub; f32x4 s = (f32x4){0.f, 0.f, 0.f, 0.f};
; #pragma unroll
;       for (int rs = 0; rs < 4; ++rs) s += *(const LAS f32x4*)(L + MS_RED + (rs * 4 + t) * 512 + 4 * c4);
;       const float wp = L[MS_SC + 8 + t]; f32x4 num = s * wp; float den = wp * L[MS_QN + t];
; #pragma unroll
;       for (int s2 = 0; s2 < 4; ++s2) { const float sp = L[MS_SP + t * 4 + s2]; num += vs[s2] * sp; den += sp; }
;       const float inv = 1.0f / fmaxf(fabsf(den), L[MS_SC + 12 + t]);
;       const f32x4 o = num * inv; v2u w; w.x = pk2(o[0], o[1]); w.y = pk2(o[2], o[3]); *(GAS v2u*)(HRAW + (r0 + t) * D + h * 512 + 4 * c4) = w; }
;     if (tid < 4) *(GAS f32x4*)(WSP(float, WS_DENINV) + ((r0 + tid) * 4 + h) * 4) = (f32x4){1.0f, 0.0f, 0.0f, 0.0f};
;     if (tid < 256) { float nn = decay * L[MS_N + tid];
	ds_read_b128 v[22:25], v30 offset:22528
	ds_read_b32 v32, v78 offset:21696
	s_lshl_b32 s86, s86, 1
	v_lshlrev_b32_e32 v66, 3, v66
	s_waitcnt lgkmcnt(1)
	v_pk_add_f32 v[26:27], v[24:25], 0 op_sel_hi:[1,0]
	v_pk_add_f32 v[28:29], v[22:23], 0 op_sel_hi:[1,0]
	ds_read_b128 v[22:25], v30 offset:30720
	s_waitcnt lgkmcnt(0)
	v_pk_add_f32 v[26:27], v[26:27], v[24:25]
	v_pk_add_f32 v[28:29], v[28:29], v[22:23]
	ds_read_b128 v[22:25], v30 offset:38912
	s_waitcnt lgkmcnt(0)
	v_pk_add_f32 v[26:27], v[26:27], v[24:25]
	v_pk_add_f32 v[28:29], v[28:29], v[22:23]
	ds_read_b128 v[22:25], v30 offset:47104
	v_add_u32_e32 v30, 0x5400, v78
	ds_read2_b32 v[30:31], v30 offset0:8 offset1:12
	s_waitcnt lgkmcnt(1)
	v_pk_add_f32 v[28:29], v[28:29], v[22:23]
	v_lshl_add_u32 v22, v40, 4, 0
	v_pk_add_f32 v[26:27], v[26:27], v[24:25]
	ds_read_b128 v[22:25], v22 offset:21632
	s_waitcnt lgkmcnt(0)
	v_pk_mul_f32 v[18:19], v[18:19], v[22:23] op_sel_hi:[1,0]
	v_pk_mul_f32 v[20:21], v[20:21], v[22:23] op_sel_hi:[1,0]
	v_pk_fma_f32 v[18:19], v[28:29], v[30:31], v[18:19] op_sel_hi:[1,0,1]
	v_pk_fma_f32 v[20:21], v[26:27], v[30:31], v[20:21] op_sel_hi:[1,0,1]
	v_fma_f32 v26, v30, v32, v22
	v_pk_fma_f32 v[14:15], v[14:15], v[22:23], v[18:19] op_sel:[0,1,0]
	v_add_f32_e32 v18, v26, v23
	v_pk_fma_f32 v[10:11], v[10:11], v[24:25], v[14:15] op_sel_hi:[1,0,1]
	v_add_f32_e32 v15, v18, v24
	v_mov_b32_e32 v14, v25
	v_pk_fma_f32 v[6:7], v[6:7], v[14:15], v[10:11] op_sel_hi:[1,0,1]
	v_add_f32_e32 v10, v15, v25
	v_max_f32_e32 v11, v31, v31
	v_pk_fma_f32 v[16:17], v[16:17], v[22:23], v[20:21] op_sel:[0,1,0]
	v_max_f32_e64 v10, |v10|, v11
	v_pk_fma_f32 v[12:13], v[12:13], v[24:25], v[16:17] op_sel_hi:[1,0,1]
	v_div_scale_f32 v11, s[6:7], v10, v10, 1.0
	v_pk_fma_f32 v[8:9], v[8:9], v[14:15], v[12:13] op_sel_hi:[1,0,1]
	v_rcp_f32_e32 v12, v11
	s_nop 0
	v_fma_f32 v13, -v11, v12, 1.0
	v_fmac_f32_e32 v12, v13, v12
	v_div_scale_f32 v13, vcc, 1.0, v10, 1.0
	v_mul_f32_e32 v14, v13, v12
	v_fma_f32 v15, -v11, v14, v13
	v_fmac_f32_e32 v14, v15, v12
	v_fma_f32 v11, -v11, v14, v13
	v_div_fmas_f32 v11, v11, v12, v14
	v_div_fixup_f32 v10, v11, v10, 1.0
	v_pk_mul_f32 v[6:7], v[6:7], v[10:11] op_sel_hi:[1,0]
	v_pk_mul_f32 v[8:9], v[8:9], v[10:11] op_sel_hi:[1,0]
	v_bfe_u32 v10, v6, 16, 1
	v_add3_u32 v6, v6, v10, s3
	v_bfe_u32 v10, v7, 16, 1
	v_lshrrev_b32_e32 v6, 16, v6
	v_add3_u32 v7, v7, v10, s3
	v_and_or_b32 v6, v7, s66, v6
	v_bfe_u32 v7, v8, 16, 1
	v_add3_u32 v7, v8, v7, s3
	v_bfe_u32 v8, v9, 16, 1
	v_lshrrev_b32_e32 v7, 16, v7
	v_add3_u32 v8, v9, v8, s3
	v_and_or_b32 v7, v8, s66, v7
	v_lshl_add_u64 v[8:9], s[90:91], 0, v[38:39]
	v_lshl_add_u64 v[8:9], v[8:9], 0, s[86:87]
	v_lshl_add_u64 v[8:9], v[8:9], 0, v[66:67]
	v_cmp_gt_i32_e32 vcc, 4, v68
	global_store_dwordx2 v[8:9], v[6:7], off
	s_and_saveexec_b64 s[6:7], vcc
	s_cbranch_execnz .LBB0_1081
	s_or_b64 exec, exec, s[6:7]
	s_and_saveexec_b64 s[6:7], s[0:1]
	s_cbranch_execnz .LBB0_1082
